# GEMM K-loops: 24 throw-away DMA addresses (scalar base + lane offset) switched to saddr form, 64-bit VALU adds dropped; rest = v028
# speedup vs baseline: 1.0031x; 1.0031x over previous
; #define PG8_STAGE(bufoff, gbase, voff) do { _Pragma("unroll") for (int _i = 0; _i < 2; ++_i) \
;         __builtin_amdgcn_global_load_lds((const unsigned*)((const char*)(gbase) + (voff)[_i]), (LAS unsigned*)(lds + (bufoff) + ldsw + _i * 8192), 16, 0, 0); } while (0)
; #define PG8_LDA(dst, b, h) do { _Pragma("unroll") for (int m = 0; m < 4; ++m) _Pragma("unroll") for (int k = 0; k < 2; ++k) dst[m][k] = *(const LAS bf16x8*)(lds + PG8_SA(b, h) + aoff + m * 2048 + k * 1024); } while (0)
; #define PG8_LDB(dst, b, h) do { _Pragma("unroll") for (int n = 0; n < 2; ++n) _Pragma("unroll") for (int k = 0; k < 2; ++k) dst[n][k] = *(const LAS bf16x8*)(lds + PG8_SB(b, h) + boff + n * 2048 + k * 1024); } while (0)
; #define PG8_MMA(ai, bj, At, Bt) do { __builtin_amdgcn_s_setprio(1); _Pragma("unroll") for (int m = 0; m < 4; ++m) _Pragma("unroll") for (int n = 0; n < 2; ++n) _Pragma("unroll") for (int k = 0; k < 2; ++k) \
;         acc[ai][bj][m][n] = __builtin_amdgcn_mfma_f32_16x16x32_bf16(Bt[n][k], At[m][k], acc[ai][bj][m][n], 0, 0, 0); __builtin_amdgcn_s_setprio(0); } while (0)
; #define PG8_WAIT_V(n) asm volatile("s_waitcnt vmcnt(" #n ")" ::: "memory")
; #define PG8_WAIT_L(n) asm volatile("s_waitcnt lgkmcnt(" #n ")" ::: "memory")
; #define PG8_BAR __builtin_amdgcn_s_barrier()
; #define PG8_SCHED __builtin_amdgcn_sched_barrier(0)
; template <class Epi, bool ALIGN_EPI>
; __device__ __forceinline__ void gemm_phase(LAS unsigned char* lds, const Gemm g, const StaticOrder& S, const Epi& E, const int wave_s) {
;     ...
;         for (int t = 0; t < nt; t += 2) {
;             const bool last = (t == nt - 2);
;             const char* a1 = cA + (size_t)(t + 1) * kstep;
;             const char* a2 = last ? nA : cA + (size_t)(t + 2) * kstep; const char* b2 = last ? nB : cB + (size_t)(t + 2) * kstep;
;             const char* a3 = a2 + kstep; const char* b3 = b2 + kstep;
;             PG8_LDB(B0, 0, 0); PG8_LDB(B1, 0, 1); PG8_SCHED; PG8_LDA(At, 0, 0); PG8_STAGE(PG8_SA(1, 1), a1 + hstepA, voffA);
;             PG8_WAIT_V(8); PG8_WAIT_L(0); PG8_BAR; PG8_MMA(0, 0, At, B0); PG8_MMA(0, 1, At, B1); PG8_BAR; PG8_SCHED;
;             PG8_LDA(At, 0, 1); PG8_STAGE(PG8_SB(0, 0), b2, voffB); PG8_STAGE(PG8_SB(0, 1), b2 + hstepB, voffB); PG8_STAGE(PG8_SA(0, 0), a2, voffA);
;             PG8_WAIT_V(8); PG8_WAIT_L(0); PG8_BAR; PG8_MMA(1, 0, At, B0); PG8_MMA(1, 1, At, B1); PG8_BAR; PG8_SCHED;
.LBB0_108:
	s_add_i32 s55, s40, 2
	s_add_u32 s56, s38, 0x80
	s_addc_u32 s41, s39, 0
	s_add_i32 s58, 0, 0x10000
	s_cmp_eq_u32 s47, s40
	s_cselect_b32 s41, s29, s41
	s_cselect_b32 s40, s28, s56
	v_add_u32_e32 v138, s58, v141
	s_cselect_b32 s57, s37, s54
	s_cselect_b32 s56, s36, s53
	s_add_i32 s59, 0, 0x14000
	ds_read_b128 v[144:147], v138
	ds_read_b128 v[148:151], v138 offset:1024
	ds_read_b128 v[152:155], v138 offset:2048
	ds_read_b128 v[156:159], v138 offset:3072
	v_add_u32_e32 v138, s59, v141
	ds_read_b128 v[160:163], v138
	ds_read_b128 v[164:167], v138 offset:1024
	ds_read_b128 v[168:171], v138 offset:2048
	ds_read_b128 v[172:175], v138 offset:3072
	s_add_i32 m0, s24, 0xc000
	ds_read_b128 v[176:179], v143
	ds_read_b128 v[180:183], v143 offset:1024
	ds_read_b128 v[188:191], v143 offset:2048
	ds_read_b128 v[192:195], v143 offset:3072
	ds_read_b128 v[196:199], v143 offset:4096
	ds_read_b128 v[200:203], v143 offset:5120
	ds_read_b128 v[204:207], v143 offset:6144
	ds_read_b128 v[208:211], v143 offset:7168
	global_load_lds_dwordx4 v136, s[38:39]
	s_add_i32 m0, s24, 0xe000
	s_nop 0
	global_load_lds_dwordx4 v134, s[38:39]
	s_waitcnt vmcnt(8)
	s_waitcnt lgkmcnt(0)
	s_barrier
	s_setprio 1
	s_waitcnt lgkmcnt(0)
	v_mfma_f32_16x16x32_bf16 v[124:127], v[144:147], v[176:179], v[124:127]
	v_mfma_f32_16x16x32_bf16 v[120:123], v[152:155], v[176:179], v[120:123]
	v_mfma_f32_16x16x32_bf16 v[108:111], v[144:147], v[188:191], v[108:111]
	v_mfma_f32_16x16x32_bf16 v[104:107], v[152:155], v[188:191], v[104:107]
	v_mfma_f32_16x16x32_bf16 v[92:95], v[144:147], v[196:199], v[92:95]
	v_mfma_f32_16x16x32_bf16 v[88:91], v[152:155], v[196:199], v[88:91]
	v_mfma_f32_16x16x32_bf16 v[76:79], v[144:147], v[204:207], v[76:79]
	v_mfma_f32_16x16x32_bf16 v[72:75], v[152:155], v[204:207], v[72:75]
	v_mfma_f32_16x16x32_bf16 v[124:127], v[148:151], v[180:183], v[124:127]
	v_mfma_f32_16x16x32_bf16 v[120:123], v[156:159], v[180:183], v[120:123]
	v_mfma_f32_16x16x32_bf16 v[108:111], v[148:151], v[192:195], v[108:111]
	v_mfma_f32_16x16x32_bf16 v[104:107], v[156:159], v[192:195], v[104:107]
	v_mfma_f32_16x16x32_bf16 v[92:95], v[148:151], v[200:203], v[92:95]
	v_mfma_f32_16x16x32_bf16 v[88:91], v[156:159], v[200:203], v[88:91]
	v_mfma_f32_16x16x32_bf16 v[76:79], v[148:151], v[208:211], v[76:79]
	v_mfma_f32_16x16x32_bf16 v[72:75], v[156:159], v[208:211], v[72:75]
	s_setprio 0
	s_setprio 1
	v_mfma_f32_16x16x32_bf16 v[116:119], v[160:163], v[176:179], v[116:119]
	v_mfma_f32_16x16x32_bf16 v[112:115], v[168:171], v[176:179], v[112:115]
	v_mfma_f32_16x16x32_bf16 v[100:103], v[160:163], v[188:191], v[100:103]
	v_mfma_f32_16x16x32_bf16 v[96:99], v[168:171], v[188:191], v[96:99]
	v_mfma_f32_16x16x32_bf16 v[84:87], v[160:163], v[196:199], v[84:87]
	v_mfma_f32_16x16x32_bf16 v[80:83], v[168:171], v[196:199], v[80:83]
	v_mfma_f32_16x16x32_bf16 v[68:71], v[160:163], v[204:207], v[68:71]
	v_mfma_f32_16x16x32_bf16 v[64:67], v[168:171], v[204:207], v[64:67]
	v_mfma_f32_16x16x32_bf16 v[116:119], v[164:167], v[180:183], v[116:119]
	v_mfma_f32_16x16x32_bf16 v[112:115], v[172:175], v[180:183], v[112:115]
	v_mfma_f32_16x16x32_bf16 v[100:103], v[164:167], v[192:195], v[100:103]
	v_mfma_f32_16x16x32_bf16 v[96:99], v[172:175], v[192:195], v[96:99]
	v_mfma_f32_16x16x32_bf16 v[84:87], v[164:167], v[200:203], v[84:87]
	v_mfma_f32_16x16x32_bf16 v[80:83], v[172:175], v[200:203], v[80:83]
	v_mfma_f32_16x16x32_bf16 v[68:71], v[164:167], v[208:211], v[68:71]
	v_mfma_f32_16x16x32_bf16 v[64:67], v[172:175], v[208:211], v[64:67]
	s_setprio 0
	s_barrier
	s_add_i32 s58, s58, s4
	v_lshl_add_u64 v[138:139], s[56:57], 0, v[184:185]
	s_mov_b32 m0, s58
	ds_read_b128 v[176:179], v143 offset:16384
	ds_read_b128 v[180:183], v143 offset:17408
	ds_read_b128 v[188:191], v143 offset:18432
	ds_read_b128 v[192:195], v143 offset:19456
	ds_read_b128 v[196:199], v143 offset:20480
	ds_read_b128 v[200:203], v143 offset:21504
	ds_read_b128 v[204:207], v143 offset:22528
	ds_read_b128 v[208:211], v143 offset:23552
	global_load_lds_dwordx4 v[138:139], off
	s_add_i32 m0, s58, 0x2000
	v_lshl_add_u64 v[212:213], s[56:57], 0, v[128:129]
	s_add_u32 s56, s56, s10
	s_addc_u32 s57, s57, s11
	s_add_i32 s58, s59, s4
	global_load_lds_dwordx4 v[212:213], off
	v_lshl_add_u64 v[214:215], s[56:57], 0, v[184:185]
	s_mov_b32 m0, s58
	v_lshl_add_u64 v[216:217], s[56:57], 0, v[128:129]
	global_load_lds_dwordx4 v[214:215], off
	s_add_i32 m0, s58, 0x2000
	v_lshl_add_u64 v[218:219], s[40:41], 0, v[132:133]
	global_load_lds_dwordx4 v[216:217], off
	s_mov_b32 m0, s24
	v_lshl_add_u64 v[220:221], s[40:41], 0, v[130:131]
	global_load_lds_dwordx4 v[218:219], off
	s_mov_b32 m0, s25
	s_nop 0
	global_load_lds_dwordx4 v[220:221], off
	s_waitcnt vmcnt(8)
	s_waitcnt lgkmcnt(0)
	s_barrier
; #define PG8_STAGE(bufoff, gbase, voff) do { _Pragma("unroll") for (int _i = 0; _i < 2; ++_i) \
;         __builtin_amdgcn_global_load_lds((const unsigned*)((const char*)(gbase) + (voff)[_i]), (LAS unsigned*)(lds + (bufoff) + ldsw + _i * 8192), 16, 0, 0); } while (0)
; #define PG8_LDA(dst, b, h) do { _Pragma("unroll") for (int m = 0; m < 4; ++m) _Pragma("unroll") for (int k = 0; k < 2; ++k) dst[m][k] = *(const LAS bf16x8*)(lds + PG8_SA(b, h) + aoff + m * 2048 + k * 1024); } while (0)
; #define PG8_LDB(dst, b, h) do { _Pragma("unroll") for (int n = 0; n < 2; ++n) _Pragma("unroll") for (int k = 0; k < 2; ++k) dst[n][k] = *(const LAS bf16x8*)(lds + PG8_SB(b, h) + boff + n * 2048 + k * 1024); } while (0)
; #define PG8_MMA(ai, bj, At, Bt) do { __builtin_amdgcn_s_setprio(1); _Pragma("unroll") for (int m = 0; m < 4; ++m) _Pragma("unroll") for (int n = 0; n < 2; ++n) _Pragma("unroll") for (int k = 0; k < 2; ++k) \
;         acc[ai][bj][m][n] = __builtin_amdgcn_mfma_f32_16x16x32_bf16(Bt[n][k], At[m][k], acc[ai][bj][m][n], 0, 0, 0); __builtin_amdgcn_s_setprio(0); } while (0)
; #define PG8_WAIT_V(n) asm volatile("s_waitcnt vmcnt(" #n ")" ::: "memory")
; #define PG8_WAIT_L(n) asm volatile("s_waitcnt lgkmcnt(" #n ")" ::: "memory")
; #define PG8_BAR __builtin_amdgcn_s_barrier()
; #define PG8_SCHED __builtin_amdgcn_sched_barrier(0)
; template <class Epi, bool ALIGN_EPI>
; __device__ __forceinline__ void gemm_phase(LAS unsigned char* lds, const Gemm g, const StaticOrder& S, const Epi& E, const int wave_s) {
;     ...
;             PG8_WAIT_V(8); PG8_WAIT_L(0); PG8_BAR; PG8_MMA(1, 0, At, B0); PG8_MMA(1, 1, At, B1); PG8_BAR; PG8_SCHED;
;             PG8_LDB(B0, 1, 0); PG8_LDB(B1, 1, 1); PG8_SCHED; PG8_LDA(At, 1, 0); PG8_STAGE(PG8_SA(0, 1), a2 + hstepA, voffA);
;             PG8_WAIT_V(8); PG8_WAIT_L(0); PG8_BAR; PG8_MMA(0, 0, At, B0); PG8_MMA(0, 1, At, B1); PG8_BAR; PG8_SCHED;
	s_setprio 1
	s_waitcnt lgkmcnt(0)
	v_mfma_f32_16x16x32_bf16 v[60:63], v[144:147], v[176:179], v[60:63]
	v_mfma_f32_16x16x32_bf16 v[56:59], v[152:155], v[176:179], v[56:59]
	v_mfma_f32_16x16x32_bf16 v[44:47], v[144:147], v[188:191], v[44:47]
	v_mfma_f32_16x16x32_bf16 v[40:43], v[152:155], v[188:191], v[40:43]
	v_mfma_f32_16x16x32_bf16 v[28:31], v[144:147], v[196:199], v[28:31]
	v_mfma_f32_16x16x32_bf16 v[24:27], v[152:155], v[196:199], v[24:27]
	v_mfma_f32_16x16x32_bf16 v[12:15], v[144:147], v[204:207], v[12:15]
	v_mfma_f32_16x16x32_bf16 v[8:11], v[152:155], v[204:207], v[8:11]
	v_mfma_f32_16x16x32_bf16 v[60:63], v[148:151], v[180:183], v[60:63]
	v_mfma_f32_16x16x32_bf16 v[56:59], v[156:159], v[180:183], v[56:59]
	v_mfma_f32_16x16x32_bf16 v[44:47], v[148:151], v[192:195], v[44:47]
	v_mfma_f32_16x16x32_bf16 v[40:43], v[156:159], v[192:195], v[40:43]
	v_mfma_f32_16x16x32_bf16 v[28:31], v[148:151], v[200:203], v[28:31]
	v_mfma_f32_16x16x32_bf16 v[24:27], v[156:159], v[200:203], v[24:27]
	v_mfma_f32_16x16x32_bf16 v[12:15], v[148:151], v[208:211], v[12:15]
	v_mfma_f32_16x16x32_bf16 v[8:11], v[156:159], v[208:211], v[8:11]
	s_setprio 0
	s_setprio 1
	v_mfma_f32_16x16x32_bf16 v[52:55], v[160:163], v[176:179], v[52:55]
	v_mfma_f32_16x16x32_bf16 v[48:51], v[168:171], v[176:179], v[48:51]
	v_mfma_f32_16x16x32_bf16 v[36:39], v[160:163], v[188:191], v[36:39]
	v_mfma_f32_16x16x32_bf16 v[32:35], v[168:171], v[188:191], v[32:35]
	v_mfma_f32_16x16x32_bf16 v[20:23], v[160:163], v[196:199], v[20:23]
	v_mfma_f32_16x16x32_bf16 v[16:19], v[168:171], v[196:199], v[16:19]
	v_mfma_f32_16x16x32_bf16 v[4:7], v[160:163], v[204:207], v[4:7]
	v_mfma_f32_16x16x32_bf16 v[0:3], v[168:171], v[204:207], v[0:3]
	v_mfma_f32_16x16x32_bf16 v[52:55], v[164:167], v[180:183], v[52:55]
	v_mfma_f32_16x16x32_bf16 v[48:51], v[172:175], v[180:183], v[48:51]
	v_mfma_f32_16x16x32_bf16 v[36:39], v[164:167], v[192:195], v[36:39]
	v_mfma_f32_16x16x32_bf16 v[32:35], v[172:175], v[192:195], v[32:35]
	v_mfma_f32_16x16x32_bf16 v[20:23], v[164:167], v[200:203], v[20:23]
	v_mfma_f32_16x16x32_bf16 v[16:19], v[172:175], v[200:203], v[16:19]
	v_mfma_f32_16x16x32_bf16 v[4:7], v[164:167], v[208:211], v[4:7]
	v_mfma_f32_16x16x32_bf16 v[0:3], v[172:175], v[208:211], v[0:3]
	s_setprio 0
	s_barrier
	s_add_i32 s56, 0, 0x18000
	s_add_i32 s57, 0, 0x1c000
	v_add_u32_e32 v156, s56, v141
	v_add_u32_e32 v172, s57, v141
	ds_read_b128 v[144:147], v156
	ds_read_b128 v[148:151], v156 offset:1024
	ds_read_b128 v[152:155], v156 offset:2048
	ds_read_b128 v[156:159], v156 offset:3072
	ds_read_b128 v[160:163], v172
	ds_read_b128 v[164:167], v172 offset:1024
	ds_read_b128 v[168:171], v172 offset:2048
	ds_read_b128 v[172:175], v172 offset:3072
	s_add_u32 s40, s40, s8
	s_addc_u32 s41, s41, s9
	s_mov_b32 m0, s42
	ds_read_b128 v[176:179], v143 offset:32768
	ds_read_b128 v[180:183], v143 offset:33792
	ds_read_b128 v[188:191], v143 offset:34816
	ds_read_b128 v[192:195], v143 offset:35840
	ds_read_b128 v[196:199], v143 offset:36864
	ds_read_b128 v[200:203], v143 offset:37888
	ds_read_b128 v[204:207], v143 offset:38912
	ds_read_b128 v[208:211], v143 offset:39936
	global_load_lds_dwordx4 v132, s[40:41]
	v_lshl_add_u64 v[222:223], s[40:41], 0, v[130:131]
	s_mov_b32 m0, s43
	s_nop 0
	global_load_lds_dwordx4 v[222:223], off
	s_waitcnt vmcnt(8)
	s_waitcnt lgkmcnt(0)
	s_barrier
	s_setprio 1
	s_waitcnt lgkmcnt(0)
	v_mfma_f32_16x16x32_bf16 v[124:127], v[144:147], v[176:179], v[124:127]
	v_mfma_f32_16x16x32_bf16 v[120:123], v[152:155], v[176:179], v[120:123]
	v_mfma_f32_16x16x32_bf16 v[108:111], v[144:147], v[188:191], v[108:111]
	v_mfma_f32_16x16x32_bf16 v[104:107], v[152:155], v[188:191], v[104:107]
	v_mfma_f32_16x16x32_bf16 v[92:95], v[144:147], v[196:199], v[92:95]
	v_mfma_f32_16x16x32_bf16 v[88:91], v[152:155], v[196:199], v[88:91]
	v_mfma_f32_16x16x32_bf16 v[76:79], v[144:147], v[204:207], v[76:79]
	v_mfma_f32_16x16x32_bf16 v[72:75], v[152:155], v[204:207], v[72:75]
	v_mfma_f32_16x16x32_bf16 v[124:127], v[148:151], v[180:183], v[124:127]
	v_mfma_f32_16x16x32_bf16 v[120:123], v[156:159], v[180:183], v[120:123]
	v_mfma_f32_16x16x32_bf16 v[108:111], v[148:151], v[192:195], v[108:111]
	v_mfma_f32_16x16x32_bf16 v[104:107], v[156:159], v[192:195], v[104:107]
	v_mfma_f32_16x16x32_bf16 v[92:95], v[148:151], v[200:203], v[92:95]
	v_mfma_f32_16x16x32_bf16 v[88:91], v[156:159], v[200:203], v[88:91]
	v_mfma_f32_16x16x32_bf16 v[76:79], v[148:151], v[208:211], v[76:79]
	v_mfma_f32_16x16x32_bf16 v[72:75], v[156:159], v[208:211], v[72:75]
	s_setprio 0
	s_setprio 1
	v_mfma_f32_16x16x32_bf16 v[116:119], v[160:163], v[176:179], v[116:119]
	v_mfma_f32_16x16x32_bf16 v[112:115], v[168:171], v[176:179], v[112:115]
	v_mfma_f32_16x16x32_bf16 v[100:103], v[160:163], v[188:191], v[100:103]
	v_mfma_f32_16x16x32_bf16 v[96:99], v[168:171], v[188:191], v[96:99]
	v_mfma_f32_16x16x32_bf16 v[84:87], v[160:163], v[196:199], v[84:87]
	v_mfma_f32_16x16x32_bf16 v[80:83], v[168:171], v[196:199], v[80:83]
	v_mfma_f32_16x16x32_bf16 v[68:71], v[160:163], v[204:207], v[68:71]
	v_mfma_f32_16x16x32_bf16 v[64:67], v[168:171], v[204:207], v[64:67]
	v_mfma_f32_16x16x32_bf16 v[116:119], v[164:167], v[180:183], v[116:119]
	v_mfma_f32_16x16x32_bf16 v[112:115], v[172:175], v[180:183], v[112:115]
	v_mfma_f32_16x16x32_bf16 v[100:103], v[164:167], v[192:195], v[100:103]
	v_mfma_f32_16x16x32_bf16 v[96:99], v[172:175], v[192:195], v[96:99]
	v_mfma_f32_16x16x32_bf16 v[84:87], v[164:167], v[200:203], v[84:87]
	v_mfma_f32_16x16x32_bf16 v[80:83], v[172:175], v[200:203], v[80:83]
	v_mfma_f32_16x16x32_bf16 v[68:71], v[164:167], v[208:211], v[68:71]
	v_mfma_f32_16x16x32_bf16 v[64:67], v[172:175], v[208:211], v[64:67]
	s_setprio 0
	s_barrier
; #define PG8_STAGE(bufoff, gbase, voff) do { _Pragma("unroll") for (int _i = 0; _i < 2; ++_i) \
;         __builtin_amdgcn_global_load_lds((const unsigned*)((const char*)(gbase) + (voff)[_i]), (LAS unsigned*)(lds + (bufoff) + ldsw + _i * 8192), 16, 0, 0); } while (0)
; #define PG8_LDA(dst, b, h) do { _Pragma("unroll") for (int m = 0; m < 4; ++m) _Pragma("unroll") for (int k = 0; k < 2; ++k) dst[m][k] = *(const LAS bf16x8*)(lds + PG8_SA(b, h) + aoff + m * 2048 + k * 1024); } while (0)
; #define PG8_MMA(ai, bj, At, Bt) do { __builtin_amdgcn_s_setprio(1); _Pragma("unroll") for (int m = 0; m < 4; ++m) _Pragma("unroll") for (int n = 0; n < 2; ++n) _Pragma("unroll") for (int k = 0; k < 2; ++k) \
;         acc[ai][bj][m][n] = __builtin_amdgcn_mfma_f32_16x16x32_bf16(Bt[n][k], At[m][k], acc[ai][bj][m][n], 0, 0, 0); __builtin_amdgcn_s_setprio(0); } while (0)
; #define PG8_WAIT_V(n) asm volatile("s_waitcnt vmcnt(" #n ")" ::: "memory")
; #define PG8_WAIT_L(n) asm volatile("s_waitcnt lgkmcnt(" #n ")" ::: "memory")
; #define PG8_BAR __builtin_amdgcn_s_barrier()
; #define PG8_SCHED __builtin_amdgcn_sched_barrier(0)
; template <class Epi, bool ALIGN_EPI>
; __device__ __forceinline__ void gemm_phase(LAS unsigned char* lds, const Gemm g, const StaticOrder& S, const Epi& E, const int wave_s) {
;     ...
;             PG8_LDA(At, 1, 1); PG8_STAGE(PG8_SB(1, 0), b3, voffB); PG8_STAGE(PG8_SB(1, 1), b3 + hstepB, voffB); PG8_STAGE(PG8_SA(1, 0), a3, voffA);
;             PG8_WAIT_V(8); PG8_WAIT_L(0); PG8_BAR; PG8_MMA(1, 0, At, B0); PG8_MMA(1, 1, At, B1); PG8_BAR; PG8_SCHED;
;         }
	s_add_i32 s40, s56, s4
	v_lshl_add_u64 v[138:139], v[138:139], 0, s[64:65]
	s_mov_b32 m0, s40
	ds_read_b128 v[176:179], v143 offset:49152
	ds_read_b128 v[180:183], v143 offset:50176
	ds_read_b128 v[188:191], v143 offset:51200
	ds_read_b128 v[192:195], v143 offset:52224
	ds_read_b128 v[196:199], v143 offset:53248
	ds_read_b128 v[200:203], v143 offset:54272
	ds_read_b128 v[204:207], v143 offset:55296
	ds_read_b128 v[208:211], v143 offset:56320
	global_load_lds_dwordx4 v[138:139], off
	v_lshl_add_u64 v[138:139], v[212:213], 0, s[64:65]
	s_add_i32 m0, s40, 0x2000
	s_add_i32 s40, s57, s4
	global_load_lds_dwordx4 v[138:139], off
	v_lshl_add_u64 v[138:139], v[214:215], 0, s[64:65]
	s_mov_b32 m0, s40
	s_nop 0
	global_load_lds_dwordx4 v[138:139], off
	v_lshl_add_u64 v[138:139], v[216:217], 0, s[64:65]
	s_add_i32 m0, s40, 0x2000
	s_nop 0
	global_load_lds_dwordx4 v[138:139], off
	v_lshl_add_u64 v[138:139], v[218:219], 0, s[64:65]
	s_mov_b32 m0, s44
	s_nop 0
	global_load_lds_dwordx4 v[138:139], off
	v_lshl_add_u64 v[138:139], v[220:221], 0, s[64:65]
	s_mov_b32 m0, s45
	s_nop 0
	global_load_lds_dwordx4 v[138:139], off
	s_waitcnt vmcnt(8)
	s_waitcnt lgkmcnt(0)
	s_barrier
	s_setprio 1
	s_waitcnt lgkmcnt(0)
	v_mfma_f32_16x16x32_bf16 v[60:63], v[144:147], v[176:179], v[60:63]
	v_mfma_f32_16x16x32_bf16 v[56:59], v[152:155], v[176:179], v[56:59]
	v_mfma_f32_16x16x32_bf16 v[44:47], v[144:147], v[188:191], v[44:47]
	v_mfma_f32_16x16x32_bf16 v[40:43], v[152:155], v[188:191], v[40:43]
	v_mfma_f32_16x16x32_bf16 v[28:31], v[144:147], v[196:199], v[28:31]
	v_mfma_f32_16x16x32_bf16 v[24:27], v[152:155], v[196:199], v[24:27]
	v_mfma_f32_16x16x32_bf16 v[12:15], v[144:147], v[204:207], v[12:15]
	v_mfma_f32_16x16x32_bf16 v[8:11], v[152:155], v[204:207], v[8:11]
	v_mfma_f32_16x16x32_bf16 v[60:63], v[148:151], v[180:183], v[60:63]
	v_mfma_f32_16x16x32_bf16 v[56:59], v[156:159], v[180:183], v[56:59]
	v_mfma_f32_16x16x32_bf16 v[44:47], v[148:151], v[192:195], v[44:47]
	v_mfma_f32_16x16x32_bf16 v[40:43], v[156:159], v[192:195], v[40:43]
	v_mfma_f32_16x16x32_bf16 v[28:31], v[148:151], v[200:203], v[28:31]
	v_mfma_f32_16x16x32_bf16 v[24:27], v[156:159], v[200:203], v[24:27]
	v_mfma_f32_16x16x32_bf16 v[12:15], v[148:151], v[208:211], v[12:15]
	v_mfma_f32_16x16x32_bf16 v[8:11], v[156:159], v[208:211], v[8:11]
	s_setprio 0
	s_setprio 1
	v_mfma_f32_16x16x32_bf16 v[52:55], v[160:163], v[176:179], v[52:55]
	v_mfma_f32_16x16x32_bf16 v[48:51], v[168:171], v[176:179], v[48:51]
	v_mfma_f32_16x16x32_bf16 v[36:39], v[160:163], v[188:191], v[36:39]
	v_mfma_f32_16x16x32_bf16 v[32:35], v[168:171], v[188:191], v[32:35]
	v_mfma_f32_16x16x32_bf16 v[20:23], v[160:163], v[196:199], v[20:23]
	v_mfma_f32_16x16x32_bf16 v[16:19], v[168:171], v[196:199], v[16:19]
	v_mfma_f32_16x16x32_bf16 v[4:7], v[160:163], v[204:207], v[4:7]
	v_mfma_f32_16x16x32_bf16 v[0:3], v[168:171], v[204:207], v[0:3]
	v_mfma_f32_16x16x32_bf16 v[52:55], v[164:167], v[180:183], v[52:55]
	v_mfma_f32_16x16x32_bf16 v[48:51], v[172:175], v[180:183], v[48:51]
	v_mfma_f32_16x16x32_bf16 v[36:39], v[164:167], v[192:195], v[36:39]
	v_mfma_f32_16x16x32_bf16 v[32:35], v[172:175], v[192:195], v[32:35]
	v_mfma_f32_16x16x32_bf16 v[20:23], v[164:167], v[200:203], v[20:23]
	v_mfma_f32_16x16x32_bf16 v[16:19], v[172:175], v[200:203], v[16:19]
	v_mfma_f32_16x16x32_bf16 v[4:7], v[164:167], v[208:211], v[4:7]
	v_mfma_f32_16x16x32_bf16 v[0:3], v[172:175], v[208:211], v[0:3]
	s_setprio 0
	s_barrier
	s_add_u32 s53, s53, 0x100
	s_addc_u32 s54, s54, 0
	s_add_u32 s38, s38, 0x100
	s_addc_u32 s39, s39, 0
	s_cmp_ge_i32 s55, s46
	s_mov_b32 s40, s55
	s_cbranch_scc0 .LBB0_108
	s_and_b64 vcc, exec, s[20:21]
	s_cbranch_vccz .LBB0_111

; #define PG8_STAGE(bufoff, gbase, voff) do { _Pragma("unroll") for (int _i = 0; _i < 2; ++_i) \
;         __builtin_amdgcn_global_load_lds((const unsigned*)((const char*)(gbase) + (voff)[_i]), (LAS unsigned*)(lds + (bufoff) + ldsw + _i * 8192), 16, 0, 0); } while (0)
; #define PG8_LDA(dst, b, h) do { _Pragma("unroll") for (int m = 0; m < 4; ++m) _Pragma("unroll") for (int k = 0; k < 2; ++k) dst[m][k] = *(const LAS bf16x8*)(lds + PG8_SA(b, h) + aoff + m * 2048 + k * 1024); } while (0)
; #define PG8_LDB(dst, b, h) do { _Pragma("unroll") for (int n = 0; n < 2; ++n) _Pragma("unroll") for (int k = 0; k < 2; ++k) dst[n][k] = *(const LAS bf16x8*)(lds + PG8_SB(b, h) + boff + n * 2048 + k * 1024); } while (0)
; #define PG8_MMA(ai, bj, At, Bt) do { __builtin_amdgcn_s_setprio(1); _Pragma("unroll") for (int m = 0; m < 4; ++m) _Pragma("unroll") for (int n = 0; n < 2; ++n) _Pragma("unroll") for (int k = 0; k < 2; ++k) \
;         acc[ai][bj][m][n] = __builtin_amdgcn_mfma_f32_16x16x32_bf16(Bt[n][k], At[m][k], acc[ai][bj][m][n], 0, 0, 0); __builtin_amdgcn_s_setprio(0); } while (0)
; #define PG8_WAIT_V(n) asm volatile("s_waitcnt vmcnt(" #n ")" ::: "memory")
; #define PG8_WAIT_L(n) asm volatile("s_waitcnt lgkmcnt(" #n ")" ::: "memory")
; #define PG8_BAR __builtin_amdgcn_s_barrier()
; #define PG8_SCHED __builtin_amdgcn_sched_barrier(0)
; template <class Epi, bool ALIGN_EPI>
; __device__ __forceinline__ void gemm_phase(LAS unsigned char* lds, const Gemm g, const StaticOrder& S, const Epi& E, const int wave_s) {
;     ...
;         for (int t = 0; t < nt; t += 2) {
;             const bool last = (t == nt - 2);
;             const char* a1 = cA + (size_t)(t + 1) * kstep;
;             const char* a2 = last ? nA : cA + (size_t)(t + 2) * kstep; const char* b2 = last ? nB : cB + (size_t)(t + 2) * kstep;
;             const char* a3 = a2 + kstep; const char* b3 = b2 + kstep;
;             PG8_LDB(B0, 0, 0); PG8_LDB(B1, 0, 1); PG8_SCHED; PG8_LDA(At, 0, 0); PG8_STAGE(PG8_SA(1, 1), a1 + hstepA, voffA);
;             PG8_WAIT_V(8); PG8_WAIT_L(0); PG8_BAR; PG8_MMA(0, 0, At, B0); PG8_MMA(0, 1, At, B1); PG8_BAR; PG8_SCHED;
;             PG8_LDA(At, 0, 1); PG8_STAGE(PG8_SB(0, 0), b2, voffB); PG8_STAGE(PG8_SB(0, 1), b2 + hstepB, voffB); PG8_STAGE(PG8_SA(0, 0), a2, voffA);
;             PG8_WAIT_V(8); PG8_WAIT_L(0); PG8_BAR; PG8_MMA(1, 0, At, B0); PG8_MMA(1, 1, At, B1); PG8_BAR; PG8_SCHED;
.LBB0_138:
	s_add_i32 s55, s40, 2
	s_add_u32 s56, s38, 0x80
	s_addc_u32 s41, s39, 0
	s_add_i32 s58, 0, 0x10000
	s_cmp_eq_u32 s47, s40
	s_cselect_b32 s41, s1, s41
	s_cselect_b32 s40, s0, s56
	v_add_u32_e32 v142, s58, v145
	s_cselect_b32 s57, s29, s54
	s_cselect_b32 s56, s28, s53
	s_add_i32 s59, 0, 0x14000
	ds_read_b128 v[138:141], v142
	ds_read_b128 v[148:151], v142 offset:1024
	ds_read_b128 v[152:155], v142 offset:2048
	ds_read_b128 v[156:159], v142 offset:3072
	v_add_u32_e32 v142, s59, v145
	ds_read_b128 v[160:163], v142
	ds_read_b128 v[164:167], v142 offset:1024
	ds_read_b128 v[168:171], v142 offset:2048
	ds_read_b128 v[172:175], v142 offset:3072
	s_add_i32 m0, s24, 0xc000
	ds_read_b128 v[176:179], v147
	ds_read_b128 v[180:183], v147 offset:1024
	ds_read_b128 v[188:191], v147 offset:2048
	ds_read_b128 v[192:195], v147 offset:3072
	ds_read_b128 v[196:199], v147 offset:4096
	ds_read_b128 v[200:203], v147 offset:5120
	ds_read_b128 v[204:207], v147 offset:6144
	ds_read_b128 v[208:211], v147 offset:7168
	global_load_lds_dwordx4 v136, s[38:39]
	s_add_i32 m0, s24, 0xe000
	s_nop 0
	global_load_lds_dwordx4 v134, s[38:39]
	s_waitcnt vmcnt(8)
	s_waitcnt lgkmcnt(0)
	s_barrier
	s_setprio 1
	s_waitcnt lgkmcnt(0)
	v_mfma_f32_16x16x32_bf16 v[124:127], v[138:141], v[176:179], v[124:127]
	v_mfma_f32_16x16x32_bf16 v[120:123], v[152:155], v[176:179], v[120:123]
	v_mfma_f32_16x16x32_bf16 v[108:111], v[138:141], v[188:191], v[108:111]
	v_mfma_f32_16x16x32_bf16 v[104:107], v[152:155], v[188:191], v[104:107]
	v_mfma_f32_16x16x32_bf16 v[92:95], v[138:141], v[196:199], v[92:95]
	v_mfma_f32_16x16x32_bf16 v[88:91], v[152:155], v[196:199], v[88:91]
	v_mfma_f32_16x16x32_bf16 v[76:79], v[138:141], v[204:207], v[76:79]
	v_mfma_f32_16x16x32_bf16 v[72:75], v[152:155], v[204:207], v[72:75]
	v_mfma_f32_16x16x32_bf16 v[124:127], v[148:151], v[180:183], v[124:127]
	v_mfma_f32_16x16x32_bf16 v[120:123], v[156:159], v[180:183], v[120:123]
	v_mfma_f32_16x16x32_bf16 v[108:111], v[148:151], v[192:195], v[108:111]
	v_mfma_f32_16x16x32_bf16 v[104:107], v[156:159], v[192:195], v[104:107]
	v_mfma_f32_16x16x32_bf16 v[92:95], v[148:151], v[200:203], v[92:95]
	v_mfma_f32_16x16x32_bf16 v[88:91], v[156:159], v[200:203], v[88:91]
	v_mfma_f32_16x16x32_bf16 v[76:79], v[148:151], v[208:211], v[76:79]
	v_mfma_f32_16x16x32_bf16 v[72:75], v[156:159], v[208:211], v[72:75]
	s_setprio 0
	s_setprio 1
	v_mfma_f32_16x16x32_bf16 v[116:119], v[160:163], v[176:179], v[116:119]
	v_mfma_f32_16x16x32_bf16 v[112:115], v[168:171], v[176:179], v[112:115]
	v_mfma_f32_16x16x32_bf16 v[100:103], v[160:163], v[188:191], v[100:103]
	v_mfma_f32_16x16x32_bf16 v[96:99], v[168:171], v[188:191], v[96:99]
	v_mfma_f32_16x16x32_bf16 v[84:87], v[160:163], v[196:199], v[84:87]
	v_mfma_f32_16x16x32_bf16 v[80:83], v[168:171], v[196:199], v[80:83]
	v_mfma_f32_16x16x32_bf16 v[68:71], v[160:163], v[204:207], v[68:71]
	v_mfma_f32_16x16x32_bf16 v[64:67], v[168:171], v[204:207], v[64:67]
	v_mfma_f32_16x16x32_bf16 v[116:119], v[164:167], v[180:183], v[116:119]
	v_mfma_f32_16x16x32_bf16 v[112:115], v[172:175], v[180:183], v[112:115]
	v_mfma_f32_16x16x32_bf16 v[100:103], v[164:167], v[192:195], v[100:103]
	v_mfma_f32_16x16x32_bf16 v[96:99], v[172:175], v[192:195], v[96:99]
	v_mfma_f32_16x16x32_bf16 v[84:87], v[164:167], v[200:203], v[84:87]
	v_mfma_f32_16x16x32_bf16 v[80:83], v[172:175], v[200:203], v[80:83]
	v_mfma_f32_16x16x32_bf16 v[68:71], v[164:167], v[208:211], v[68:71]
	v_mfma_f32_16x16x32_bf16 v[64:67], v[172:175], v[208:211], v[64:67]
	s_setprio 0
	s_barrier
	s_add_i32 s58, s58, s4
	v_lshl_add_u64 v[142:143], s[56:57], 0, v[184:185]
	s_mov_b32 m0, s58
	ds_read_b128 v[176:179], v147 offset:16384
	ds_read_b128 v[180:183], v147 offset:17408
	ds_read_b128 v[188:191], v147 offset:18432
	ds_read_b128 v[192:195], v147 offset:19456
	ds_read_b128 v[196:199], v147 offset:20480
	ds_read_b128 v[200:203], v147 offset:21504
	ds_read_b128 v[204:207], v147 offset:22528
	ds_read_b128 v[208:211], v147 offset:23552
	global_load_lds_dwordx4 v[142:143], off
	s_add_i32 m0, s58, 0x2000
	v_lshl_add_u64 v[212:213], s[56:57], 0, v[128:129]
	s_add_u32 s56, s56, s10
	s_addc_u32 s57, s57, s11
	s_add_i32 s58, s59, s4
	global_load_lds_dwordx4 v[212:213], off
	v_lshl_add_u64 v[214:215], s[56:57], 0, v[184:185]
	s_mov_b32 m0, s58
	v_lshl_add_u64 v[216:217], s[56:57], 0, v[128:129]
	global_load_lds_dwordx4 v[214:215], off
	s_add_i32 m0, s58, 0x2000
	v_lshl_add_u64 v[218:219], s[40:41], 0, v[132:133]
	global_load_lds_dwordx4 v[216:217], off
	s_mov_b32 m0, s24
	v_lshl_add_u64 v[220:221], s[40:41], 0, v[130:131]
	global_load_lds_dwordx4 v[218:219], off
	s_mov_b32 m0, s25
	s_nop 0
	global_load_lds_dwordx4 v[220:221], off
	s_waitcnt vmcnt(8)
	s_waitcnt lgkmcnt(0)
	s_barrier
; #define PG8_STAGE(bufoff, gbase, voff) do { _Pragma("unroll") for (int _i = 0; _i < 2; ++_i) \
;         __builtin_amdgcn_global_load_lds((const unsigned*)((const char*)(gbase) + (voff)[_i]), (LAS unsigned*)(lds + (bufoff) + ldsw + _i * 8192), 16, 0, 0); } while (0)
; #define PG8_LDA(dst, b, h) do { _Pragma("unroll") for (int m = 0; m < 4; ++m) _Pragma("unroll") for (int k = 0; k < 2; ++k) dst[m][k] = *(const LAS bf16x8*)(lds + PG8_SA(b, h) + aoff + m * 2048 + k * 1024); } while (0)
; #define PG8_LDB(dst, b, h) do { _Pragma("unroll") for (int n = 0; n < 2; ++n) _Pragma("unroll") for (int k = 0; k < 2; ++k) dst[n][k] = *(const LAS bf16x8*)(lds + PG8_SB(b, h) + boff + n * 2048 + k * 1024); } while (0)
; #define PG8_MMA(ai, bj, At, Bt) do { __builtin_amdgcn_s_setprio(1); _Pragma("unroll") for (int m = 0; m < 4; ++m) _Pragma("unroll") for (int n = 0; n < 2; ++n) _Pragma("unroll") for (int k = 0; k < 2; ++k) \
;         acc[ai][bj][m][n] = __builtin_amdgcn_mfma_f32_16x16x32_bf16(Bt[n][k], At[m][k], acc[ai][bj][m][n], 0, 0, 0); __builtin_amdgcn_s_setprio(0); } while (0)
; #define PG8_WAIT_V(n) asm volatile("s_waitcnt vmcnt(" #n ")" ::: "memory")
; #define PG8_WAIT_L(n) asm volatile("s_waitcnt lgkmcnt(" #n ")" ::: "memory")
; #define PG8_BAR __builtin_amdgcn_s_barrier()
; #define PG8_SCHED __builtin_amdgcn_sched_barrier(0)
; template <class Epi, bool ALIGN_EPI>
; __device__ __forceinline__ void gemm_phase(LAS unsigned char* lds, const Gemm g, const StaticOrder& S, const Epi& E, const int wave_s) {
;     ...
;             PG8_WAIT_V(8); PG8_WAIT_L(0); PG8_BAR; PG8_MMA(1, 0, At, B0); PG8_MMA(1, 1, At, B1); PG8_BAR; PG8_SCHED;
;             PG8_LDB(B0, 1, 0); PG8_LDB(B1, 1, 1); PG8_SCHED; PG8_LDA(At, 1, 0); PG8_STAGE(PG8_SA(0, 1), a2 + hstepA, voffA);
;             PG8_WAIT_V(8); PG8_WAIT_L(0); PG8_BAR; PG8_MMA(0, 0, At, B0); PG8_MMA(0, 1, At, B1); PG8_BAR; PG8_SCHED;
	s_setprio 1
	s_waitcnt lgkmcnt(0)
	v_mfma_f32_16x16x32_bf16 v[60:63], v[138:141], v[176:179], v[60:63]
	v_mfma_f32_16x16x32_bf16 v[56:59], v[152:155], v[176:179], v[56:59]
	v_mfma_f32_16x16x32_bf16 v[44:47], v[138:141], v[188:191], v[44:47]
	v_mfma_f32_16x16x32_bf16 v[40:43], v[152:155], v[188:191], v[40:43]
	v_mfma_f32_16x16x32_bf16 v[28:31], v[138:141], v[196:199], v[28:31]
	v_mfma_f32_16x16x32_bf16 v[24:27], v[152:155], v[196:199], v[24:27]
	v_mfma_f32_16x16x32_bf16 v[12:15], v[138:141], v[204:207], v[12:15]
	v_mfma_f32_16x16x32_bf16 v[8:11], v[152:155], v[204:207], v[8:11]
	v_mfma_f32_16x16x32_bf16 v[60:63], v[148:151], v[180:183], v[60:63]
	v_mfma_f32_16x16x32_bf16 v[56:59], v[156:159], v[180:183], v[56:59]
	v_mfma_f32_16x16x32_bf16 v[44:47], v[148:151], v[192:195], v[44:47]
	v_mfma_f32_16x16x32_bf16 v[40:43], v[156:159], v[192:195], v[40:43]
	v_mfma_f32_16x16x32_bf16 v[28:31], v[148:151], v[200:203], v[28:31]
	v_mfma_f32_16x16x32_bf16 v[24:27], v[156:159], v[200:203], v[24:27]
	v_mfma_f32_16x16x32_bf16 v[12:15], v[148:151], v[208:211], v[12:15]
	v_mfma_f32_16x16x32_bf16 v[8:11], v[156:159], v[208:211], v[8:11]
	s_setprio 0
	s_setprio 1
	v_mfma_f32_16x16x32_bf16 v[52:55], v[160:163], v[176:179], v[52:55]
	v_mfma_f32_16x16x32_bf16 v[48:51], v[168:171], v[176:179], v[48:51]
	v_mfma_f32_16x16x32_bf16 v[36:39], v[160:163], v[188:191], v[36:39]
	v_mfma_f32_16x16x32_bf16 v[32:35], v[168:171], v[188:191], v[32:35]
	v_mfma_f32_16x16x32_bf16 v[20:23], v[160:163], v[196:199], v[20:23]
	v_mfma_f32_16x16x32_bf16 v[16:19], v[168:171], v[196:199], v[16:19]
	v_mfma_f32_16x16x32_bf16 v[4:7], v[160:163], v[204:207], v[4:7]
	v_mfma_f32_16x16x32_bf16 v[0:3], v[168:171], v[204:207], v[0:3]
	v_mfma_f32_16x16x32_bf16 v[52:55], v[164:167], v[180:183], v[52:55]
	v_mfma_f32_16x16x32_bf16 v[48:51], v[172:175], v[180:183], v[48:51]
	v_mfma_f32_16x16x32_bf16 v[36:39], v[164:167], v[192:195], v[36:39]
	v_mfma_f32_16x16x32_bf16 v[32:35], v[172:175], v[192:195], v[32:35]
	v_mfma_f32_16x16x32_bf16 v[20:23], v[164:167], v[200:203], v[20:23]
	v_mfma_f32_16x16x32_bf16 v[16:19], v[172:175], v[200:203], v[16:19]
	v_mfma_f32_16x16x32_bf16 v[4:7], v[164:167], v[208:211], v[4:7]
	v_mfma_f32_16x16x32_bf16 v[0:3], v[172:175], v[208:211], v[0:3]
	s_setprio 0
	s_barrier
	s_add_i32 s56, 0, 0x18000
	s_add_i32 s57, 0, 0x1c000
	v_add_u32_e32 v156, s56, v145
	v_add_u32_e32 v172, s57, v145
	ds_read_b128 v[138:141], v156
	ds_read_b128 v[148:151], v156 offset:1024
	ds_read_b128 v[152:155], v156 offset:2048
	ds_read_b128 v[156:159], v156 offset:3072
	ds_read_b128 v[160:163], v172
	ds_read_b128 v[164:167], v172 offset:1024
	ds_read_b128 v[168:171], v172 offset:2048
	ds_read_b128 v[172:175], v172 offset:3072
	s_add_u32 s40, s40, s8
	s_addc_u32 s41, s41, s9
	s_mov_b32 m0, s42
	ds_read_b128 v[176:179], v147 offset:32768
	ds_read_b128 v[180:183], v147 offset:33792
	ds_read_b128 v[188:191], v147 offset:34816
	ds_read_b128 v[192:195], v147 offset:35840
	ds_read_b128 v[196:199], v147 offset:36864
	ds_read_b128 v[200:203], v147 offset:37888
	ds_read_b128 v[204:207], v147 offset:38912
	ds_read_b128 v[208:211], v147 offset:39936
	global_load_lds_dwordx4 v132, s[40:41]
	v_lshl_add_u64 v[222:223], s[40:41], 0, v[130:131]
	s_mov_b32 m0, s43
	s_nop 0
	global_load_lds_dwordx4 v[222:223], off
	s_waitcnt vmcnt(8)
	s_waitcnt lgkmcnt(0)
	s_barrier
	s_setprio 1
	s_waitcnt lgkmcnt(0)
	v_mfma_f32_16x16x32_bf16 v[124:127], v[138:141], v[176:179], v[124:127]
	v_mfma_f32_16x16x32_bf16 v[120:123], v[152:155], v[176:179], v[120:123]
	v_mfma_f32_16x16x32_bf16 v[108:111], v[138:141], v[188:191], v[108:111]
	v_mfma_f32_16x16x32_bf16 v[104:107], v[152:155], v[188:191], v[104:107]
	v_mfma_f32_16x16x32_bf16 v[92:95], v[138:141], v[196:199], v[92:95]
	v_mfma_f32_16x16x32_bf16 v[88:91], v[152:155], v[196:199], v[88:91]
	v_mfma_f32_16x16x32_bf16 v[76:79], v[138:141], v[204:207], v[76:79]
	v_mfma_f32_16x16x32_bf16 v[72:75], v[152:155], v[204:207], v[72:75]
	v_mfma_f32_16x16x32_bf16 v[124:127], v[148:151], v[180:183], v[124:127]
	v_mfma_f32_16x16x32_bf16 v[120:123], v[156:159], v[180:183], v[120:123]
	v_mfma_f32_16x16x32_bf16 v[108:111], v[148:151], v[192:195], v[108:111]
	v_mfma_f32_16x16x32_bf16 v[104:107], v[156:159], v[192:195], v[104:107]
	v_mfma_f32_16x16x32_bf16 v[92:95], v[148:151], v[200:203], v[92:95]
	v_mfma_f32_16x16x32_bf16 v[88:91], v[156:159], v[200:203], v[88:91]
	v_mfma_f32_16x16x32_bf16 v[76:79], v[148:151], v[208:211], v[76:79]
	v_mfma_f32_16x16x32_bf16 v[72:75], v[156:159], v[208:211], v[72:75]
	s_setprio 0
	s_setprio 1
	v_mfma_f32_16x16x32_bf16 v[116:119], v[160:163], v[176:179], v[116:119]
	v_mfma_f32_16x16x32_bf16 v[112:115], v[168:171], v[176:179], v[112:115]
	v_mfma_f32_16x16x32_bf16 v[100:103], v[160:163], v[188:191], v[100:103]
	v_mfma_f32_16x16x32_bf16 v[96:99], v[168:171], v[188:191], v[96:99]
	v_mfma_f32_16x16x32_bf16 v[84:87], v[160:163], v[196:199], v[84:87]
	v_mfma_f32_16x16x32_bf16 v[80:83], v[168:171], v[196:199], v[80:83]
	v_mfma_f32_16x16x32_bf16 v[68:71], v[160:163], v[204:207], v[68:71]
	v_mfma_f32_16x16x32_bf16 v[64:67], v[168:171], v[204:207], v[64:67]
	v_mfma_f32_16x16x32_bf16 v[116:119], v[164:167], v[180:183], v[116:119]
	v_mfma_f32_16x16x32_bf16 v[112:115], v[172:175], v[180:183], v[112:115]
	v_mfma_f32_16x16x32_bf16 v[100:103], v[164:167], v[192:195], v[100:103]
	v_mfma_f32_16x16x32_bf16 v[96:99], v[172:175], v[192:195], v[96:99]
	v_mfma_f32_16x16x32_bf16 v[84:87], v[164:167], v[200:203], v[84:87]
	v_mfma_f32_16x16x32_bf16 v[80:83], v[172:175], v[200:203], v[80:83]
	v_mfma_f32_16x16x32_bf16 v[68:71], v[164:167], v[208:211], v[68:71]
	v_mfma_f32_16x16x32_bf16 v[64:67], v[172:175], v[208:211], v[64:67]
	s_setprio 0
	s_barrier
; #define PG8_STAGE(bufoff, gbase, voff) do { _Pragma("unroll") for (int _i = 0; _i < 2; ++_i) \
;         __builtin_amdgcn_global_load_lds((const unsigned*)((const char*)(gbase) + (voff)[_i]), (LAS unsigned*)(lds + (bufoff) + ldsw + _i * 8192), 16, 0, 0); } while (0)
; #define PG8_LDA(dst, b, h) do { _Pragma("unroll") for (int m = 0; m < 4; ++m) _Pragma("unroll") for (int k = 0; k < 2; ++k) dst[m][k] = *(const LAS bf16x8*)(lds + PG8_SA(b, h) + aoff + m * 2048 + k * 1024); } while (0)
; #define PG8_MMA(ai, bj, At, Bt) do { __builtin_amdgcn_s_setprio(1); _Pragma("unroll") for (int m = 0; m < 4; ++m) _Pragma("unroll") for (int n = 0; n < 2; ++n) _Pragma("unroll") for (int k = 0; k < 2; ++k) \
;         acc[ai][bj][m][n] = __builtin_amdgcn_mfma_f32_16x16x32_bf16(Bt[n][k], At[m][k], acc[ai][bj][m][n], 0, 0, 0); __builtin_amdgcn_s_setprio(0); } while (0)
; #define PG8_WAIT_V(n) asm volatile("s_waitcnt vmcnt(" #n ")" ::: "memory")
; #define PG8_WAIT_L(n) asm volatile("s_waitcnt lgkmcnt(" #n ")" ::: "memory")
; #define PG8_BAR __builtin_amdgcn_s_barrier()
; #define PG8_SCHED __builtin_amdgcn_sched_barrier(0)
; template <class Epi, bool ALIGN_EPI>
; __device__ __forceinline__ void gemm_phase(LAS unsigned char* lds, const Gemm g, const StaticOrder& S, const Epi& E, const int wave_s) {
;     ...
;             PG8_LDA(At, 1, 1); PG8_STAGE(PG8_SB(1, 0), b3, voffB); PG8_STAGE(PG8_SB(1, 1), b3 + hstepB, voffB); PG8_STAGE(PG8_SA(1, 0), a3, voffA);
;             PG8_WAIT_V(8); PG8_WAIT_L(0); PG8_BAR; PG8_MMA(1, 0, At, B0); PG8_MMA(1, 1, At, B1); PG8_BAR; PG8_SCHED;
;         }
	s_add_i32 s40, s56, s4
	v_lshl_add_u64 v[142:143], v[142:143], 0, s[64:65]
	s_mov_b32 m0, s40
	ds_read_b128 v[176:179], v147 offset:49152
	ds_read_b128 v[180:183], v147 offset:50176
	ds_read_b128 v[188:191], v147 offset:51200
	ds_read_b128 v[192:195], v147 offset:52224
	ds_read_b128 v[196:199], v147 offset:53248
	ds_read_b128 v[200:203], v147 offset:54272
	ds_read_b128 v[204:207], v147 offset:55296
	ds_read_b128 v[208:211], v147 offset:56320
	global_load_lds_dwordx4 v[142:143], off
	v_lshl_add_u64 v[142:143], v[212:213], 0, s[64:65]
	s_add_i32 m0, s40, 0x2000
	s_add_i32 s40, s57, s4
	global_load_lds_dwordx4 v[142:143], off
	v_lshl_add_u64 v[142:143], v[214:215], 0, s[64:65]
	s_mov_b32 m0, s40
	s_nop 0
	global_load_lds_dwordx4 v[142:143], off
	v_lshl_add_u64 v[142:143], v[216:217], 0, s[64:65]
	s_add_i32 m0, s40, 0x2000
	s_nop 0
	global_load_lds_dwordx4 v[142:143], off
	v_lshl_add_u64 v[142:143], v[218:219], 0, s[64:65]
	s_mov_b32 m0, s44
	s_nop 0
	global_load_lds_dwordx4 v[142:143], off
	v_lshl_add_u64 v[142:143], v[220:221], 0, s[64:65]
	s_mov_b32 m0, s45
	s_nop 0
	global_load_lds_dwordx4 v[142:143], off
	s_waitcnt vmcnt(8)
	s_waitcnt lgkmcnt(0)
	s_barrier
	s_setprio 1
	s_waitcnt lgkmcnt(0)
	v_mfma_f32_16x16x32_bf16 v[60:63], v[138:141], v[176:179], v[60:63]
	v_mfma_f32_16x16x32_bf16 v[56:59], v[152:155], v[176:179], v[56:59]
	v_mfma_f32_16x16x32_bf16 v[44:47], v[138:141], v[188:191], v[44:47]
	v_mfma_f32_16x16x32_bf16 v[40:43], v[152:155], v[188:191], v[40:43]
	v_mfma_f32_16x16x32_bf16 v[28:31], v[138:141], v[196:199], v[28:31]
	v_mfma_f32_16x16x32_bf16 v[24:27], v[152:155], v[196:199], v[24:27]
	v_mfma_f32_16x16x32_bf16 v[12:15], v[138:141], v[204:207], v[12:15]
	v_mfma_f32_16x16x32_bf16 v[8:11], v[152:155], v[204:207], v[8:11]
	v_mfma_f32_16x16x32_bf16 v[60:63], v[148:151], v[180:183], v[60:63]
	v_mfma_f32_16x16x32_bf16 v[56:59], v[156:159], v[180:183], v[56:59]
	v_mfma_f32_16x16x32_bf16 v[44:47], v[148:151], v[192:195], v[44:47]
	v_mfma_f32_16x16x32_bf16 v[40:43], v[156:159], v[192:195], v[40:43]
	v_mfma_f32_16x16x32_bf16 v[28:31], v[148:151], v[200:203], v[28:31]
	v_mfma_f32_16x16x32_bf16 v[24:27], v[156:159], v[200:203], v[24:27]
	v_mfma_f32_16x16x32_bf16 v[12:15], v[148:151], v[208:211], v[12:15]
	v_mfma_f32_16x16x32_bf16 v[8:11], v[156:159], v[208:211], v[8:11]
	s_setprio 0
	s_setprio 1
	v_mfma_f32_16x16x32_bf16 v[52:55], v[160:163], v[176:179], v[52:55]
	v_mfma_f32_16x16x32_bf16 v[48:51], v[168:171], v[176:179], v[48:51]
	v_mfma_f32_16x16x32_bf16 v[36:39], v[160:163], v[188:191], v[36:39]
	v_mfma_f32_16x16x32_bf16 v[32:35], v[168:171], v[188:191], v[32:35]
	v_mfma_f32_16x16x32_bf16 v[20:23], v[160:163], v[196:199], v[20:23]
	v_mfma_f32_16x16x32_bf16 v[16:19], v[168:171], v[196:199], v[16:19]
	v_mfma_f32_16x16x32_bf16 v[4:7], v[160:163], v[204:207], v[4:7]
	v_mfma_f32_16x16x32_bf16 v[0:3], v[168:171], v[204:207], v[0:3]
	v_mfma_f32_16x16x32_bf16 v[52:55], v[164:167], v[180:183], v[52:55]
	v_mfma_f32_16x16x32_bf16 v[48:51], v[172:175], v[180:183], v[48:51]
	v_mfma_f32_16x16x32_bf16 v[36:39], v[164:167], v[192:195], v[36:39]
	v_mfma_f32_16x16x32_bf16 v[32:35], v[172:175], v[192:195], v[32:35]
	v_mfma_f32_16x16x32_bf16 v[20:23], v[164:167], v[200:203], v[20:23]
	v_mfma_f32_16x16x32_bf16 v[16:19], v[172:175], v[200:203], v[16:19]
	v_mfma_f32_16x16x32_bf16 v[4:7], v[164:167], v[208:211], v[4:7]
	v_mfma_f32_16x16x32_bf16 v[0:3], v[172:175], v[208:211], v[0:3]
	s_setprio 0
	s_barrier
	s_add_u32 s53, s53, 0x100
	s_addc_u32 s54, s54, 0
	s_add_u32 s38, s38, 0x100
	s_addc_u32 s39, s39, 0
	s_cmp_ge_i32 s55, s46
	s_mov_b32 s40, s55
	s_cbranch_scc0 .LBB0_138
	s_and_b64 vcc, exec, s[20:21]
	s_cbranch_vccz .LBB0_141

; #define PG8_STAGE(bufoff, gbase, voff) do { _Pragma("unroll") for (int _i = 0; _i < 2; ++_i) \
;         __builtin_amdgcn_global_load_lds((const unsigned*)((const char*)(gbase) + (voff)[_i]), (LAS unsigned*)(lds + (bufoff) + ldsw + _i * 8192), 16, 0, 0); } while (0)
; #define PG8_LDA(dst, b, h) do { _Pragma("unroll") for (int m = 0; m < 4; ++m) _Pragma("unroll") for (int k = 0; k < 2; ++k) dst[m][k] = *(const LAS bf16x8*)(lds + PG8_SA(b, h) + aoff + m * 2048 + k * 1024); } while (0)
; #define PG8_LDB(dst, b, h) do { _Pragma("unroll") for (int n = 0; n < 2; ++n) _Pragma("unroll") for (int k = 0; k < 2; ++k) dst[n][k] = *(const LAS bf16x8*)(lds + PG8_SB(b, h) + boff + n * 2048 + k * 1024); } while (0)
; #define PG8_MMA(ai, bj, At, Bt) do { __builtin_amdgcn_s_setprio(1); _Pragma("unroll") for (int m = 0; m < 4; ++m) _Pragma("unroll") for (int n = 0; n < 2; ++n) _Pragma("unroll") for (int k = 0; k < 2; ++k) \
;         acc[ai][bj][m][n] = __builtin_amdgcn_mfma_f32_16x16x32_bf16(Bt[n][k], At[m][k], acc[ai][bj][m][n], 0, 0, 0); __builtin_amdgcn_s_setprio(0); } while (0)
; #define PG8_WAIT_V(n) asm volatile("s_waitcnt vmcnt(" #n ")" ::: "memory")
; #define PG8_WAIT_L(n) asm volatile("s_waitcnt lgkmcnt(" #n ")" ::: "memory")
; #define PG8_BAR __builtin_amdgcn_s_barrier()
; #define PG8_SCHED __builtin_amdgcn_sched_barrier(0)
; template <class Epi, bool ALIGN_EPI>
; __device__ __forceinline__ void gemm_phase(LAS unsigned char* lds, const Gemm g, const StaticOrder& S, const Epi& E, const int wave_s) {
;     ...
;         for (int t = 0; t < nt; t += 2) {
;             const bool last = (t == nt - 2);
;             const char* a1 = cA + (size_t)(t + 1) * kstep;
;             const char* a2 = last ? nA : cA + (size_t)(t + 2) * kstep; const char* b2 = last ? nB : cB + (size_t)(t + 2) * kstep;
;             const char* a3 = a2 + kstep; const char* b3 = b2 + kstep;
;             PG8_LDB(B0, 0, 0); PG8_LDB(B1, 0, 1); PG8_SCHED; PG8_LDA(At, 0, 0); PG8_STAGE(PG8_SA(1, 1), a1 + hstepA, voffA);
;             PG8_WAIT_V(8); PG8_WAIT_L(0); PG8_BAR; PG8_MMA(0, 0, At, B0); PG8_MMA(0, 1, At, B1); PG8_BAR; PG8_SCHED;
;             PG8_LDA(At, 0, 1); PG8_STAGE(PG8_SB(0, 0), b2, voffB); PG8_STAGE(PG8_SB(0, 1), b2 + hstepB, voffB); PG8_STAGE(PG8_SA(0, 0), a2, voffA);
;             PG8_WAIT_V(8); PG8_WAIT_L(0); PG8_BAR; PG8_MMA(1, 0, At, B0); PG8_MMA(1, 1, At, B1); PG8_BAR; PG8_SCHED;
.LBB0_180:
	s_add_i32 s40, s38, 2
	s_add_u32 s41, s0, 0x80
	s_addc_u32 s39, s1, 0
	s_add_i32 s45, 0, 0x10000
	s_cmp_eq_u32 s93, s38
	s_cselect_b32 s39, s69, s39
	s_cselect_b32 s38, s68, s41
	v_add_u32_e32 v20, s45, v212
	s_cselect_b32 s49, s71, s44
	s_cselect_b32 s48, s70, s43
	s_add_i32 s41, 0, 0x14000
	ds_read_b128 v[96:99], v20
	ds_read_b128 v[100:103], v20 offset:1024
	ds_read_b128 v[104:107], v20 offset:2048
	ds_read_b128 v[140:143], v20 offset:3072
	v_add_u32_e32 v20, s41, v212
	ds_read_b128 v[152:155], v20
	ds_read_b128 v[156:159], v20 offset:1024
	ds_read_b128 v[170:173], v20 offset:2048
	ds_read_b128 v[174:177], v20 offset:3072
	s_add_i32 m0, s82, 0xc000
	ds_read_b128 v[178:181], v213
	ds_read_b128 v[188:191], v213 offset:1024
	ds_read_b128 v[192:195], v213 offset:2048
	ds_read_b128 v[196:199], v213 offset:3072
	ds_read_b128 v[200:203], v213 offset:4096
	ds_read_b128 v[204:207], v213 offset:5120
	ds_read_b128 v[214:217], v213 offset:6144
	ds_read_b128 v[218:221], v213 offset:7168
	global_load_lds_dwordx4 v168, s[0:1]
	v_lshl_add_u64 v[20:21], s[0:1], 0, v[166:167]
	s_add_i32 m0, s82, 0xe000
	s_nop 0
	global_load_lds_dwordx4 v[20:21], off
	s_waitcnt vmcnt(8)
	s_waitcnt lgkmcnt(0)
	s_barrier
	s_setprio 1
	s_waitcnt lgkmcnt(0)
	v_mfma_f32_16x16x32_bf16 v[148:151], v[96:99], v[178:181], v[148:151]
	v_mfma_f32_16x16x32_bf16 v[52:55], v[104:107], v[178:181], v[54:57]
	v_mfma_f32_16x16x32_bf16 v[144:147], v[96:99], v[192:195], v[144:147]
	v_mfma_f32_16x16x32_bf16 v[66:69], v[104:107], v[192:195], v[66:69]
	v_mfma_f32_16x16x32_bf16 v[132:135], v[96:99], v[200:203], v[132:135]
	v_mfma_f32_16x16x32_bf16 v[56:59], v[104:107], v[200:203], v[58:61]
	v_mfma_f32_16x16x32_bf16 v[124:127], v[96:99], v[214:217], v[124:127]
	v_mfma_f32_16x16x32_bf16 v[42:45], v[104:107], v[214:217], v[44:47]
	v_mfma_f32_16x16x32_bf16 v[148:151], v[100:103], v[188:191], v[148:151]
	v_mfma_f32_16x16x32_bf16 v[52:55], v[140:143], v[188:191], v[52:55]
	v_mfma_f32_16x16x32_bf16 v[144:147], v[100:103], v[196:199], v[144:147]
	v_mfma_f32_16x16x32_bf16 v[66:69], v[140:143], v[196:199], v[66:69]
	v_mfma_f32_16x16x32_bf16 v[132:135], v[100:103], v[204:207], v[132:135]
	v_mfma_f32_16x16x32_bf16 v[58:61], v[140:143], v[204:207], v[56:59]
	v_mfma_f32_16x16x32_bf16 v[124:127], v[100:103], v[218:221], v[124:127]
	v_mfma_f32_16x16x32_bf16 v[42:45], v[140:143], v[218:221], v[42:45]
	s_setprio 0
	s_setprio 1
	v_mfma_f32_16x16x32_bf16 v[136:139], v[152:155], v[178:181], v[136:139]
	v_mfma_f32_16x16x32_bf16 v[62:65], v[170:173], v[178:181], v[62:65]
	v_mfma_f32_16x16x32_bf16 v[128:131], v[152:155], v[192:195], v[128:131]
	v_mfma_f32_16x16x32_bf16 v[46:49], v[170:173], v[192:195], v[48:51]
	v_mfma_f32_16x16x32_bf16 v[120:123], v[152:155], v[200:203], v[120:123]
	v_mfma_f32_16x16x32_bf16 v[38:41], v[170:173], v[200:203], v[38:41]
	v_mfma_f32_16x16x32_bf16 v[116:119], v[152:155], v[214:217], v[116:119]
	v_mfma_f32_16x16x32_bf16 v[34:37], v[170:173], v[214:217], v[34:37]
	v_mfma_f32_16x16x32_bf16 v[136:139], v[156:159], v[188:191], v[136:139]
	v_mfma_f32_16x16x32_bf16 v[62:65], v[174:177], v[188:191], v[62:65]
	v_mfma_f32_16x16x32_bf16 v[128:131], v[156:159], v[196:199], v[128:131]
	v_mfma_f32_16x16x32_bf16 v[48:51], v[174:177], v[196:199], v[46:49]
	v_mfma_f32_16x16x32_bf16 v[120:123], v[156:159], v[204:207], v[120:123]
	v_mfma_f32_16x16x32_bf16 v[38:41], v[174:177], v[204:207], v[38:41]
	v_mfma_f32_16x16x32_bf16 v[116:119], v[156:159], v[218:221], v[116:119]
	v_mfma_f32_16x16x32_bf16 v[34:37], v[174:177], v[218:221], v[34:37]
	s_setprio 0
	s_barrier
	s_add_i32 s45, s45, s4
	v_lshl_add_u64 v[182:183], s[48:49], 0, v[184:185]
	s_mov_b32 m0, s45
	ds_read_b128 v[178:181], v213 offset:16384
	ds_read_b128 v[188:191], v213 offset:17408
	ds_read_b128 v[192:195], v213 offset:18432
	ds_read_b128 v[196:199], v213 offset:19456
	ds_read_b128 v[200:203], v213 offset:20480
	ds_read_b128 v[204:207], v213 offset:21504
	ds_read_b128 v[214:217], v213 offset:22528
	ds_read_b128 v[218:221], v213 offset:23552
	global_load_lds_dwordx4 v[182:183], off
	s_add_i32 m0, s45, 0x2000
	v_lshl_add_u64 v[208:209], s[48:49], 0, v[160:161]
	s_add_u32 s48, s48, s16
	s_addc_u32 s49, s49, s17
	s_add_i32 s41, s41, s4
	global_load_lds_dwordx4 v[208:209], off
	v_lshl_add_u64 v[222:223], s[48:49], 0, v[184:185]
	s_mov_b32 m0, s41
	v_lshl_add_u64 v[224:225], s[48:49], 0, v[160:161]
	global_load_lds_dwordx4 v[222:223], off
	s_add_i32 m0, s41, 0x2000
	v_lshl_add_u64 v[226:227], s[38:39], 0, v[164:165]
	global_load_lds_dwordx4 v[224:225], off
	s_mov_b32 m0, s82
	v_lshl_add_u64 v[228:229], s[38:39], 0, v[162:163]
	global_load_lds_dwordx4 v[226:227], off
	s_mov_b32 m0, s95
	s_nop 0
	global_load_lds_dwordx4 v[228:229], off
	s_waitcnt vmcnt(8)
	s_waitcnt lgkmcnt(0)
	s_barrier
; #define PG8_STAGE(bufoff, gbase, voff) do { _Pragma("unroll") for (int _i = 0; _i < 2; ++_i) \
;         __builtin_amdgcn_global_load_lds((const unsigned*)((const char*)(gbase) + (voff)[_i]), (LAS unsigned*)(lds + (bufoff) + ldsw + _i * 8192), 16, 0, 0); } while (0)
; #define PG8_LDA(dst, b, h) do { _Pragma("unroll") for (int m = 0; m < 4; ++m) _Pragma("unroll") for (int k = 0; k < 2; ++k) dst[m][k] = *(const LAS bf16x8*)(lds + PG8_SA(b, h) + aoff + m * 2048 + k * 1024); } while (0)
; #define PG8_LDB(dst, b, h) do { _Pragma("unroll") for (int n = 0; n < 2; ++n) _Pragma("unroll") for (int k = 0; k < 2; ++k) dst[n][k] = *(const LAS bf16x8*)(lds + PG8_SB(b, h) + boff + n * 2048 + k * 1024); } while (0)
; #define PG8_MMA(ai, bj, At, Bt) do { __builtin_amdgcn_s_setprio(1); _Pragma("unroll") for (int m = 0; m < 4; ++m) _Pragma("unroll") for (int n = 0; n < 2; ++n) _Pragma("unroll") for (int k = 0; k < 2; ++k) \
;         acc[ai][bj][m][n] = __builtin_amdgcn_mfma_f32_16x16x32_bf16(Bt[n][k], At[m][k], acc[ai][bj][m][n], 0, 0, 0); __builtin_amdgcn_s_setprio(0); } while (0)
; #define PG8_WAIT_V(n) asm volatile("s_waitcnt vmcnt(" #n ")" ::: "memory")
; #define PG8_WAIT_L(n) asm volatile("s_waitcnt lgkmcnt(" #n ")" ::: "memory")
; #define PG8_BAR __builtin_amdgcn_s_barrier()
; #define PG8_SCHED __builtin_amdgcn_sched_barrier(0)
; template <class Epi, bool ALIGN_EPI>
; __device__ __forceinline__ void gemm_phase(LAS unsigned char* lds, const Gemm g, const StaticOrder& S, const Epi& E, const int wave_s) {
;     ...
;             PG8_WAIT_V(8); PG8_WAIT_L(0); PG8_BAR; PG8_MMA(1, 0, At, B0); PG8_MMA(1, 1, At, B1); PG8_BAR; PG8_SCHED;
;             PG8_LDB(B0, 1, 0); PG8_LDB(B1, 1, 1); PG8_SCHED; PG8_LDA(At, 1, 0); PG8_STAGE(PG8_SA(0, 1), a2 + hstepA, voffA);
;             PG8_WAIT_V(8); PG8_WAIT_L(0); PG8_BAR; PG8_MMA(0, 0, At, B0); PG8_MMA(0, 1, At, B1); PG8_BAR; PG8_SCHED;
	s_setprio 1
	s_waitcnt lgkmcnt(0)
	v_mfma_f32_16x16x32_bf16 v[112:115], v[96:99], v[178:181], v[112:115]
	v_mfma_f32_16x16x32_bf16 v[30:33], v[104:107], v[178:181], v[30:33]
	v_mfma_f32_16x16x32_bf16 v[108:111], v[96:99], v[192:195], v[108:111]
	v_mfma_f32_16x16x32_bf16 v[26:29], v[104:107], v[192:195], v[26:29]
	v_mfma_f32_16x16x32_bf16 v[88:91], v[96:99], v[200:203], v[88:91]
	v_mfma_f32_16x16x32_bf16 v[16:19], v[104:107], v[200:203], v[16:19]
	v_mfma_f32_16x16x32_bf16 v[78:81], v[96:99], v[214:217], v[80:83]
	v_mfma_f32_16x16x32_bf16 v[8:11], v[104:107], v[214:217], v[8:11]
	v_mfma_f32_16x16x32_bf16 v[112:115], v[100:103], v[188:191], v[112:115]
	v_mfma_f32_16x16x32_bf16 v[30:33], v[140:143], v[188:191], v[30:33]
	v_mfma_f32_16x16x32_bf16 v[108:111], v[100:103], v[196:199], v[108:111]
	v_mfma_f32_16x16x32_bf16 v[26:29], v[140:143], v[196:199], v[26:29]
	v_mfma_f32_16x16x32_bf16 v[88:91], v[100:103], v[204:207], v[88:91]
	v_mfma_f32_16x16x32_bf16 v[16:19], v[140:143], v[204:207], v[16:19]
	v_mfma_f32_16x16x32_bf16 v[78:81], v[100:103], v[218:221], v[78:81]
	v_mfma_f32_16x16x32_bf16 v[8:11], v[140:143], v[218:221], v[8:11]
	s_setprio 0
	s_setprio 1
	v_mfma_f32_16x16x32_bf16 v[92:95], v[152:155], v[178:181], v[92:95]
	v_mfma_f32_16x16x32_bf16 v[20:23], v[170:173], v[178:181], v[22:25]
	v_mfma_f32_16x16x32_bf16 v[82:85], v[152:155], v[192:195], v[84:87]
	v_mfma_f32_16x16x32_bf16 v[12:15], v[170:173], v[192:195], v[12:15]
	v_mfma_f32_16x16x32_bf16 v[74:77], v[152:155], v[200:203], v[74:77]
	v_mfma_f32_16x16x32_bf16 v[4:7], v[170:173], v[200:203], v[4:7]
	v_mfma_f32_16x16x32_bf16 v[70:73], v[152:155], v[214:217], v[70:73]
	v_mfma_f32_16x16x32_bf16 v[0:3], v[170:173], v[214:217], v[0:3]
	v_mfma_f32_16x16x32_bf16 v[92:95], v[156:159], v[188:191], v[92:95]
	v_mfma_f32_16x16x32_bf16 v[20:23], v[174:177], v[188:191], v[20:23]
	v_mfma_f32_16x16x32_bf16 v[84:87], v[156:159], v[196:199], v[82:85]
	v_mfma_f32_16x16x32_bf16 v[12:15], v[174:177], v[196:199], v[12:15]
	v_mfma_f32_16x16x32_bf16 v[74:77], v[156:159], v[204:207], v[74:77]
	v_mfma_f32_16x16x32_bf16 v[4:7], v[174:177], v[204:207], v[4:7]
	v_mfma_f32_16x16x32_bf16 v[70:73], v[156:159], v[218:221], v[70:73]
	v_mfma_f32_16x16x32_bf16 v[0:3], v[174:177], v[218:221], v[0:3]
	s_setprio 0
	s_barrier
	s_add_i32 s41, 0, 0x18000
	v_add_u32_e32 v24, s41, v212
	s_add_i32 s45, 0, 0x1c000
	ds_read_b128 v[96:99], v24
	ds_read_b128 v[100:103], v24 offset:1024
	ds_read_b128 v[104:107], v24 offset:2048
	ds_read_b128 v[140:143], v24 offset:3072
	v_add_u32_e32 v24, s45, v212
	ds_read_b128 v[152:155], v24
	ds_read_b128 v[156:159], v24 offset:1024
	ds_read_b128 v[170:173], v24 offset:2048
	ds_read_b128 v[174:177], v24 offset:3072
	s_add_u32 s38, s38, s14
	s_addc_u32 s39, s39, s15
	s_mov_b32 m0, s87
	ds_read_b128 v[178:181], v213 offset:32768
	ds_read_b128 v[188:191], v213 offset:33792
	ds_read_b128 v[192:195], v213 offset:34816
	ds_read_b128 v[196:199], v213 offset:35840
	ds_read_b128 v[200:203], v213 offset:36864
	ds_read_b128 v[204:207], v213 offset:37888
	ds_read_b128 v[214:217], v213 offset:38912
	ds_read_b128 v[218:221], v213 offset:39936
	global_load_lds_dwordx4 v164, s[38:39]
	s_mov_b32 m0, s24
	s_nop 0
	global_load_lds_dwordx4 v162, s[38:39]
	s_waitcnt vmcnt(8)
	s_waitcnt lgkmcnt(0)
	s_barrier
	s_setprio 1
	s_waitcnt lgkmcnt(0)
	v_mfma_f32_16x16x32_bf16 v[148:151], v[96:99], v[178:181], v[148:151]
	v_mfma_f32_16x16x32_bf16 v[52:55], v[104:107], v[178:181], v[52:55]
	v_mfma_f32_16x16x32_bf16 v[144:147], v[96:99], v[192:195], v[144:147]
	v_mfma_f32_16x16x32_bf16 v[66:69], v[104:107], v[192:195], v[66:69]
	v_mfma_f32_16x16x32_bf16 v[132:135], v[96:99], v[200:203], v[132:135]
	v_mfma_f32_16x16x32_bf16 v[58:61], v[104:107], v[200:203], v[58:61]
	v_mfma_f32_16x16x32_bf16 v[124:127], v[96:99], v[214:217], v[124:127]
	v_mfma_f32_16x16x32_bf16 v[42:45], v[104:107], v[214:217], v[42:45]
	v_mfma_f32_16x16x32_bf16 v[148:151], v[100:103], v[188:191], v[148:151]
	v_mfma_f32_16x16x32_bf16 v[54:57], v[140:143], v[188:191], v[52:55]
	v_mfma_f32_16x16x32_bf16 v[144:147], v[100:103], v[196:199], v[144:147]
	v_mfma_f32_16x16x32_bf16 v[66:69], v[140:143], v[196:199], v[66:69]
	v_mfma_f32_16x16x32_bf16 v[132:135], v[100:103], v[204:207], v[132:135]
	v_mfma_f32_16x16x32_bf16 v[58:61], v[140:143], v[204:207], v[58:61]
	v_mfma_f32_16x16x32_bf16 v[124:127], v[100:103], v[218:221], v[124:127]
	v_mfma_f32_16x16x32_bf16 v[44:47], v[140:143], v[218:221], v[42:45]
	s_setprio 0
	s_setprio 1
	v_mfma_f32_16x16x32_bf16 v[136:139], v[152:155], v[178:181], v[136:139]
	v_mfma_f32_16x16x32_bf16 v[62:65], v[170:173], v[178:181], v[62:65]
	v_mfma_f32_16x16x32_bf16 v[128:131], v[152:155], v[192:195], v[128:131]
	v_mfma_f32_16x16x32_bf16 v[48:51], v[170:173], v[192:195], v[48:51]
	v_mfma_f32_16x16x32_bf16 v[120:123], v[152:155], v[200:203], v[120:123]
	v_mfma_f32_16x16x32_bf16 v[38:41], v[170:173], v[200:203], v[38:41]
	v_mfma_f32_16x16x32_bf16 v[116:119], v[152:155], v[214:217], v[116:119]
	v_mfma_f32_16x16x32_bf16 v[34:37], v[170:173], v[214:217], v[34:37]
	v_mfma_f32_16x16x32_bf16 v[136:139], v[156:159], v[188:191], v[136:139]
	v_mfma_f32_16x16x32_bf16 v[62:65], v[174:177], v[188:191], v[62:65]
	v_mfma_f32_16x16x32_bf16 v[128:131], v[156:159], v[196:199], v[128:131]
	v_mfma_f32_16x16x32_bf16 v[48:51], v[174:177], v[196:199], v[48:51]
	v_mfma_f32_16x16x32_bf16 v[120:123], v[156:159], v[204:207], v[120:123]
	v_mfma_f32_16x16x32_bf16 v[38:41], v[174:177], v[204:207], v[38:41]
	v_mfma_f32_16x16x32_bf16 v[116:119], v[156:159], v[218:221], v[116:119]
	v_mfma_f32_16x16x32_bf16 v[34:37], v[174:177], v[218:221], v[34:37]
	s_setprio 0
	s_barrier
; #define PG8_STAGE(bufoff, gbase, voff) do { _Pragma("unroll") for (int _i = 0; _i < 2; ++_i) \
;         __builtin_amdgcn_global_load_lds((const unsigned*)((const char*)(gbase) + (voff)[_i]), (LAS unsigned*)(lds + (bufoff) + ldsw + _i * 8192), 16, 0, 0); } while (0)
; #define PG8_LDA(dst, b, h) do { _Pragma("unroll") for (int m = 0; m < 4; ++m) _Pragma("unroll") for (int k = 0; k < 2; ++k) dst[m][k] = *(const LAS bf16x8*)(lds + PG8_SA(b, h) + aoff + m * 2048 + k * 1024); } while (0)
; #define PG8_MMA(ai, bj, At, Bt) do { __builtin_amdgcn_s_setprio(1); _Pragma("unroll") for (int m = 0; m < 4; ++m) _Pragma("unroll") for (int n = 0; n < 2; ++n) _Pragma("unroll") for (int k = 0; k < 2; ++k) \
;         acc[ai][bj][m][n] = __builtin_amdgcn_mfma_f32_16x16x32_bf16(Bt[n][k], At[m][k], acc[ai][bj][m][n], 0, 0, 0); __builtin_amdgcn_s_setprio(0); } while (0)
; #define PG8_WAIT_V(n) asm volatile("s_waitcnt vmcnt(" #n ")" ::: "memory")
; #define PG8_WAIT_L(n) asm volatile("s_waitcnt lgkmcnt(" #n ")" ::: "memory")
; #define PG8_BAR __builtin_amdgcn_s_barrier()
; #define PG8_SCHED __builtin_amdgcn_sched_barrier(0)
; template <class Epi, bool ALIGN_EPI>
; __device__ __forceinline__ void gemm_phase(LAS unsigned char* lds, const Gemm g, const StaticOrder& S, const Epi& E, const int wave_s) {
;     ...
;             PG8_LDA(At, 1, 1); PG8_STAGE(PG8_SB(1, 0), b3, voffB); PG8_STAGE(PG8_SB(1, 1), b3 + hstepB, voffB); PG8_STAGE(PG8_SA(1, 0), a3, voffA);
;             PG8_WAIT_V(8); PG8_WAIT_L(0); PG8_BAR; PG8_MMA(1, 0, At, B0); PG8_MMA(1, 1, At, B1); PG8_BAR; PG8_SCHED;
;         }
	s_add_i32 s38, s41, s4
	v_lshl_add_u64 v[24:25], v[182:183], 0, s[64:65]
	s_mov_b32 m0, s38
	ds_read_b128 v[178:181], v213 offset:49152
	ds_read_b128 v[188:191], v213 offset:50176
	ds_read_b128 v[192:195], v213 offset:51200
	ds_read_b128 v[196:199], v213 offset:52224
	ds_read_b128 v[200:203], v213 offset:53248
	ds_read_b128 v[204:207], v213 offset:54272
	ds_read_b128 v[214:217], v213 offset:55296
	ds_read_b128 v[218:221], v213 offset:56320
	global_load_lds_dwordx4 v[24:25], off
	v_lshl_add_u64 v[24:25], v[208:209], 0, s[64:65]
	s_add_i32 m0, s38, 0x2000
	s_add_i32 s38, s45, s4
	global_load_lds_dwordx4 v[24:25], off
	v_lshl_add_u64 v[24:25], v[222:223], 0, s[64:65]
	s_mov_b32 m0, s38
	s_nop 0
	global_load_lds_dwordx4 v[24:25], off
	v_lshl_add_u64 v[24:25], v[224:225], 0, s[64:65]
	s_add_i32 m0, s38, 0x2000
	s_nop 0
	global_load_lds_dwordx4 v[24:25], off
	v_lshl_add_u64 v[24:25], v[226:227], 0, s[64:65]
	s_mov_b32 m0, s25
	s_nop 0
	global_load_lds_dwordx4 v[24:25], off
	v_lshl_add_u64 v[24:25], v[228:229], 0, s[64:65]
	s_mov_b32 m0, s86
	s_nop 0
	global_load_lds_dwordx4 v[24:25], off
	s_waitcnt vmcnt(8)
	s_waitcnt lgkmcnt(0)
	s_barrier
	s_setprio 1
	s_waitcnt lgkmcnt(0)
	v_mfma_f32_16x16x32_bf16 v[112:115], v[96:99], v[178:181], v[112:115]
	v_mfma_f32_16x16x32_bf16 v[30:33], v[104:107], v[178:181], v[30:33]
	v_mfma_f32_16x16x32_bf16 v[108:111], v[96:99], v[192:195], v[108:111]
	v_mfma_f32_16x16x32_bf16 v[24:27], v[104:107], v[192:195], v[26:29]
	v_mfma_f32_16x16x32_bf16 v[88:91], v[96:99], v[200:203], v[88:91]
	v_mfma_f32_16x16x32_bf16 v[16:19], v[104:107], v[200:203], v[16:19]
	v_mfma_f32_16x16x32_bf16 v[78:81], v[96:99], v[214:217], v[78:81]
	v_mfma_f32_16x16x32_bf16 v[8:11], v[104:107], v[214:217], v[8:11]
	v_mfma_f32_16x16x32_bf16 v[112:115], v[100:103], v[188:191], v[112:115]
	v_mfma_f32_16x16x32_bf16 v[30:33], v[140:143], v[188:191], v[30:33]
	v_mfma_f32_16x16x32_bf16 v[108:111], v[100:103], v[196:199], v[108:111]
	v_mfma_f32_16x16x32_bf16 v[26:29], v[140:143], v[196:199], v[24:27]
	v_mfma_f32_16x16x32_bf16 v[88:91], v[100:103], v[204:207], v[88:91]
	v_mfma_f32_16x16x32_bf16 v[16:19], v[140:143], v[204:207], v[16:19]
	v_mfma_f32_16x16x32_bf16 v[80:83], v[100:103], v[218:221], v[78:81]
	v_mfma_f32_16x16x32_bf16 v[8:11], v[140:143], v[218:221], v[8:11]
	s_setprio 0
	s_setprio 1
	v_mfma_f32_16x16x32_bf16 v[92:95], v[152:155], v[178:181], v[92:95]
	v_mfma_f32_16x16x32_bf16 v[20:23], v[170:173], v[178:181], v[20:23]
	v_mfma_f32_16x16x32_bf16 v[84:87], v[152:155], v[192:195], v[84:87]
	v_mfma_f32_16x16x32_bf16 v[12:15], v[170:173], v[192:195], v[12:15]
	v_mfma_f32_16x16x32_bf16 v[74:77], v[152:155], v[200:203], v[74:77]
	v_mfma_f32_16x16x32_bf16 v[4:7], v[170:173], v[200:203], v[4:7]
	v_mfma_f32_16x16x32_bf16 v[70:73], v[152:155], v[214:217], v[70:73]
	v_mfma_f32_16x16x32_bf16 v[0:3], v[170:173], v[214:217], v[0:3]
	v_mfma_f32_16x16x32_bf16 v[92:95], v[156:159], v[188:191], v[92:95]
	v_mfma_f32_16x16x32_bf16 v[22:25], v[174:177], v[188:191], v[20:23]
	v_mfma_f32_16x16x32_bf16 v[84:87], v[156:159], v[196:199], v[84:87]
	v_mfma_f32_16x16x32_bf16 v[12:15], v[174:177], v[196:199], v[12:15]
	v_mfma_f32_16x16x32_bf16 v[74:77], v[156:159], v[204:207], v[74:77]
	v_mfma_f32_16x16x32_bf16 v[4:7], v[174:177], v[204:207], v[4:7]
	v_mfma_f32_16x16x32_bf16 v[70:73], v[156:159], v[218:221], v[70:73]
	v_mfma_f32_16x16x32_bf16 v[0:3], v[174:177], v[218:221], v[0:3]
	s_setprio 0
	s_barrier
	s_add_u32 s43, s43, 0x100
	s_addc_u32 s44, s44, 0
	s_add_u32 s0, s0, 0x100
	s_addc_u32 s1, s1, 0
	s_cmp_ge_i32 s40, s63
	s_mov_b32 s38, s40
	s_cbranch_scc0 .LBB0_180
	s_branch .LBB0_182

; #define PG8_STAGE(bufoff, gbase, voff) do { _Pragma("unroll") for (int _i = 0; _i < 2; ++_i) \
;         __builtin_amdgcn_global_load_lds((const unsigned*)((const char*)(gbase) + (voff)[_i]), (LAS unsigned*)(lds + (bufoff) + ldsw + _i * 8192), 16, 0, 0); } while (0)
; #define PG8_LDA(dst, b, h) do { _Pragma("unroll") for (int m = 0; m < 4; ++m) _Pragma("unroll") for (int k = 0; k < 2; ++k) dst[m][k] = *(const LAS bf16x8*)(lds + PG8_SA(b, h) + aoff + m * 2048 + k * 1024); } while (0)
; #define PG8_LDB(dst, b, h) do { _Pragma("unroll") for (int n = 0; n < 2; ++n) _Pragma("unroll") for (int k = 0; k < 2; ++k) dst[n][k] = *(const LAS bf16x8*)(lds + PG8_SB(b, h) + boff + n * 2048 + k * 1024); } while (0)
; #define PG8_MMA(ai, bj, At, Bt) do { __builtin_amdgcn_s_setprio(1); _Pragma("unroll") for (int m = 0; m < 4; ++m) _Pragma("unroll") for (int n = 0; n < 2; ++n) _Pragma("unroll") for (int k = 0; k < 2; ++k) \
;         acc[ai][bj][m][n] = __builtin_amdgcn_mfma_f32_16x16x32_bf16(Bt[n][k], At[m][k], acc[ai][bj][m][n], 0, 0, 0); __builtin_amdgcn_s_setprio(0); } while (0)
; #define PG8_WAIT_V(n) asm volatile("s_waitcnt vmcnt(" #n ")" ::: "memory")
; #define PG8_WAIT_L(n) asm volatile("s_waitcnt lgkmcnt(" #n ")" ::: "memory")
; #define PG8_BAR __builtin_amdgcn_s_barrier()
; #define PG8_SCHED __builtin_amdgcn_sched_barrier(0)
; template <class Epi, bool ALIGN_EPI>
; __device__ __forceinline__ void gemm_phase(LAS unsigned char* lds, const Gemm g, const StaticOrder& S, const Epi& E, const int wave_s) {
;     ...
;         for (int t = 0; t < nt; t += 2) {
;             const bool last = (t == nt - 2);
;             const char* a1 = cA + (size_t)(t + 1) * kstep;
;             const char* a2 = last ? nA : cA + (size_t)(t + 2) * kstep; const char* b2 = last ? nB : cB + (size_t)(t + 2) * kstep;
;             const char* a3 = a2 + kstep; const char* b3 = b2 + kstep;
;             PG8_LDB(B0, 0, 0); PG8_LDB(B1, 0, 1); PG8_SCHED; PG8_LDA(At, 0, 0); PG8_STAGE(PG8_SA(1, 1), a1 + hstepA, voffA);
;             PG8_WAIT_V(8); PG8_WAIT_L(0); PG8_BAR; PG8_MMA(0, 0, At, B0); PG8_MMA(0, 1, At, B1); PG8_BAR; PG8_SCHED;
;             PG8_LDA(At, 0, 1); PG8_STAGE(PG8_SB(0, 0), b2, voffB); PG8_STAGE(PG8_SB(0, 1), b2 + hstepB, voffB); PG8_STAGE(PG8_SA(0, 0), a2, voffA);
;             PG8_WAIT_V(8); PG8_WAIT_L(0); PG8_BAR; PG8_MMA(1, 0, At, B0); PG8_MMA(1, 1, At, B1); PG8_BAR; PG8_SCHED;
.LBB0_355:
	s_add_i32 s57, s42, 2
	s_add_u32 s58, s40, 0x80
	s_addc_u32 s43, s41, 0
	s_add_i32 s60, 0, 0x10000
	s_cmp_eq_u32 s49, s42
	s_cselect_b32 s43, s1, s43
	s_cselect_b32 s42, s0, s58
	s_cselect_b32 s59, s29, s56
	s_cselect_b32 s58, s28, s55
	s_add_i32 s61, 0, 0x14000
	v_add_u32_e32 v150, s60, v161
	v_add_u32_e32 v158, s61, v161
	ds_read_b128 v[128:131], v150
	ds_read_b128 v[132:135], v150 offset:1024
	ds_read_b128 v[146:149], v150 offset:2048
	ds_read_b128 v[150:153], v150 offset:3072
	ds_read_b128 v[154:157], v158
	ds_read_b128 v[166:169], v158 offset:1024
	ds_read_b128 v[170:173], v158 offset:2048
	ds_read_b128 v[174:177], v158 offset:3072
	s_add_i32 m0, s24, 0xc000
	ds_read_b128 v[178:181], v165
	ds_read_b128 v[188:191], v165 offset:1024
	ds_read_b128 v[192:195], v165 offset:2048
	ds_read_b128 v[196:199], v165 offset:3072
	ds_read_b128 v[200:203], v165 offset:4096
	ds_read_b128 v[204:207], v165 offset:5120
	ds_read_b128 v[208:211], v165 offset:6144
	ds_read_b128 v[212:215], v165 offset:7168
	global_load_lds_dwordx4 v144, s[40:41]
	s_add_i32 m0, s24, 0xe000
	s_nop 0
	global_load_lds_dwordx4 v142, s[40:41]
	s_waitcnt vmcnt(8)
	s_waitcnt lgkmcnt(0)
	s_barrier
	s_setprio 1
	s_waitcnt lgkmcnt(0)
	v_mfma_f32_16x16x32_bf16 v[124:127], v[128:131], v[178:181], v[124:127]
	v_mfma_f32_16x16x32_bf16 v[120:123], v[146:149], v[178:181], v[120:123]
	v_mfma_f32_16x16x32_bf16 v[108:111], v[128:131], v[192:195], v[108:111]
	v_mfma_f32_16x16x32_bf16 v[104:107], v[146:149], v[192:195], v[104:107]
	v_mfma_f32_16x16x32_bf16 v[92:95], v[128:131], v[200:203], v[92:95]
	v_mfma_f32_16x16x32_bf16 v[88:91], v[146:149], v[200:203], v[88:91]
	v_mfma_f32_16x16x32_bf16 v[76:79], v[128:131], v[208:211], v[76:79]
	v_mfma_f32_16x16x32_bf16 v[72:75], v[146:149], v[208:211], v[72:75]
	v_mfma_f32_16x16x32_bf16 v[124:127], v[132:135], v[188:191], v[124:127]
	v_mfma_f32_16x16x32_bf16 v[120:123], v[150:153], v[188:191], v[120:123]
	v_mfma_f32_16x16x32_bf16 v[108:111], v[132:135], v[196:199], v[108:111]
	v_mfma_f32_16x16x32_bf16 v[104:107], v[150:153], v[196:199], v[104:107]
	v_mfma_f32_16x16x32_bf16 v[92:95], v[132:135], v[204:207], v[92:95]
	v_mfma_f32_16x16x32_bf16 v[88:91], v[150:153], v[204:207], v[88:91]
	v_mfma_f32_16x16x32_bf16 v[76:79], v[132:135], v[212:215], v[76:79]
	v_mfma_f32_16x16x32_bf16 v[72:75], v[150:153], v[212:215], v[72:75]
	s_setprio 0
	s_setprio 1
	v_mfma_f32_16x16x32_bf16 v[116:119], v[154:157], v[178:181], v[116:119]
	v_mfma_f32_16x16x32_bf16 v[112:115], v[170:173], v[178:181], v[112:115]
	v_mfma_f32_16x16x32_bf16 v[100:103], v[154:157], v[192:195], v[100:103]
	v_mfma_f32_16x16x32_bf16 v[96:99], v[170:173], v[192:195], v[96:99]
	v_mfma_f32_16x16x32_bf16 v[84:87], v[154:157], v[200:203], v[84:87]
	v_mfma_f32_16x16x32_bf16 v[80:83], v[170:173], v[200:203], v[80:83]
	v_mfma_f32_16x16x32_bf16 v[68:71], v[154:157], v[208:211], v[68:71]
	v_mfma_f32_16x16x32_bf16 v[64:67], v[170:173], v[208:211], v[64:67]
	v_mfma_f32_16x16x32_bf16 v[116:119], v[166:169], v[188:191], v[116:119]
	v_mfma_f32_16x16x32_bf16 v[112:115], v[174:177], v[188:191], v[112:115]
	v_mfma_f32_16x16x32_bf16 v[100:103], v[166:169], v[196:199], v[100:103]
	v_mfma_f32_16x16x32_bf16 v[96:99], v[174:177], v[196:199], v[96:99]
	v_mfma_f32_16x16x32_bf16 v[84:87], v[166:169], v[204:207], v[84:87]
	v_mfma_f32_16x16x32_bf16 v[80:83], v[174:177], v[204:207], v[80:83]
	v_mfma_f32_16x16x32_bf16 v[68:71], v[166:169], v[212:215], v[68:71]
	v_mfma_f32_16x16x32_bf16 v[64:67], v[174:177], v[212:215], v[64:67]
	s_setprio 0
	s_barrier
	s_add_i32 s60, s60, s4
	v_lshl_add_u64 v[158:159], s[58:59], 0, v[184:185]
	s_mov_b32 m0, s60
	ds_read_b128 v[178:181], v165 offset:16384
	ds_read_b128 v[188:191], v165 offset:17408
	ds_read_b128 v[192:195], v165 offset:18432
	ds_read_b128 v[196:199], v165 offset:19456
	ds_read_b128 v[200:203], v165 offset:20480
	ds_read_b128 v[204:207], v165 offset:21504
	ds_read_b128 v[208:211], v165 offset:22528
	ds_read_b128 v[212:215], v165 offset:23552
	global_load_lds_dwordx4 v[158:159], off
	s_add_i32 m0, s60, 0x2000
	v_lshl_add_u64 v[182:183], s[58:59], 0, v[136:137]
	s_add_u32 s58, s58, s10
	s_addc_u32 s59, s59, s11
	s_add_i32 s60, s61, s4
	global_load_lds_dwordx4 v[182:183], off
	v_lshl_add_u64 v[216:217], s[58:59], 0, v[184:185]
	s_mov_b32 m0, s60
	v_lshl_add_u64 v[218:219], s[58:59], 0, v[136:137]
	global_load_lds_dwordx4 v[216:217], off
	s_add_i32 m0, s60, 0x2000
	v_lshl_add_u64 v[220:221], s[42:43], 0, v[140:141]
	global_load_lds_dwordx4 v[218:219], off
	s_mov_b32 m0, s24
	v_lshl_add_u64 v[222:223], s[42:43], 0, v[138:139]
	global_load_lds_dwordx4 v[220:221], off
	s_mov_b32 m0, s25
	s_nop 0
	global_load_lds_dwordx4 v[222:223], off
	s_waitcnt vmcnt(8)
	s_waitcnt lgkmcnt(0)
	s_barrier
; #define PG8_STAGE(bufoff, gbase, voff) do { _Pragma("unroll") for (int _i = 0; _i < 2; ++_i) \
;         __builtin_amdgcn_global_load_lds((const unsigned*)((const char*)(gbase) + (voff)[_i]), (LAS unsigned*)(lds + (bufoff) + ldsw + _i * 8192), 16, 0, 0); } while (0)
; #define PG8_LDA(dst, b, h) do { _Pragma("unroll") for (int m = 0; m < 4; ++m) _Pragma("unroll") for (int k = 0; k < 2; ++k) dst[m][k] = *(const LAS bf16x8*)(lds + PG8_SA(b, h) + aoff + m * 2048 + k * 1024); } while (0)
; #define PG8_LDB(dst, b, h) do { _Pragma("unroll") for (int n = 0; n < 2; ++n) _Pragma("unroll") for (int k = 0; k < 2; ++k) dst[n][k] = *(const LAS bf16x8*)(lds + PG8_SB(b, h) + boff + n * 2048 + k * 1024); } while (0)
; #define PG8_MMA(ai, bj, At, Bt) do { __builtin_amdgcn_s_setprio(1); _Pragma("unroll") for (int m = 0; m < 4; ++m) _Pragma("unroll") for (int n = 0; n < 2; ++n) _Pragma("unroll") for (int k = 0; k < 2; ++k) \
;         acc[ai][bj][m][n] = __builtin_amdgcn_mfma_f32_16x16x32_bf16(Bt[n][k], At[m][k], acc[ai][bj][m][n], 0, 0, 0); __builtin_amdgcn_s_setprio(0); } while (0)
; #define PG8_WAIT_V(n) asm volatile("s_waitcnt vmcnt(" #n ")" ::: "memory")
; #define PG8_WAIT_L(n) asm volatile("s_waitcnt lgkmcnt(" #n ")" ::: "memory")
; #define PG8_BAR __builtin_amdgcn_s_barrier()
; #define PG8_SCHED __builtin_amdgcn_sched_barrier(0)
; template <class Epi, bool ALIGN_EPI>
; __device__ __forceinline__ void gemm_phase(LAS unsigned char* lds, const Gemm g, const StaticOrder& S, const Epi& E, const int wave_s) {
;     ...
;             PG8_WAIT_V(8); PG8_WAIT_L(0); PG8_BAR; PG8_MMA(1, 0, At, B0); PG8_MMA(1, 1, At, B1); PG8_BAR; PG8_SCHED;
;             PG8_LDB(B0, 1, 0); PG8_LDB(B1, 1, 1); PG8_SCHED; PG8_LDA(At, 1, 0); PG8_STAGE(PG8_SA(0, 1), a2 + hstepA, voffA);
;             PG8_WAIT_V(8); PG8_WAIT_L(0); PG8_BAR; PG8_MMA(0, 0, At, B0); PG8_MMA(0, 1, At, B1); PG8_BAR; PG8_SCHED;
	s_setprio 1
	s_waitcnt lgkmcnt(0)
	v_mfma_f32_16x16x32_bf16 v[60:63], v[128:131], v[178:181], v[60:63]
	v_mfma_f32_16x16x32_bf16 v[56:59], v[146:149], v[178:181], v[56:59]
	v_mfma_f32_16x16x32_bf16 v[44:47], v[128:131], v[192:195], v[44:47]
	v_mfma_f32_16x16x32_bf16 v[40:43], v[146:149], v[192:195], v[40:43]
	v_mfma_f32_16x16x32_bf16 v[28:31], v[128:131], v[200:203], v[28:31]
	v_mfma_f32_16x16x32_bf16 v[24:27], v[146:149], v[200:203], v[24:27]
	v_mfma_f32_16x16x32_bf16 v[12:15], v[128:131], v[208:211], v[12:15]
	v_mfma_f32_16x16x32_bf16 v[8:11], v[146:149], v[208:211], v[8:11]
	v_mfma_f32_16x16x32_bf16 v[60:63], v[132:135], v[188:191], v[60:63]
	v_mfma_f32_16x16x32_bf16 v[56:59], v[150:153], v[188:191], v[56:59]
	v_mfma_f32_16x16x32_bf16 v[44:47], v[132:135], v[196:199], v[44:47]
	v_mfma_f32_16x16x32_bf16 v[40:43], v[150:153], v[196:199], v[40:43]
	v_mfma_f32_16x16x32_bf16 v[28:31], v[132:135], v[204:207], v[28:31]
	v_mfma_f32_16x16x32_bf16 v[24:27], v[150:153], v[204:207], v[24:27]
	v_mfma_f32_16x16x32_bf16 v[12:15], v[132:135], v[212:215], v[12:15]
	v_mfma_f32_16x16x32_bf16 v[8:11], v[150:153], v[212:215], v[8:11]
	s_setprio 0
	s_setprio 1
	v_mfma_f32_16x16x32_bf16 v[52:55], v[154:157], v[178:181], v[52:55]
	v_mfma_f32_16x16x32_bf16 v[48:51], v[170:173], v[178:181], v[48:51]
	v_mfma_f32_16x16x32_bf16 v[36:39], v[154:157], v[192:195], v[36:39]
	v_mfma_f32_16x16x32_bf16 v[32:35], v[170:173], v[192:195], v[32:35]
	v_mfma_f32_16x16x32_bf16 v[20:23], v[154:157], v[200:203], v[20:23]
	v_mfma_f32_16x16x32_bf16 v[16:19], v[170:173], v[200:203], v[16:19]
	v_mfma_f32_16x16x32_bf16 v[4:7], v[154:157], v[208:211], v[4:7]
	v_mfma_f32_16x16x32_bf16 v[0:3], v[170:173], v[208:211], v[0:3]
	v_mfma_f32_16x16x32_bf16 v[52:55], v[166:169], v[188:191], v[52:55]
	v_mfma_f32_16x16x32_bf16 v[48:51], v[174:177], v[188:191], v[48:51]
	v_mfma_f32_16x16x32_bf16 v[36:39], v[166:169], v[196:199], v[36:39]
	v_mfma_f32_16x16x32_bf16 v[32:35], v[174:177], v[196:199], v[32:35]
	v_mfma_f32_16x16x32_bf16 v[20:23], v[166:169], v[204:207], v[20:23]
	v_mfma_f32_16x16x32_bf16 v[16:19], v[174:177], v[204:207], v[16:19]
	v_mfma_f32_16x16x32_bf16 v[4:7], v[166:169], v[212:215], v[4:7]
	v_mfma_f32_16x16x32_bf16 v[0:3], v[174:177], v[212:215], v[0:3]
	s_setprio 0
	s_barrier
	s_add_i32 s58, 0, 0x18000
	s_add_i32 s59, 0, 0x1c000
	v_add_u32_e32 v150, s58, v161
	v_add_u32_e32 v174, s59, v161
	ds_read_b128 v[128:131], v150
	ds_read_b128 v[132:135], v150 offset:1024
	ds_read_b128 v[146:149], v150 offset:2048
	ds_read_b128 v[150:153], v150 offset:3072
	ds_read_b128 v[154:157], v174
	ds_read_b128 v[166:169], v174 offset:1024
	ds_read_b128 v[170:173], v174 offset:2048
	ds_read_b128 v[174:177], v174 offset:3072
	s_add_u32 s42, s42, s8
	s_addc_u32 s43, s43, s9
	s_mov_b32 m0, s44
	ds_read_b128 v[178:181], v165 offset:32768
	ds_read_b128 v[188:191], v165 offset:33792
	ds_read_b128 v[192:195], v165 offset:34816
	ds_read_b128 v[196:199], v165 offset:35840
	ds_read_b128 v[200:203], v165 offset:36864
	ds_read_b128 v[204:207], v165 offset:37888
	ds_read_b128 v[208:211], v165 offset:38912
	ds_read_b128 v[212:215], v165 offset:39936
	global_load_lds_dwordx4 v140, s[42:43]
	v_lshl_add_u64 v[224:225], s[42:43], 0, v[138:139]
	s_mov_b32 m0, s45
	s_nop 0
	global_load_lds_dwordx4 v[224:225], off
	s_waitcnt vmcnt(8)
	s_waitcnt lgkmcnt(0)
	s_barrier
	s_setprio 1
	s_waitcnt lgkmcnt(0)
	v_mfma_f32_16x16x32_bf16 v[124:127], v[128:131], v[178:181], v[124:127]
	v_mfma_f32_16x16x32_bf16 v[120:123], v[146:149], v[178:181], v[120:123]
	v_mfma_f32_16x16x32_bf16 v[108:111], v[128:131], v[192:195], v[108:111]
	v_mfma_f32_16x16x32_bf16 v[104:107], v[146:149], v[192:195], v[104:107]
	v_mfma_f32_16x16x32_bf16 v[92:95], v[128:131], v[200:203], v[92:95]
	v_mfma_f32_16x16x32_bf16 v[88:91], v[146:149], v[200:203], v[88:91]
	v_mfma_f32_16x16x32_bf16 v[76:79], v[128:131], v[208:211], v[76:79]
	v_mfma_f32_16x16x32_bf16 v[72:75], v[146:149], v[208:211], v[72:75]
	v_mfma_f32_16x16x32_bf16 v[124:127], v[132:135], v[188:191], v[124:127]
	v_mfma_f32_16x16x32_bf16 v[120:123], v[150:153], v[188:191], v[120:123]
	v_mfma_f32_16x16x32_bf16 v[108:111], v[132:135], v[196:199], v[108:111]
	v_mfma_f32_16x16x32_bf16 v[104:107], v[150:153], v[196:199], v[104:107]
	v_mfma_f32_16x16x32_bf16 v[92:95], v[132:135], v[204:207], v[92:95]
	v_mfma_f32_16x16x32_bf16 v[88:91], v[150:153], v[204:207], v[88:91]
	v_mfma_f32_16x16x32_bf16 v[76:79], v[132:135], v[212:215], v[76:79]
	v_mfma_f32_16x16x32_bf16 v[72:75], v[150:153], v[212:215], v[72:75]
	s_setprio 0
	s_setprio 1
	v_mfma_f32_16x16x32_bf16 v[116:119], v[154:157], v[178:181], v[116:119]
	v_mfma_f32_16x16x32_bf16 v[112:115], v[170:173], v[178:181], v[112:115]
	v_mfma_f32_16x16x32_bf16 v[100:103], v[154:157], v[192:195], v[100:103]
	v_mfma_f32_16x16x32_bf16 v[96:99], v[170:173], v[192:195], v[96:99]
	v_mfma_f32_16x16x32_bf16 v[84:87], v[154:157], v[200:203], v[84:87]
	v_mfma_f32_16x16x32_bf16 v[80:83], v[170:173], v[200:203], v[80:83]
	v_mfma_f32_16x16x32_bf16 v[68:71], v[154:157], v[208:211], v[68:71]
	v_mfma_f32_16x16x32_bf16 v[64:67], v[170:173], v[208:211], v[64:67]
	v_mfma_f32_16x16x32_bf16 v[116:119], v[166:169], v[188:191], v[116:119]
	v_mfma_f32_16x16x32_bf16 v[112:115], v[174:177], v[188:191], v[112:115]
	v_mfma_f32_16x16x32_bf16 v[100:103], v[166:169], v[196:199], v[100:103]
	v_mfma_f32_16x16x32_bf16 v[96:99], v[174:177], v[196:199], v[96:99]
	v_mfma_f32_16x16x32_bf16 v[84:87], v[166:169], v[204:207], v[84:87]
	v_mfma_f32_16x16x32_bf16 v[80:83], v[174:177], v[204:207], v[80:83]
	v_mfma_f32_16x16x32_bf16 v[68:71], v[166:169], v[212:215], v[68:71]
	v_mfma_f32_16x16x32_bf16 v[64:67], v[174:177], v[212:215], v[64:67]
	s_setprio 0
	s_barrier
; #define PG8_STAGE(bufoff, gbase, voff) do { _Pragma("unroll") for (int _i = 0; _i < 2; ++_i) \
;         __builtin_amdgcn_global_load_lds((const unsigned*)((const char*)(gbase) + (voff)[_i]), (LAS unsigned*)(lds + (bufoff) + ldsw + _i * 8192), 16, 0, 0); } while (0)
; #define PG8_LDA(dst, b, h) do { _Pragma("unroll") for (int m = 0; m < 4; ++m) _Pragma("unroll") for (int k = 0; k < 2; ++k) dst[m][k] = *(const LAS bf16x8*)(lds + PG8_SA(b, h) + aoff + m * 2048 + k * 1024); } while (0)
; #define PG8_MMA(ai, bj, At, Bt) do { __builtin_amdgcn_s_setprio(1); _Pragma("unroll") for (int m = 0; m < 4; ++m) _Pragma("unroll") for (int n = 0; n < 2; ++n) _Pragma("unroll") for (int k = 0; k < 2; ++k) \
;         acc[ai][bj][m][n] = __builtin_amdgcn_mfma_f32_16x16x32_bf16(Bt[n][k], At[m][k], acc[ai][bj][m][n], 0, 0, 0); __builtin_amdgcn_s_setprio(0); } while (0)
; #define PG8_WAIT_V(n) asm volatile("s_waitcnt vmcnt(" #n ")" ::: "memory")
; #define PG8_WAIT_L(n) asm volatile("s_waitcnt lgkmcnt(" #n ")" ::: "memory")
; #define PG8_BAR __builtin_amdgcn_s_barrier()
; #define PG8_SCHED __builtin_amdgcn_sched_barrier(0)
; template <class Epi, bool ALIGN_EPI>
; __device__ __forceinline__ void gemm_phase(LAS unsigned char* lds, const Gemm g, const StaticOrder& S, const Epi& E, const int wave_s) {
;     ...
;             PG8_LDA(At, 1, 1); PG8_STAGE(PG8_SB(1, 0), b3, voffB); PG8_STAGE(PG8_SB(1, 1), b3 + hstepB, voffB); PG8_STAGE(PG8_SA(1, 0), a3, voffA);
;             PG8_WAIT_V(8); PG8_WAIT_L(0); PG8_BAR; PG8_MMA(1, 0, At, B0); PG8_MMA(1, 1, At, B1); PG8_BAR; PG8_SCHED;
;         }
	s_add_i32 s42, s58, s4
	v_lshl_add_u64 v[158:159], v[158:159], 0, s[64:65]
	s_mov_b32 m0, s42
	ds_read_b128 v[178:181], v165 offset:49152
	ds_read_b128 v[188:191], v165 offset:50176
	ds_read_b128 v[192:195], v165 offset:51200
	ds_read_b128 v[196:199], v165 offset:52224
	ds_read_b128 v[200:203], v165 offset:53248
	ds_read_b128 v[204:207], v165 offset:54272
	ds_read_b128 v[208:211], v165 offset:55296
	ds_read_b128 v[212:215], v165 offset:56320
	global_load_lds_dwordx4 v[158:159], off
	v_lshl_add_u64 v[158:159], v[182:183], 0, s[64:65]
	s_add_i32 m0, s42, 0x2000
	s_add_i32 s42, s59, s4
	global_load_lds_dwordx4 v[158:159], off
	v_lshl_add_u64 v[158:159], v[216:217], 0, s[64:65]
	s_mov_b32 m0, s42
	s_nop 0
	global_load_lds_dwordx4 v[158:159], off
	v_lshl_add_u64 v[158:159], v[218:219], 0, s[64:65]
	s_add_i32 m0, s42, 0x2000
	s_nop 0
	global_load_lds_dwordx4 v[158:159], off
	v_lshl_add_u64 v[158:159], v[220:221], 0, s[64:65]
	s_mov_b32 m0, s46
	s_nop 0
	global_load_lds_dwordx4 v[158:159], off
	v_lshl_add_u64 v[158:159], v[222:223], 0, s[64:65]
	s_mov_b32 m0, s47
	s_nop 0
	global_load_lds_dwordx4 v[158:159], off
	s_waitcnt vmcnt(8)
	s_waitcnt lgkmcnt(0)
	s_barrier
	s_setprio 1
	s_waitcnt lgkmcnt(0)
	v_mfma_f32_16x16x32_bf16 v[60:63], v[128:131], v[178:181], v[60:63]
	v_mfma_f32_16x16x32_bf16 v[56:59], v[146:149], v[178:181], v[56:59]
	v_mfma_f32_16x16x32_bf16 v[44:47], v[128:131], v[192:195], v[44:47]
	v_mfma_f32_16x16x32_bf16 v[40:43], v[146:149], v[192:195], v[40:43]
	v_mfma_f32_16x16x32_bf16 v[28:31], v[128:131], v[200:203], v[28:31]
	v_mfma_f32_16x16x32_bf16 v[24:27], v[146:149], v[200:203], v[24:27]
	v_mfma_f32_16x16x32_bf16 v[12:15], v[128:131], v[208:211], v[12:15]
	v_mfma_f32_16x16x32_bf16 v[8:11], v[146:149], v[208:211], v[8:11]
	v_mfma_f32_16x16x32_bf16 v[60:63], v[132:135], v[188:191], v[60:63]
	v_mfma_f32_16x16x32_bf16 v[56:59], v[150:153], v[188:191], v[56:59]
	v_mfma_f32_16x16x32_bf16 v[44:47], v[132:135], v[196:199], v[44:47]
	v_mfma_f32_16x16x32_bf16 v[40:43], v[150:153], v[196:199], v[40:43]
	v_mfma_f32_16x16x32_bf16 v[28:31], v[132:135], v[204:207], v[28:31]
	v_mfma_f32_16x16x32_bf16 v[24:27], v[150:153], v[204:207], v[24:27]
	v_mfma_f32_16x16x32_bf16 v[12:15], v[132:135], v[212:215], v[12:15]
	v_mfma_f32_16x16x32_bf16 v[8:11], v[150:153], v[212:215], v[8:11]
	s_setprio 0
	s_setprio 1
	v_mfma_f32_16x16x32_bf16 v[52:55], v[154:157], v[178:181], v[52:55]
	v_mfma_f32_16x16x32_bf16 v[48:51], v[170:173], v[178:181], v[48:51]
	v_mfma_f32_16x16x32_bf16 v[36:39], v[154:157], v[192:195], v[36:39]
	v_mfma_f32_16x16x32_bf16 v[32:35], v[170:173], v[192:195], v[32:35]
	v_mfma_f32_16x16x32_bf16 v[20:23], v[154:157], v[200:203], v[20:23]
	v_mfma_f32_16x16x32_bf16 v[16:19], v[170:173], v[200:203], v[16:19]
	v_mfma_f32_16x16x32_bf16 v[4:7], v[154:157], v[208:211], v[4:7]
	v_mfma_f32_16x16x32_bf16 v[0:3], v[170:173], v[208:211], v[0:3]
	v_mfma_f32_16x16x32_bf16 v[52:55], v[166:169], v[188:191], v[52:55]
	v_mfma_f32_16x16x32_bf16 v[48:51], v[174:177], v[188:191], v[48:51]
	v_mfma_f32_16x16x32_bf16 v[36:39], v[166:169], v[196:199], v[36:39]
	v_mfma_f32_16x16x32_bf16 v[32:35], v[174:177], v[196:199], v[32:35]
	v_mfma_f32_16x16x32_bf16 v[20:23], v[166:169], v[204:207], v[20:23]
	v_mfma_f32_16x16x32_bf16 v[16:19], v[174:177], v[204:207], v[16:19]
	v_mfma_f32_16x16x32_bf16 v[4:7], v[166:169], v[212:215], v[4:7]
	v_mfma_f32_16x16x32_bf16 v[0:3], v[174:177], v[212:215], v[0:3]
	s_setprio 0
	s_barrier
	s_add_u32 s55, s55, 0x100
	s_addc_u32 s56, s56, 0
	s_add_u32 s40, s40, 0x100
	s_addc_u32 s41, s41, 0
	s_cmp_ge_i32 s57, s48
	s_mov_b32 s42, s57
	s_cbranch_scc0 .LBB0_355
	v_readlane_b32 s58, v252, 12
	s_and_b64 vcc, exec, s[20:21]
	s_cbranch_vccnz .LBB0_360
	s_branch .LBB0_361

; #define PG8_STAGE(bufoff, gbase, voff) do { _Pragma("unroll") for (int _i = 0; _i < 2; ++_i) \
;         __builtin_amdgcn_global_load_lds((const unsigned*)((const char*)(gbase) + (voff)[_i]), (LAS unsigned*)(lds + (bufoff) + ldsw + _i * 8192), 16, 0, 0); } while (0)
; #define PG8_LDA(dst, b, h) do { _Pragma("unroll") for (int m = 0; m < 4; ++m) _Pragma("unroll") for (int k = 0; k < 2; ++k) dst[m][k] = *(const LAS bf16x8*)(lds + PG8_SA(b, h) + aoff + m * 2048 + k * 1024); } while (0)
; #define PG8_LDB(dst, b, h) do { _Pragma("unroll") for (int n = 0; n < 2; ++n) _Pragma("unroll") for (int k = 0; k < 2; ++k) dst[n][k] = *(const LAS bf16x8*)(lds + PG8_SB(b, h) + boff + n * 2048 + k * 1024); } while (0)
; #define PG8_MMA(ai, bj, At, Bt) do { __builtin_amdgcn_s_setprio(1); _Pragma("unroll") for (int m = 0; m < 4; ++m) _Pragma("unroll") for (int n = 0; n < 2; ++n) _Pragma("unroll") for (int k = 0; k < 2; ++k) \
;         acc[ai][bj][m][n] = __builtin_amdgcn_mfma_f32_16x16x32_bf16(Bt[n][k], At[m][k], acc[ai][bj][m][n], 0, 0, 0); __builtin_amdgcn_s_setprio(0); } while (0)
; #define PG8_WAIT_V(n) asm volatile("s_waitcnt vmcnt(" #n ")" ::: "memory")
; #define PG8_WAIT_L(n) asm volatile("s_waitcnt lgkmcnt(" #n ")" ::: "memory")
; #define PG8_BAR __builtin_amdgcn_s_barrier()
; #define PG8_SCHED __builtin_amdgcn_sched_barrier(0)
; template <class Epi, bool ALIGN_EPI>
; __device__ __forceinline__ void gemm_phase(LAS unsigned char* lds, const Gemm g, const StaticOrder& S, const Epi& E, const int wave_s) {
;     ...
;         for (int t = 0; t < nt; t += 2) {
;             const bool last = (t == nt - 2);
;             const char* a1 = cA + (size_t)(t + 1) * kstep;
;             const char* a2 = last ? nA : cA + (size_t)(t + 2) * kstep; const char* b2 = last ? nB : cB + (size_t)(t + 2) * kstep;
;             const char* a3 = a2 + kstep; const char* b3 = b2 + kstep;
;             PG8_LDB(B0, 0, 0); PG8_LDB(B1, 0, 1); PG8_SCHED; PG8_LDA(At, 0, 0); PG8_STAGE(PG8_SA(1, 1), a1 + hstepA, voffA);
;             PG8_WAIT_V(8); PG8_WAIT_L(0); PG8_BAR; PG8_MMA(0, 0, At, B0); PG8_MMA(0, 1, At, B1); PG8_BAR; PG8_SCHED;
;             PG8_LDA(At, 0, 1); PG8_STAGE(PG8_SB(0, 0), b2, voffB); PG8_STAGE(PG8_SB(0, 1), b2 + hstepB, voffB); PG8_STAGE(PG8_SA(0, 0), a2, voffA);
;             PG8_WAIT_V(8); PG8_WAIT_L(0); PG8_BAR; PG8_MMA(1, 0, At, B0); PG8_MMA(1, 1, At, B1); PG8_BAR; PG8_SCHED;
.LBB0_540:
	s_add_i32 s69, s50, 2
	s_add_u32 s70, s38, 0x80
	s_addc_u32 s51, s39, 0
	s_add_i32 s72, 0, 0x10000
	s_cmp_eq_u32 s58, s50
	s_cselect_b32 s51, s1, s51
	s_cselect_b32 s50, s0, s70
	v_add_u32_e32 v155, s72, v151
	s_cselect_b32 s71, s49, s68
	s_cselect_b32 s70, s48, s67
	s_add_i32 s73, 0, 0x14000
	ds_read_b128 v[138:141], v155
	ds_read_b128 v[142:145], v155 offset:1024
	ds_read_b128 v[146:149], v155 offset:2048
	ds_read_b128 v[156:159], v155 offset:3072
	v_add_u32_e32 v155, s73, v151
	ds_read_b128 v[160:163], v155
	ds_read_b128 v[164:167], v155 offset:1024
	ds_read_b128 v[168:171], v155 offset:2048
	ds_read_b128 v[172:175], v155 offset:3072
	s_add_i32 m0, s24, 0xc000
	ds_read_b128 v[176:179], v154
	ds_read_b128 v[180:183], v154 offset:1024
	ds_read_b128 v[192:195], v154 offset:2048
	ds_read_b128 v[196:199], v154 offset:3072
	ds_read_b128 v[200:203], v154 offset:4096
	ds_read_b128 v[204:207], v154 offset:5120
	ds_read_b128 v[210:213], v154 offset:6144
	ds_read_b128 v[214:217], v154 offset:7168
	global_load_lds_dwordx4 v136, s[38:39]
	s_add_i32 m0, s24, 0xe000
	s_nop 0
	global_load_lds_dwordx4 v134, s[38:39]
	s_waitcnt vmcnt(8)
	s_waitcnt lgkmcnt(0)
	s_barrier
	s_setprio 1
	s_waitcnt lgkmcnt(0)
	v_mfma_f32_16x16x32_bf16 v[124:127], v[138:141], v[176:179], v[124:127]
	v_mfma_f32_16x16x32_bf16 v[120:123], v[146:149], v[176:179], v[120:123]
	v_mfma_f32_16x16x32_bf16 v[116:119], v[138:141], v[192:195], v[116:119]
	v_mfma_f32_16x16x32_bf16 v[112:115], v[146:149], v[192:195], v[112:115]
	v_mfma_f32_16x16x32_bf16 v[108:111], v[138:141], v[200:203], v[108:111]
	v_mfma_f32_16x16x32_bf16 v[104:107], v[146:149], v[200:203], v[104:107]
	v_mfma_f32_16x16x32_bf16 v[100:103], v[138:141], v[210:213], v[100:103]
	v_mfma_f32_16x16x32_bf16 v[96:99], v[146:149], v[210:213], v[96:99]
	v_mfma_f32_16x16x32_bf16 v[124:127], v[142:145], v[180:183], v[124:127]
	v_mfma_f32_16x16x32_bf16 v[120:123], v[156:159], v[180:183], v[120:123]
	v_mfma_f32_16x16x32_bf16 v[116:119], v[142:145], v[196:199], v[116:119]
	v_mfma_f32_16x16x32_bf16 v[112:115], v[156:159], v[196:199], v[112:115]
	v_mfma_f32_16x16x32_bf16 v[108:111], v[142:145], v[204:207], v[108:111]
	v_mfma_f32_16x16x32_bf16 v[104:107], v[156:159], v[204:207], v[104:107]
	v_mfma_f32_16x16x32_bf16 v[100:103], v[142:145], v[214:217], v[100:103]
	v_mfma_f32_16x16x32_bf16 v[96:99], v[156:159], v[214:217], v[96:99]
	s_setprio 0
	s_setprio 1
	v_mfma_f32_16x16x32_bf16 v[60:63], v[160:163], v[176:179], v[60:63]
	v_mfma_f32_16x16x32_bf16 v[56:59], v[168:171], v[176:179], v[56:59]
	v_mfma_f32_16x16x32_bf16 v[52:55], v[160:163], v[192:195], v[52:55]
	v_mfma_f32_16x16x32_bf16 v[48:51], v[168:171], v[192:195], v[48:51]
	v_mfma_f32_16x16x32_bf16 v[44:47], v[160:163], v[200:203], v[44:47]
	v_mfma_f32_16x16x32_bf16 v[40:43], v[168:171], v[200:203], v[40:43]
	v_mfma_f32_16x16x32_bf16 v[36:39], v[160:163], v[210:213], v[36:39]
	v_mfma_f32_16x16x32_bf16 v[32:35], v[168:171], v[210:213], v[32:35]
	v_mfma_f32_16x16x32_bf16 v[60:63], v[164:167], v[180:183], v[60:63]
	v_mfma_f32_16x16x32_bf16 v[56:59], v[172:175], v[180:183], v[56:59]
	v_mfma_f32_16x16x32_bf16 v[52:55], v[164:167], v[196:199], v[52:55]
	v_mfma_f32_16x16x32_bf16 v[48:51], v[172:175], v[196:199], v[48:51]
	v_mfma_f32_16x16x32_bf16 v[44:47], v[164:167], v[204:207], v[44:47]
	v_mfma_f32_16x16x32_bf16 v[40:43], v[172:175], v[204:207], v[40:43]
	v_mfma_f32_16x16x32_bf16 v[36:39], v[164:167], v[214:217], v[36:39]
	v_mfma_f32_16x16x32_bf16 v[32:35], v[172:175], v[214:217], v[32:35]
	s_setprio 0
	s_barrier
	s_add_i32 s72, s72, s4
	v_lshl_add_u64 v[188:189], s[70:71], 0, v[184:185]
	s_mov_b32 m0, s72
	ds_read_b128 v[176:179], v154 offset:16384
	ds_read_b128 v[180:183], v154 offset:17408
	ds_read_b128 v[192:195], v154 offset:18432
	ds_read_b128 v[196:199], v154 offset:19456
	ds_read_b128 v[200:203], v154 offset:20480
	ds_read_b128 v[204:207], v154 offset:21504
	ds_read_b128 v[210:213], v154 offset:22528
	ds_read_b128 v[214:217], v154 offset:23552
	global_load_lds_dwordx4 v[188:189], off
	s_add_i32 m0, s72, 0x2000
	v_lshl_add_u64 v[190:191], s[70:71], 0, v[128:129]
	s_add_u32 s70, s70, s8
	s_addc_u32 s71, s71, s9
	s_add_i32 s72, s73, s4
	global_load_lds_dwordx4 v[190:191], off
	v_lshl_add_u64 v[208:209], s[70:71], 0, v[184:185]
	s_mov_b32 m0, s72
	v_lshl_add_u64 v[218:219], s[70:71], 0, v[128:129]
	global_load_lds_dwordx4 v[208:209], off
	s_add_i32 m0, s72, 0x2000
	v_lshl_add_u64 v[220:221], s[50:51], 0, v[132:133]
	global_load_lds_dwordx4 v[218:219], off
	s_mov_b32 m0, s24
	v_lshl_add_u64 v[222:223], s[50:51], 0, v[130:131]
	global_load_lds_dwordx4 v[220:221], off
	s_mov_b32 m0, s25
	s_nop 0
	global_load_lds_dwordx4 v[222:223], off
	s_waitcnt vmcnt(8)
	s_waitcnt lgkmcnt(0)
	s_barrier
; #define PG8_STAGE(bufoff, gbase, voff) do { _Pragma("unroll") for (int _i = 0; _i < 2; ++_i) \
;         __builtin_amdgcn_global_load_lds((const unsigned*)((const char*)(gbase) + (voff)[_i]), (LAS unsigned*)(lds + (bufoff) + ldsw + _i * 8192), 16, 0, 0); } while (0)
; #define PG8_LDA(dst, b, h) do { _Pragma("unroll") for (int m = 0; m < 4; ++m) _Pragma("unroll") for (int k = 0; k < 2; ++k) dst[m][k] = *(const LAS bf16x8*)(lds + PG8_SA(b, h) + aoff + m * 2048 + k * 1024); } while (0)
; #define PG8_LDB(dst, b, h) do { _Pragma("unroll") for (int n = 0; n < 2; ++n) _Pragma("unroll") for (int k = 0; k < 2; ++k) dst[n][k] = *(const LAS bf16x8*)(lds + PG8_SB(b, h) + boff + n * 2048 + k * 1024); } while (0)
; #define PG8_MMA(ai, bj, At, Bt) do { __builtin_amdgcn_s_setprio(1); _Pragma("unroll") for (int m = 0; m < 4; ++m) _Pragma("unroll") for (int n = 0; n < 2; ++n) _Pragma("unroll") for (int k = 0; k < 2; ++k) \
;         acc[ai][bj][m][n] = __builtin_amdgcn_mfma_f32_16x16x32_bf16(Bt[n][k], At[m][k], acc[ai][bj][m][n], 0, 0, 0); __builtin_amdgcn_s_setprio(0); } while (0)
; #define PG8_WAIT_V(n) asm volatile("s_waitcnt vmcnt(" #n ")" ::: "memory")
; #define PG8_WAIT_L(n) asm volatile("s_waitcnt lgkmcnt(" #n ")" ::: "memory")
; #define PG8_BAR __builtin_amdgcn_s_barrier()
; #define PG8_SCHED __builtin_amdgcn_sched_barrier(0)
; template <class Epi, bool ALIGN_EPI>
; __device__ __forceinline__ void gemm_phase(LAS unsigned char* lds, const Gemm g, const StaticOrder& S, const Epi& E, const int wave_s) {
;     ...
;             PG8_WAIT_V(8); PG8_WAIT_L(0); PG8_BAR; PG8_MMA(1, 0, At, B0); PG8_MMA(1, 1, At, B1); PG8_BAR; PG8_SCHED;
;             PG8_LDB(B0, 1, 0); PG8_LDB(B1, 1, 1); PG8_SCHED; PG8_LDA(At, 1, 0); PG8_STAGE(PG8_SA(0, 1), a2 + hstepA, voffA);
;             PG8_WAIT_V(8); PG8_WAIT_L(0); PG8_BAR; PG8_MMA(0, 0, At, B0); PG8_MMA(0, 1, At, B1); PG8_BAR; PG8_SCHED;
	s_setprio 1
	s_waitcnt lgkmcnt(0)
	v_mfma_f32_16x16x32_bf16 v[92:95], v[138:141], v[176:179], v[92:95]
	v_mfma_f32_16x16x32_bf16 v[88:91], v[146:149], v[176:179], v[88:91]
	v_mfma_f32_16x16x32_bf16 v[84:87], v[138:141], v[192:195], v[84:87]
	v_mfma_f32_16x16x32_bf16 v[80:83], v[146:149], v[192:195], v[80:83]
	v_mfma_f32_16x16x32_bf16 v[76:79], v[138:141], v[200:203], v[76:79]
	v_mfma_f32_16x16x32_bf16 v[72:75], v[146:149], v[200:203], v[72:75]
	v_mfma_f32_16x16x32_bf16 v[68:71], v[138:141], v[210:213], v[68:71]
	v_mfma_f32_16x16x32_bf16 v[64:67], v[146:149], v[210:213], v[64:67]
	v_mfma_f32_16x16x32_bf16 v[92:95], v[142:145], v[180:183], v[92:95]
	v_mfma_f32_16x16x32_bf16 v[88:91], v[156:159], v[180:183], v[88:91]
	v_mfma_f32_16x16x32_bf16 v[84:87], v[142:145], v[196:199], v[84:87]
	v_mfma_f32_16x16x32_bf16 v[80:83], v[156:159], v[196:199], v[80:83]
	v_mfma_f32_16x16x32_bf16 v[76:79], v[142:145], v[204:207], v[76:79]
	v_mfma_f32_16x16x32_bf16 v[72:75], v[156:159], v[204:207], v[72:75]
	v_mfma_f32_16x16x32_bf16 v[68:71], v[142:145], v[214:217], v[68:71]
	v_mfma_f32_16x16x32_bf16 v[64:67], v[156:159], v[214:217], v[64:67]
	s_setprio 0
	s_setprio 1
	v_mfma_f32_16x16x32_bf16 v[28:31], v[160:163], v[176:179], v[28:31]
	v_mfma_f32_16x16x32_bf16 v[24:27], v[168:171], v[176:179], v[24:27]
	v_mfma_f32_16x16x32_bf16 v[20:23], v[160:163], v[192:195], v[20:23]
	v_mfma_f32_16x16x32_bf16 v[16:19], v[168:171], v[192:195], v[16:19]
	v_mfma_f32_16x16x32_bf16 v[12:15], v[160:163], v[200:203], v[12:15]
	v_mfma_f32_16x16x32_bf16 v[8:11], v[168:171], v[200:203], v[8:11]
	v_mfma_f32_16x16x32_bf16 v[4:7], v[160:163], v[210:213], v[4:7]
	v_mfma_f32_16x16x32_bf16 v[0:3], v[168:171], v[210:213], v[0:3]
	v_mfma_f32_16x16x32_bf16 v[28:31], v[164:167], v[180:183], v[28:31]
	v_mfma_f32_16x16x32_bf16 v[24:27], v[172:175], v[180:183], v[24:27]
	v_mfma_f32_16x16x32_bf16 v[20:23], v[164:167], v[196:199], v[20:23]
	v_mfma_f32_16x16x32_bf16 v[16:19], v[172:175], v[196:199], v[16:19]
	v_mfma_f32_16x16x32_bf16 v[12:15], v[164:167], v[204:207], v[12:15]
	v_mfma_f32_16x16x32_bf16 v[8:11], v[172:175], v[204:207], v[8:11]
	v_mfma_f32_16x16x32_bf16 v[4:7], v[164:167], v[214:217], v[4:7]
	v_mfma_f32_16x16x32_bf16 v[0:3], v[172:175], v[214:217], v[0:3]
	s_setprio 0
	s_barrier
	s_add_i32 s70, 0, 0x18000
	v_add_u32_e32 v155, s70, v151
	s_add_i32 s71, 0, 0x1c000
	ds_read_b128 v[138:141], v155
	ds_read_b128 v[142:145], v155 offset:1024
	ds_read_b128 v[146:149], v155 offset:2048
	ds_read_b128 v[156:159], v155 offset:3072
	v_add_u32_e32 v155, s71, v151
	ds_read_b128 v[160:163], v155
	ds_read_b128 v[164:167], v155 offset:1024
	ds_read_b128 v[168:171], v155 offset:2048
	ds_read_b128 v[172:175], v155 offset:3072
	s_add_u32 s50, s50, s6
	s_addc_u32 s51, s51, s7
	s_mov_b32 m0, s52
	ds_read_b128 v[176:179], v154 offset:32768
	ds_read_b128 v[180:183], v154 offset:33792
	ds_read_b128 v[192:195], v154 offset:34816
	ds_read_b128 v[196:199], v154 offset:35840
	ds_read_b128 v[200:203], v154 offset:36864
	ds_read_b128 v[204:207], v154 offset:37888
	ds_read_b128 v[210:213], v154 offset:38912
	ds_read_b128 v[214:217], v154 offset:39936
	global_load_lds_dwordx4 v132, s[50:51]
	v_lshl_add_u64 v[224:225], s[50:51], 0, v[130:131]
	s_mov_b32 m0, s53
	s_nop 0
	global_load_lds_dwordx4 v[224:225], off
	s_waitcnt vmcnt(8)
	s_waitcnt lgkmcnt(0)
	s_barrier
	s_setprio 1
	s_waitcnt lgkmcnt(0)
	v_mfma_f32_16x16x32_bf16 v[124:127], v[138:141], v[176:179], v[124:127]
	v_mfma_f32_16x16x32_bf16 v[120:123], v[146:149], v[176:179], v[120:123]
	v_mfma_f32_16x16x32_bf16 v[116:119], v[138:141], v[192:195], v[116:119]
	v_mfma_f32_16x16x32_bf16 v[112:115], v[146:149], v[192:195], v[112:115]
	v_mfma_f32_16x16x32_bf16 v[108:111], v[138:141], v[200:203], v[108:111]
	v_mfma_f32_16x16x32_bf16 v[104:107], v[146:149], v[200:203], v[104:107]
	v_mfma_f32_16x16x32_bf16 v[100:103], v[138:141], v[210:213], v[100:103]
	v_mfma_f32_16x16x32_bf16 v[96:99], v[146:149], v[210:213], v[96:99]
	v_mfma_f32_16x16x32_bf16 v[124:127], v[142:145], v[180:183], v[124:127]
	v_mfma_f32_16x16x32_bf16 v[120:123], v[156:159], v[180:183], v[120:123]
	v_mfma_f32_16x16x32_bf16 v[116:119], v[142:145], v[196:199], v[116:119]
	v_mfma_f32_16x16x32_bf16 v[112:115], v[156:159], v[196:199], v[112:115]
	v_mfma_f32_16x16x32_bf16 v[108:111], v[142:145], v[204:207], v[108:111]
	v_mfma_f32_16x16x32_bf16 v[104:107], v[156:159], v[204:207], v[104:107]
	v_mfma_f32_16x16x32_bf16 v[100:103], v[142:145], v[214:217], v[100:103]
	v_mfma_f32_16x16x32_bf16 v[96:99], v[156:159], v[214:217], v[96:99]
	s_setprio 0
	s_setprio 1
	v_mfma_f32_16x16x32_bf16 v[60:63], v[160:163], v[176:179], v[60:63]
	v_mfma_f32_16x16x32_bf16 v[56:59], v[168:171], v[176:179], v[56:59]
	v_mfma_f32_16x16x32_bf16 v[52:55], v[160:163], v[192:195], v[52:55]
	v_mfma_f32_16x16x32_bf16 v[48:51], v[168:171], v[192:195], v[48:51]
	v_mfma_f32_16x16x32_bf16 v[44:47], v[160:163], v[200:203], v[44:47]
	v_mfma_f32_16x16x32_bf16 v[40:43], v[168:171], v[200:203], v[40:43]
	v_mfma_f32_16x16x32_bf16 v[36:39], v[160:163], v[210:213], v[36:39]
	v_mfma_f32_16x16x32_bf16 v[32:35], v[168:171], v[210:213], v[32:35]
	v_mfma_f32_16x16x32_bf16 v[60:63], v[164:167], v[180:183], v[60:63]
	v_mfma_f32_16x16x32_bf16 v[56:59], v[172:175], v[180:183], v[56:59]
	v_mfma_f32_16x16x32_bf16 v[52:55], v[164:167], v[196:199], v[52:55]
	v_mfma_f32_16x16x32_bf16 v[48:51], v[172:175], v[196:199], v[48:51]
	v_mfma_f32_16x16x32_bf16 v[44:47], v[164:167], v[204:207], v[44:47]
	v_mfma_f32_16x16x32_bf16 v[40:43], v[172:175], v[204:207], v[40:43]
	v_mfma_f32_16x16x32_bf16 v[36:39], v[164:167], v[214:217], v[36:39]
	v_mfma_f32_16x16x32_bf16 v[32:35], v[172:175], v[214:217], v[32:35]
	s_setprio 0
	s_barrier
; #define PG8_STAGE(bufoff, gbase, voff) do { _Pragma("unroll") for (int _i = 0; _i < 2; ++_i) \
;         __builtin_amdgcn_global_load_lds((const unsigned*)((const char*)(gbase) + (voff)[_i]), (LAS unsigned*)(lds + (bufoff) + ldsw + _i * 8192), 16, 0, 0); } while (0)
; #define PG8_LDA(dst, b, h) do { _Pragma("unroll") for (int m = 0; m < 4; ++m) _Pragma("unroll") for (int k = 0; k < 2; ++k) dst[m][k] = *(const LAS bf16x8*)(lds + PG8_SA(b, h) + aoff + m * 2048 + k * 1024); } while (0)
; #define PG8_MMA(ai, bj, At, Bt) do { __builtin_amdgcn_s_setprio(1); _Pragma("unroll") for (int m = 0; m < 4; ++m) _Pragma("unroll") for (int n = 0; n < 2; ++n) _Pragma("unroll") for (int k = 0; k < 2; ++k) \
;         acc[ai][bj][m][n] = __builtin_amdgcn_mfma_f32_16x16x32_bf16(Bt[n][k], At[m][k], acc[ai][bj][m][n], 0, 0, 0); __builtin_amdgcn_s_setprio(0); } while (0)
; #define PG8_WAIT_V(n) asm volatile("s_waitcnt vmcnt(" #n ")" ::: "memory")
; #define PG8_WAIT_L(n) asm volatile("s_waitcnt lgkmcnt(" #n ")" ::: "memory")
; #define PG8_BAR __builtin_amdgcn_s_barrier()
; #define PG8_SCHED __builtin_amdgcn_sched_barrier(0)
; template <class Epi, bool ALIGN_EPI>
; __device__ __forceinline__ void gemm_phase(LAS unsigned char* lds, const Gemm g, const StaticOrder& S, const Epi& E, const int wave_s) {
;     ...
;             PG8_LDA(At, 1, 1); PG8_STAGE(PG8_SB(1, 0), b3, voffB); PG8_STAGE(PG8_SB(1, 1), b3 + hstepB, voffB); PG8_STAGE(PG8_SA(1, 0), a3, voffA);
;             PG8_WAIT_V(8); PG8_WAIT_L(0); PG8_BAR; PG8_MMA(1, 0, At, B0); PG8_MMA(1, 1, At, B1); PG8_BAR; PG8_SCHED;
;         }
	s_add_i32 s50, s70, s4
	v_lshl_add_u64 v[188:189], v[188:189], 0, s[64:65]
	s_mov_b32 m0, s50
	ds_read_b128 v[176:179], v154 offset:49152
	ds_read_b128 v[180:183], v154 offset:50176
	ds_read_b128 v[192:195], v154 offset:51200
	ds_read_b128 v[196:199], v154 offset:52224
	ds_read_b128 v[200:203], v154 offset:53248
	ds_read_b128 v[204:207], v154 offset:54272
	ds_read_b128 v[210:213], v154 offset:55296
	ds_read_b128 v[214:217], v154 offset:56320
	global_load_lds_dwordx4 v[188:189], off
	v_lshl_add_u64 v[188:189], v[190:191], 0, s[64:65]
	s_add_i32 m0, s50, 0x2000
	s_add_i32 s50, s71, s4
	global_load_lds_dwordx4 v[188:189], off
	v_lshl_add_u64 v[188:189], v[208:209], 0, s[64:65]
	s_mov_b32 m0, s50
	s_nop 0
	global_load_lds_dwordx4 v[188:189], off
	v_lshl_add_u64 v[188:189], v[218:219], 0, s[64:65]
	s_add_i32 m0, s50, 0x2000
	s_nop 0
	global_load_lds_dwordx4 v[188:189], off
	v_lshl_add_u64 v[188:189], v[220:221], 0, s[64:65]
	s_mov_b32 m0, s56
	s_nop 0
	global_load_lds_dwordx4 v[188:189], off
	v_lshl_add_u64 v[188:189], v[222:223], 0, s[64:65]
	s_mov_b32 m0, s57
	s_nop 0
	global_load_lds_dwordx4 v[188:189], off
	s_waitcnt vmcnt(8)
	s_waitcnt lgkmcnt(0)
	s_barrier
	s_setprio 1
	s_waitcnt lgkmcnt(0)
	v_mfma_f32_16x16x32_bf16 v[92:95], v[138:141], v[176:179], v[92:95]
	v_mfma_f32_16x16x32_bf16 v[88:91], v[146:149], v[176:179], v[88:91]
	v_mfma_f32_16x16x32_bf16 v[84:87], v[138:141], v[192:195], v[84:87]
	v_mfma_f32_16x16x32_bf16 v[80:83], v[146:149], v[192:195], v[80:83]
	v_mfma_f32_16x16x32_bf16 v[76:79], v[138:141], v[200:203], v[76:79]
	v_mfma_f32_16x16x32_bf16 v[72:75], v[146:149], v[200:203], v[72:75]
	v_mfma_f32_16x16x32_bf16 v[68:71], v[138:141], v[210:213], v[68:71]
	v_mfma_f32_16x16x32_bf16 v[64:67], v[146:149], v[210:213], v[64:67]
	v_mfma_f32_16x16x32_bf16 v[92:95], v[142:145], v[180:183], v[92:95]
	v_mfma_f32_16x16x32_bf16 v[88:91], v[156:159], v[180:183], v[88:91]
	v_mfma_f32_16x16x32_bf16 v[84:87], v[142:145], v[196:199], v[84:87]
	v_mfma_f32_16x16x32_bf16 v[80:83], v[156:159], v[196:199], v[80:83]
	v_mfma_f32_16x16x32_bf16 v[76:79], v[142:145], v[204:207], v[76:79]
	v_mfma_f32_16x16x32_bf16 v[72:75], v[156:159], v[204:207], v[72:75]
	v_mfma_f32_16x16x32_bf16 v[68:71], v[142:145], v[214:217], v[68:71]
	v_mfma_f32_16x16x32_bf16 v[64:67], v[156:159], v[214:217], v[64:67]
	s_setprio 0
	s_setprio 1
	v_mfma_f32_16x16x32_bf16 v[28:31], v[160:163], v[176:179], v[28:31]
	v_mfma_f32_16x16x32_bf16 v[24:27], v[168:171], v[176:179], v[24:27]
	v_mfma_f32_16x16x32_bf16 v[20:23], v[160:163], v[192:195], v[20:23]
	v_mfma_f32_16x16x32_bf16 v[16:19], v[168:171], v[192:195], v[16:19]
	v_mfma_f32_16x16x32_bf16 v[12:15], v[160:163], v[200:203], v[12:15]
	v_mfma_f32_16x16x32_bf16 v[8:11], v[168:171], v[200:203], v[8:11]
	v_mfma_f32_16x16x32_bf16 v[4:7], v[160:163], v[210:213], v[4:7]
	v_mfma_f32_16x16x32_bf16 v[0:3], v[168:171], v[210:213], v[0:3]
	v_mfma_f32_16x16x32_bf16 v[28:31], v[164:167], v[180:183], v[28:31]
	v_mfma_f32_16x16x32_bf16 v[24:27], v[172:175], v[180:183], v[24:27]
	v_mfma_f32_16x16x32_bf16 v[20:23], v[164:167], v[196:199], v[20:23]
	v_mfma_f32_16x16x32_bf16 v[16:19], v[172:175], v[196:199], v[16:19]
	v_mfma_f32_16x16x32_bf16 v[12:15], v[164:167], v[204:207], v[12:15]
	v_mfma_f32_16x16x32_bf16 v[8:11], v[172:175], v[204:207], v[8:11]
	v_mfma_f32_16x16x32_bf16 v[4:7], v[164:167], v[214:217], v[4:7]
	v_mfma_f32_16x16x32_bf16 v[0:3], v[172:175], v[214:217], v[0:3]
	s_setprio 0
	s_barrier
	s_add_u32 s67, s67, 0x100
	s_addc_u32 s68, s68, 0
	s_add_u32 s38, s38, 0x100
	s_addc_u32 s39, s39, 0
	s_cmp_ge_i32 s69, s54
	s_mov_b32 s50, s69
	s_cbranch_scc0 .LBB0_540
	s_and_b64 vcc, exec, s[28:29]
	s_cbranch_vccz .LBB0_543

; #define PG8_STAGE(bufoff, gbase, voff) do { _Pragma("unroll") for (int _i = 0; _i < 2; ++_i) \
;         __builtin_amdgcn_global_load_lds((const unsigned*)((const char*)(gbase) + (voff)[_i]), (LAS unsigned*)(lds + (bufoff) + ldsw + _i * 8192), 16, 0, 0); } while (0)
; #define PG8_LDA(dst, b, h) do { _Pragma("unroll") for (int m = 0; m < 4; ++m) _Pragma("unroll") for (int k = 0; k < 2; ++k) dst[m][k] = *(const LAS bf16x8*)(lds + PG8_SA(b, h) + aoff + m * 2048 + k * 1024); } while (0)
; #define PG8_LDB(dst, b, h) do { _Pragma("unroll") for (int n = 0; n < 2; ++n) _Pragma("unroll") for (int k = 0; k < 2; ++k) dst[n][k] = *(const LAS bf16x8*)(lds + PG8_SB(b, h) + boff + n * 2048 + k * 1024); } while (0)
; #define PG8_MMA(ai, bj, At, Bt) do { __builtin_amdgcn_s_setprio(1); _Pragma("unroll") for (int m = 0; m < 4; ++m) _Pragma("unroll") for (int n = 0; n < 2; ++n) _Pragma("unroll") for (int k = 0; k < 2; ++k) \
;         acc[ai][bj][m][n] = __builtin_amdgcn_mfma_f32_16x16x32_bf16(Bt[n][k], At[m][k], acc[ai][bj][m][n], 0, 0, 0); __builtin_amdgcn_s_setprio(0); } while (0)
; #define PG8_WAIT_V(n) asm volatile("s_waitcnt vmcnt(" #n ")" ::: "memory")
; #define PG8_WAIT_L(n) asm volatile("s_waitcnt lgkmcnt(" #n ")" ::: "memory")
; #define PG8_BAR __builtin_amdgcn_s_barrier()
; #define PG8_SCHED __builtin_amdgcn_sched_barrier(0)
; template <class Epi, bool ALIGN_EPI>
; __device__ __forceinline__ void gemm_phase(LAS unsigned char* lds, const Gemm g, const StaticOrder& S, const Epi& E, const int wave_s) {
;     ...
;         for (int t = 0; t < nt; t += 2) {
;             const bool last = (t == nt - 2);
;             const char* a1 = cA + (size_t)(t + 1) * kstep;
;             const char* a2 = last ? nA : cA + (size_t)(t + 2) * kstep; const char* b2 = last ? nB : cB + (size_t)(t + 2) * kstep;
;             const char* a3 = a2 + kstep; const char* b3 = b2 + kstep;
;             PG8_LDB(B0, 0, 0); PG8_LDB(B1, 0, 1); PG8_SCHED; PG8_LDA(At, 0, 0); PG8_STAGE(PG8_SA(1, 1), a1 + hstepA, voffA);
;             PG8_WAIT_V(8); PG8_WAIT_L(0); PG8_BAR; PG8_MMA(0, 0, At, B0); PG8_MMA(0, 1, At, B1); PG8_BAR; PG8_SCHED;
;             PG8_LDA(At, 0, 1); PG8_STAGE(PG8_SB(0, 0), b2, voffB); PG8_STAGE(PG8_SB(0, 1), b2 + hstepB, voffB); PG8_STAGE(PG8_SA(0, 0), a2, voffA);
;             PG8_WAIT_V(8); PG8_WAIT_L(0); PG8_BAR; PG8_MMA(1, 0, At, B0); PG8_MMA(1, 1, At, B1); PG8_BAR; PG8_SCHED;
.LBB0_598:
	s_add_i32 s66, s46, 2
	s_add_u32 s67, s38, 0x80
	s_addc_u32 s47, s39, 0
	s_add_i32 s70, 0, 0x10000
	s_cmp_eq_u32 s55, s46
	s_cselect_b32 s47, s1, s47
	s_cselect_b32 s46, s0, s67
	s_cselect_b32 s69, s29, s63
	s_cselect_b32 s68, s28, s61
	s_add_i32 s67, 0, 0x14000
	v_add_u32_e32 v154, s70, v147
	v_add_u32_e32 v170, s67, v147
	ds_read_b128 v[138:141], v154
	ds_read_b128 v[142:145], v154 offset:1024
	ds_read_b128 v[150:153], v154 offset:2048
	ds_read_b128 v[154:157], v154 offset:3072
	ds_read_b128 v[158:161], v170
	ds_read_b128 v[162:165], v170 offset:1024
	ds_read_b128 v[166:169], v170 offset:2048
	ds_read_b128 v[170:173], v170 offset:3072
	s_add_i32 m0, s48, 0xc000
	ds_read_b128 v[174:177], v149
	ds_read_b128 v[178:181], v149 offset:1024
	ds_read_b128 v[192:195], v149 offset:2048
	ds_read_b128 v[196:199], v149 offset:3072
	ds_read_b128 v[200:203], v149 offset:4096
	ds_read_b128 v[204:207], v149 offset:5120
	ds_read_b128 v[210:213], v149 offset:6144
	ds_read_b128 v[214:217], v149 offset:7168
	global_load_lds_dwordx4 v136, s[38:39]
	s_add_i32 m0, s48, 0xe000
	s_nop 0
	global_load_lds_dwordx4 v134, s[38:39]
	s_waitcnt vmcnt(8)
	s_waitcnt lgkmcnt(0)
	s_barrier
	s_setprio 1
	s_waitcnt lgkmcnt(0)
	v_mfma_f32_16x16x32_bf16 v[124:127], v[138:141], v[174:177], v[124:127]
	v_mfma_f32_16x16x32_bf16 v[120:123], v[150:153], v[174:177], v[120:123]
	v_mfma_f32_16x16x32_bf16 v[108:111], v[138:141], v[192:195], v[108:111]
	v_mfma_f32_16x16x32_bf16 v[104:107], v[150:153], v[192:195], v[104:107]
	v_mfma_f32_16x16x32_bf16 v[92:95], v[138:141], v[200:203], v[92:95]
	v_mfma_f32_16x16x32_bf16 v[88:91], v[150:153], v[200:203], v[88:91]
	v_mfma_f32_16x16x32_bf16 v[76:79], v[138:141], v[210:213], v[76:79]
	v_mfma_f32_16x16x32_bf16 v[72:75], v[150:153], v[210:213], v[72:75]
	v_mfma_f32_16x16x32_bf16 v[124:127], v[142:145], v[178:181], v[124:127]
	v_mfma_f32_16x16x32_bf16 v[120:123], v[154:157], v[178:181], v[120:123]
	v_mfma_f32_16x16x32_bf16 v[108:111], v[142:145], v[196:199], v[108:111]
	v_mfma_f32_16x16x32_bf16 v[104:107], v[154:157], v[196:199], v[104:107]
	v_mfma_f32_16x16x32_bf16 v[92:95], v[142:145], v[204:207], v[92:95]
	v_mfma_f32_16x16x32_bf16 v[88:91], v[154:157], v[204:207], v[88:91]
	v_mfma_f32_16x16x32_bf16 v[76:79], v[142:145], v[214:217], v[76:79]
	v_mfma_f32_16x16x32_bf16 v[72:75], v[154:157], v[214:217], v[72:75]
	s_setprio 0
	s_setprio 1
	v_mfma_f32_16x16x32_bf16 v[116:119], v[158:161], v[174:177], v[116:119]
	v_mfma_f32_16x16x32_bf16 v[112:115], v[166:169], v[174:177], v[112:115]
	v_mfma_f32_16x16x32_bf16 v[100:103], v[158:161], v[192:195], v[100:103]
	v_mfma_f32_16x16x32_bf16 v[96:99], v[166:169], v[192:195], v[96:99]
	v_mfma_f32_16x16x32_bf16 v[84:87], v[158:161], v[200:203], v[84:87]
	v_mfma_f32_16x16x32_bf16 v[80:83], v[166:169], v[200:203], v[80:83]
	v_mfma_f32_16x16x32_bf16 v[68:71], v[158:161], v[210:213], v[68:71]
	v_mfma_f32_16x16x32_bf16 v[64:67], v[166:169], v[210:213], v[64:67]
	v_mfma_f32_16x16x32_bf16 v[116:119], v[162:165], v[178:181], v[116:119]
	v_mfma_f32_16x16x32_bf16 v[112:115], v[170:173], v[178:181], v[112:115]
	v_mfma_f32_16x16x32_bf16 v[100:103], v[162:165], v[196:199], v[100:103]
	v_mfma_f32_16x16x32_bf16 v[96:99], v[170:173], v[196:199], v[96:99]
	v_mfma_f32_16x16x32_bf16 v[84:87], v[162:165], v[204:207], v[84:87]
	v_mfma_f32_16x16x32_bf16 v[80:83], v[170:173], v[204:207], v[80:83]
	v_mfma_f32_16x16x32_bf16 v[68:71], v[162:165], v[214:217], v[68:71]
	v_mfma_f32_16x16x32_bf16 v[64:67], v[170:173], v[214:217], v[64:67]
	s_setprio 0
	s_barrier
	s_add_i32 s70, s70, s25
	v_lshl_add_u64 v[182:183], s[68:69], 0, v[184:185]
	s_mov_b32 m0, s70
	ds_read_b128 v[174:177], v149 offset:16384
	ds_read_b128 v[178:181], v149 offset:17408
	ds_read_b128 v[192:195], v149 offset:18432
	ds_read_b128 v[196:199], v149 offset:19456
	ds_read_b128 v[200:203], v149 offset:20480
	ds_read_b128 v[204:207], v149 offset:21504
	ds_read_b128 v[210:213], v149 offset:22528
	ds_read_b128 v[214:217], v149 offset:23552
	global_load_lds_dwordx4 v[182:183], off
	s_add_i32 m0, s70, 0x2000
	v_lshl_add_u64 v[188:189], s[68:69], 0, v[128:129]
	s_add_u32 s68, s68, s8
	s_addc_u32 s69, s69, s9
	s_add_i32 s67, s67, s25
	global_load_lds_dwordx4 v[188:189], off
	v_lshl_add_u64 v[190:191], s[68:69], 0, v[184:185]
	s_mov_b32 m0, s67
	v_lshl_add_u64 v[208:209], s[68:69], 0, v[128:129]
	global_load_lds_dwordx4 v[190:191], off
	s_add_i32 m0, s67, 0x2000
	v_lshl_add_u64 v[218:219], s[46:47], 0, v[132:133]
	global_load_lds_dwordx4 v[208:209], off
	s_mov_b32 m0, s48
	v_lshl_add_u64 v[220:221], s[46:47], 0, v[130:131]
	global_load_lds_dwordx4 v[218:219], off
	s_mov_b32 m0, s49
	s_nop 0
	global_load_lds_dwordx4 v[220:221], off
	s_waitcnt vmcnt(8)
	s_waitcnt lgkmcnt(0)
	s_barrier
; #define PG8_STAGE(bufoff, gbase, voff) do { _Pragma("unroll") for (int _i = 0; _i < 2; ++_i) \
;         __builtin_amdgcn_global_load_lds((const unsigned*)((const char*)(gbase) + (voff)[_i]), (LAS unsigned*)(lds + (bufoff) + ldsw + _i * 8192), 16, 0, 0); } while (0)
; #define PG8_LDA(dst, b, h) do { _Pragma("unroll") for (int m = 0; m < 4; ++m) _Pragma("unroll") for (int k = 0; k < 2; ++k) dst[m][k] = *(const LAS bf16x8*)(lds + PG8_SA(b, h) + aoff + m * 2048 + k * 1024); } while (0)
; #define PG8_LDB(dst, b, h) do { _Pragma("unroll") for (int n = 0; n < 2; ++n) _Pragma("unroll") for (int k = 0; k < 2; ++k) dst[n][k] = *(const LAS bf16x8*)(lds + PG8_SB(b, h) + boff + n * 2048 + k * 1024); } while (0)
; #define PG8_MMA(ai, bj, At, Bt) do { __builtin_amdgcn_s_setprio(1); _Pragma("unroll") for (int m = 0; m < 4; ++m) _Pragma("unroll") for (int n = 0; n < 2; ++n) _Pragma("unroll") for (int k = 0; k < 2; ++k) \
;         acc[ai][bj][m][n] = __builtin_amdgcn_mfma_f32_16x16x32_bf16(Bt[n][k], At[m][k], acc[ai][bj][m][n], 0, 0, 0); __builtin_amdgcn_s_setprio(0); } while (0)
; #define PG8_WAIT_V(n) asm volatile("s_waitcnt vmcnt(" #n ")" ::: "memory")
; #define PG8_WAIT_L(n) asm volatile("s_waitcnt lgkmcnt(" #n ")" ::: "memory")
; #define PG8_BAR __builtin_amdgcn_s_barrier()
; #define PG8_SCHED __builtin_amdgcn_sched_barrier(0)
; template <class Epi, bool ALIGN_EPI>
; __device__ __forceinline__ void gemm_phase(LAS unsigned char* lds, const Gemm g, const StaticOrder& S, const Epi& E, const int wave_s) {
;     ...
;             PG8_WAIT_V(8); PG8_WAIT_L(0); PG8_BAR; PG8_MMA(1, 0, At, B0); PG8_MMA(1, 1, At, B1); PG8_BAR; PG8_SCHED;
;             PG8_LDB(B0, 1, 0); PG8_LDB(B1, 1, 1); PG8_SCHED; PG8_LDA(At, 1, 0); PG8_STAGE(PG8_SA(0, 1), a2 + hstepA, voffA);
;             PG8_WAIT_V(8); PG8_WAIT_L(0); PG8_BAR; PG8_MMA(0, 0, At, B0); PG8_MMA(0, 1, At, B1); PG8_BAR; PG8_SCHED;
	s_setprio 1
	s_waitcnt lgkmcnt(0)
	v_mfma_f32_16x16x32_bf16 v[60:63], v[138:141], v[174:177], v[60:63]
	v_mfma_f32_16x16x32_bf16 v[56:59], v[150:153], v[174:177], v[56:59]
	v_mfma_f32_16x16x32_bf16 v[44:47], v[138:141], v[192:195], v[44:47]
	v_mfma_f32_16x16x32_bf16 v[40:43], v[150:153], v[192:195], v[40:43]
	v_mfma_f32_16x16x32_bf16 v[28:31], v[138:141], v[200:203], v[28:31]
	v_mfma_f32_16x16x32_bf16 v[24:27], v[150:153], v[200:203], v[24:27]
	v_mfma_f32_16x16x32_bf16 v[12:15], v[138:141], v[210:213], v[12:15]
	v_mfma_f32_16x16x32_bf16 v[8:11], v[150:153], v[210:213], v[8:11]
	v_mfma_f32_16x16x32_bf16 v[60:63], v[142:145], v[178:181], v[60:63]
	v_mfma_f32_16x16x32_bf16 v[56:59], v[154:157], v[178:181], v[56:59]
	v_mfma_f32_16x16x32_bf16 v[44:47], v[142:145], v[196:199], v[44:47]
	v_mfma_f32_16x16x32_bf16 v[40:43], v[154:157], v[196:199], v[40:43]
	v_mfma_f32_16x16x32_bf16 v[28:31], v[142:145], v[204:207], v[28:31]
	v_mfma_f32_16x16x32_bf16 v[24:27], v[154:157], v[204:207], v[24:27]
	v_mfma_f32_16x16x32_bf16 v[12:15], v[142:145], v[214:217], v[12:15]
	v_mfma_f32_16x16x32_bf16 v[8:11], v[154:157], v[214:217], v[8:11]
	s_setprio 0
	s_setprio 1
	v_mfma_f32_16x16x32_bf16 v[52:55], v[158:161], v[174:177], v[52:55]
	v_mfma_f32_16x16x32_bf16 v[48:51], v[166:169], v[174:177], v[48:51]
	v_mfma_f32_16x16x32_bf16 v[36:39], v[158:161], v[192:195], v[36:39]
	v_mfma_f32_16x16x32_bf16 v[32:35], v[166:169], v[192:195], v[32:35]
	v_mfma_f32_16x16x32_bf16 v[20:23], v[158:161], v[200:203], v[20:23]
	v_mfma_f32_16x16x32_bf16 v[16:19], v[166:169], v[200:203], v[16:19]
	v_mfma_f32_16x16x32_bf16 v[4:7], v[158:161], v[210:213], v[4:7]
	v_mfma_f32_16x16x32_bf16 v[0:3], v[166:169], v[210:213], v[0:3]
	v_mfma_f32_16x16x32_bf16 v[52:55], v[162:165], v[178:181], v[52:55]
	v_mfma_f32_16x16x32_bf16 v[48:51], v[170:173], v[178:181], v[48:51]
	v_mfma_f32_16x16x32_bf16 v[36:39], v[162:165], v[196:199], v[36:39]
	v_mfma_f32_16x16x32_bf16 v[32:35], v[170:173], v[196:199], v[32:35]
	v_mfma_f32_16x16x32_bf16 v[20:23], v[162:165], v[204:207], v[20:23]
	v_mfma_f32_16x16x32_bf16 v[16:19], v[170:173], v[204:207], v[16:19]
	v_mfma_f32_16x16x32_bf16 v[4:7], v[162:165], v[214:217], v[4:7]
	v_mfma_f32_16x16x32_bf16 v[0:3], v[170:173], v[214:217], v[0:3]
	s_setprio 0
	s_barrier
	s_add_i32 s67, 0, 0x18000
	s_add_i32 s68, 0, 0x1c000
	v_add_u32_e32 v154, s67, v147
	v_add_u32_e32 v170, s68, v147
	ds_read_b128 v[138:141], v154
	ds_read_b128 v[142:145], v154 offset:1024
	ds_read_b128 v[150:153], v154 offset:2048
	ds_read_b128 v[154:157], v154 offset:3072
	ds_read_b128 v[158:161], v170
	ds_read_b128 v[162:165], v170 offset:1024
	ds_read_b128 v[166:169], v170 offset:2048
	ds_read_b128 v[170:173], v170 offset:3072
	s_add_u32 s46, s46, s6
	s_addc_u32 s47, s47, s7
	s_mov_b32 m0, s50
	ds_read_b128 v[174:177], v149 offset:32768
	ds_read_b128 v[178:181], v149 offset:33792
	ds_read_b128 v[192:195], v149 offset:34816
	ds_read_b128 v[196:199], v149 offset:35840
	ds_read_b128 v[200:203], v149 offset:36864
	ds_read_b128 v[204:207], v149 offset:37888
	ds_read_b128 v[210:213], v149 offset:38912
	ds_read_b128 v[214:217], v149 offset:39936
	global_load_lds_dwordx4 v132, s[46:47]
	v_lshl_add_u64 v[222:223], s[46:47], 0, v[130:131]
	s_mov_b32 m0, s51
	s_nop 0
	global_load_lds_dwordx4 v[222:223], off
	s_waitcnt vmcnt(8)
	s_waitcnt lgkmcnt(0)
	s_barrier
	s_setprio 1
	s_waitcnt lgkmcnt(0)
	v_mfma_f32_16x16x32_bf16 v[124:127], v[138:141], v[174:177], v[124:127]
	v_mfma_f32_16x16x32_bf16 v[120:123], v[150:153], v[174:177], v[120:123]
	v_mfma_f32_16x16x32_bf16 v[108:111], v[138:141], v[192:195], v[108:111]
	v_mfma_f32_16x16x32_bf16 v[104:107], v[150:153], v[192:195], v[104:107]
	v_mfma_f32_16x16x32_bf16 v[92:95], v[138:141], v[200:203], v[92:95]
	v_mfma_f32_16x16x32_bf16 v[88:91], v[150:153], v[200:203], v[88:91]
	v_mfma_f32_16x16x32_bf16 v[76:79], v[138:141], v[210:213], v[76:79]
	v_mfma_f32_16x16x32_bf16 v[72:75], v[150:153], v[210:213], v[72:75]
	v_mfma_f32_16x16x32_bf16 v[124:127], v[142:145], v[178:181], v[124:127]
	v_mfma_f32_16x16x32_bf16 v[120:123], v[154:157], v[178:181], v[120:123]
	v_mfma_f32_16x16x32_bf16 v[108:111], v[142:145], v[196:199], v[108:111]
	v_mfma_f32_16x16x32_bf16 v[104:107], v[154:157], v[196:199], v[104:107]
	v_mfma_f32_16x16x32_bf16 v[92:95], v[142:145], v[204:207], v[92:95]
	v_mfma_f32_16x16x32_bf16 v[88:91], v[154:157], v[204:207], v[88:91]
	v_mfma_f32_16x16x32_bf16 v[76:79], v[142:145], v[214:217], v[76:79]
	v_mfma_f32_16x16x32_bf16 v[72:75], v[154:157], v[214:217], v[72:75]
	s_setprio 0
	s_setprio 1
	v_mfma_f32_16x16x32_bf16 v[116:119], v[158:161], v[174:177], v[116:119]
	v_mfma_f32_16x16x32_bf16 v[112:115], v[166:169], v[174:177], v[112:115]
	v_mfma_f32_16x16x32_bf16 v[100:103], v[158:161], v[192:195], v[100:103]
	v_mfma_f32_16x16x32_bf16 v[96:99], v[166:169], v[192:195], v[96:99]
	v_mfma_f32_16x16x32_bf16 v[84:87], v[158:161], v[200:203], v[84:87]
	v_mfma_f32_16x16x32_bf16 v[80:83], v[166:169], v[200:203], v[80:83]
	v_mfma_f32_16x16x32_bf16 v[68:71], v[158:161], v[210:213], v[68:71]
	v_mfma_f32_16x16x32_bf16 v[64:67], v[166:169], v[210:213], v[64:67]
	v_mfma_f32_16x16x32_bf16 v[116:119], v[162:165], v[178:181], v[116:119]
	v_mfma_f32_16x16x32_bf16 v[112:115], v[170:173], v[178:181], v[112:115]
	v_mfma_f32_16x16x32_bf16 v[100:103], v[162:165], v[196:199], v[100:103]
	v_mfma_f32_16x16x32_bf16 v[96:99], v[170:173], v[196:199], v[96:99]
	v_mfma_f32_16x16x32_bf16 v[84:87], v[162:165], v[204:207], v[84:87]
	v_mfma_f32_16x16x32_bf16 v[80:83], v[170:173], v[204:207], v[80:83]
	v_mfma_f32_16x16x32_bf16 v[68:71], v[162:165], v[214:217], v[68:71]
	v_mfma_f32_16x16x32_bf16 v[64:67], v[170:173], v[214:217], v[64:67]
	s_setprio 0
	s_barrier
; #define PG8_STAGE(bufoff, gbase, voff) do { _Pragma("unroll") for (int _i = 0; _i < 2; ++_i) \
;         __builtin_amdgcn_global_load_lds((const unsigned*)((const char*)(gbase) + (voff)[_i]), (LAS unsigned*)(lds + (bufoff) + ldsw + _i * 8192), 16, 0, 0); } while (0)
; #define PG8_LDA(dst, b, h) do { _Pragma("unroll") for (int m = 0; m < 4; ++m) _Pragma("unroll") for (int k = 0; k < 2; ++k) dst[m][k] = *(const LAS bf16x8*)(lds + PG8_SA(b, h) + aoff + m * 2048 + k * 1024); } while (0)
; #define PG8_MMA(ai, bj, At, Bt) do { __builtin_amdgcn_s_setprio(1); _Pragma("unroll") for (int m = 0; m < 4; ++m) _Pragma("unroll") for (int n = 0; n < 2; ++n) _Pragma("unroll") for (int k = 0; k < 2; ++k) \
;         acc[ai][bj][m][n] = __builtin_amdgcn_mfma_f32_16x16x32_bf16(Bt[n][k], At[m][k], acc[ai][bj][m][n], 0, 0, 0); __builtin_amdgcn_s_setprio(0); } while (0)
; #define PG8_WAIT_V(n) asm volatile("s_waitcnt vmcnt(" #n ")" ::: "memory")
; #define PG8_WAIT_L(n) asm volatile("s_waitcnt lgkmcnt(" #n ")" ::: "memory")
; #define PG8_BAR __builtin_amdgcn_s_barrier()
; #define PG8_SCHED __builtin_amdgcn_sched_barrier(0)
; template <class Epi, bool ALIGN_EPI>
; __device__ __forceinline__ void gemm_phase(LAS unsigned char* lds, const Gemm g, const StaticOrder& S, const Epi& E, const int wave_s) {
;     ...
;             PG8_LDA(At, 1, 1); PG8_STAGE(PG8_SB(1, 0), b3, voffB); PG8_STAGE(PG8_SB(1, 1), b3 + hstepB, voffB); PG8_STAGE(PG8_SA(1, 0), a3, voffA);
;             PG8_WAIT_V(8); PG8_WAIT_L(0); PG8_BAR; PG8_MMA(1, 0, At, B0); PG8_MMA(1, 1, At, B1); PG8_BAR; PG8_SCHED;
;         }
	s_add_i32 s46, s67, s25
	v_lshl_add_u64 v[182:183], v[182:183], 0, s[64:65]
	s_mov_b32 m0, s46
	ds_read_b128 v[174:177], v149 offset:49152
	ds_read_b128 v[178:181], v149 offset:50176
	ds_read_b128 v[192:195], v149 offset:51200
	ds_read_b128 v[196:199], v149 offset:52224
	ds_read_b128 v[200:203], v149 offset:53248
	ds_read_b128 v[204:207], v149 offset:54272
	ds_read_b128 v[210:213], v149 offset:55296
	ds_read_b128 v[214:217], v149 offset:56320
	global_load_lds_dwordx4 v[182:183], off
	v_lshl_add_u64 v[182:183], v[188:189], 0, s[64:65]
	s_add_i32 m0, s46, 0x2000
	s_add_i32 s46, s68, s25
	global_load_lds_dwordx4 v[182:183], off
	v_lshl_add_u64 v[182:183], v[190:191], 0, s[64:65]
	s_mov_b32 m0, s46
	s_nop 0
	global_load_lds_dwordx4 v[182:183], off
	v_lshl_add_u64 v[182:183], v[208:209], 0, s[64:65]
	s_add_i32 m0, s46, 0x2000
	s_nop 0
	global_load_lds_dwordx4 v[182:183], off
	v_lshl_add_u64 v[182:183], v[218:219], 0, s[64:65]
	s_mov_b32 m0, s53
	s_nop 0
	global_load_lds_dwordx4 v[182:183], off
	v_lshl_add_u64 v[182:183], v[220:221], 0, s[64:65]
	s_mov_b32 m0, s54
	s_nop 0
	global_load_lds_dwordx4 v[182:183], off
	s_waitcnt vmcnt(8)
	s_waitcnt lgkmcnt(0)
	s_barrier
	s_setprio 1
	s_waitcnt lgkmcnt(0)
	v_mfma_f32_16x16x32_bf16 v[60:63], v[138:141], v[174:177], v[60:63]
	v_mfma_f32_16x16x32_bf16 v[56:59], v[150:153], v[174:177], v[56:59]
	v_mfma_f32_16x16x32_bf16 v[44:47], v[138:141], v[192:195], v[44:47]
	v_mfma_f32_16x16x32_bf16 v[40:43], v[150:153], v[192:195], v[40:43]
	v_mfma_f32_16x16x32_bf16 v[28:31], v[138:141], v[200:203], v[28:31]
	v_mfma_f32_16x16x32_bf16 v[24:27], v[150:153], v[200:203], v[24:27]
	v_mfma_f32_16x16x32_bf16 v[12:15], v[138:141], v[210:213], v[12:15]
	v_mfma_f32_16x16x32_bf16 v[8:11], v[150:153], v[210:213], v[8:11]
	v_mfma_f32_16x16x32_bf16 v[60:63], v[142:145], v[178:181], v[60:63]
	v_mfma_f32_16x16x32_bf16 v[56:59], v[154:157], v[178:181], v[56:59]
	v_mfma_f32_16x16x32_bf16 v[44:47], v[142:145], v[196:199], v[44:47]
	v_mfma_f32_16x16x32_bf16 v[40:43], v[154:157], v[196:199], v[40:43]
	v_mfma_f32_16x16x32_bf16 v[28:31], v[142:145], v[204:207], v[28:31]
	v_mfma_f32_16x16x32_bf16 v[24:27], v[154:157], v[204:207], v[24:27]
	v_mfma_f32_16x16x32_bf16 v[12:15], v[142:145], v[214:217], v[12:15]
	v_mfma_f32_16x16x32_bf16 v[8:11], v[154:157], v[214:217], v[8:11]
	s_setprio 0
	s_setprio 1
	v_mfma_f32_16x16x32_bf16 v[52:55], v[158:161], v[174:177], v[52:55]
	v_mfma_f32_16x16x32_bf16 v[48:51], v[166:169], v[174:177], v[48:51]
	v_mfma_f32_16x16x32_bf16 v[36:39], v[158:161], v[192:195], v[36:39]
	v_mfma_f32_16x16x32_bf16 v[32:35], v[166:169], v[192:195], v[32:35]
	v_mfma_f32_16x16x32_bf16 v[20:23], v[158:161], v[200:203], v[20:23]
	v_mfma_f32_16x16x32_bf16 v[16:19], v[166:169], v[200:203], v[16:19]
	v_mfma_f32_16x16x32_bf16 v[4:7], v[158:161], v[210:213], v[4:7]
	v_mfma_f32_16x16x32_bf16 v[0:3], v[166:169], v[210:213], v[0:3]
	v_mfma_f32_16x16x32_bf16 v[52:55], v[162:165], v[178:181], v[52:55]
	v_mfma_f32_16x16x32_bf16 v[48:51], v[170:173], v[178:181], v[48:51]
	v_mfma_f32_16x16x32_bf16 v[36:39], v[162:165], v[196:199], v[36:39]
	v_mfma_f32_16x16x32_bf16 v[32:35], v[170:173], v[196:199], v[32:35]
	v_mfma_f32_16x16x32_bf16 v[20:23], v[162:165], v[204:207], v[20:23]
	v_mfma_f32_16x16x32_bf16 v[16:19], v[170:173], v[204:207], v[16:19]
	v_mfma_f32_16x16x32_bf16 v[4:7], v[162:165], v[214:217], v[4:7]
	v_mfma_f32_16x16x32_bf16 v[0:3], v[170:173], v[214:217], v[0:3]
	s_setprio 0
	s_barrier
	s_add_u32 s61, s61, 0x100
	s_addc_u32 s63, s63, 0
	s_add_u32 s38, s38, 0x100
	s_addc_u32 s39, s39, 0
	s_cmp_ge_i32 s66, s52
	s_mov_b32 s46, s66
	s_cbranch_scc0 .LBB0_598
	s_and_b64 vcc, exec, s[20:21]
	s_cbranch_vccz .LBB0_601

; #define PG8_STAGE(bufoff, gbase, voff) do { _Pragma("unroll") for (int _i = 0; _i < 2; ++_i) \
;         __builtin_amdgcn_global_load_lds((const unsigned*)((const char*)(gbase) + (voff)[_i]), (LAS unsigned*)(lds + (bufoff) + ldsw + _i * 8192), 16, 0, 0); } while (0)
; #define PG8_LDA(dst, b, h) do { _Pragma("unroll") for (int m = 0; m < 4; ++m) _Pragma("unroll") for (int k = 0; k < 2; ++k) dst[m][k] = *(const LAS bf16x8*)(lds + PG8_SA(b, h) + aoff + m * 2048 + k * 1024); } while (0)
; #define PG8_LDB(dst, b, h) do { _Pragma("unroll") for (int n = 0; n < 2; ++n) _Pragma("unroll") for (int k = 0; k < 2; ++k) dst[n][k] = *(const LAS bf16x8*)(lds + PG8_SB(b, h) + boff + n * 2048 + k * 1024); } while (0)
; #define PG8_MMA(ai, bj, At, Bt) do { __builtin_amdgcn_s_setprio(1); _Pragma("unroll") for (int m = 0; m < 4; ++m) _Pragma("unroll") for (int n = 0; n < 2; ++n) _Pragma("unroll") for (int k = 0; k < 2; ++k) \
;         acc[ai][bj][m][n] = __builtin_amdgcn_mfma_f32_16x16x32_bf16(Bt[n][k], At[m][k], acc[ai][bj][m][n], 0, 0, 0); __builtin_amdgcn_s_setprio(0); } while (0)
; #define PG8_WAIT_V(n) asm volatile("s_waitcnt vmcnt(" #n ")" ::: "memory")
; #define PG8_WAIT_L(n) asm volatile("s_waitcnt lgkmcnt(" #n ")" ::: "memory")
; #define PG8_BAR __builtin_amdgcn_s_barrier()
; #define PG8_SCHED __builtin_amdgcn_sched_barrier(0)
; template <class Epi, bool ALIGN_EPI>
; __device__ __forceinline__ void gemm_phase(LAS unsigned char* lds, const Gemm g, const StaticOrder& S, const Epi& E, const int wave_s) {
;     ...
;         for (int t = 0; t < nt; t += 2) {
;             const bool last = (t == nt - 2);
;             const char* a1 = cA + (size_t)(t + 1) * kstep;
;             const char* a2 = last ? nA : cA + (size_t)(t + 2) * kstep; const char* b2 = last ? nB : cB + (size_t)(t + 2) * kstep;
;             const char* a3 = a2 + kstep; const char* b3 = b2 + kstep;
;             PG8_LDB(B0, 0, 0); PG8_LDB(B1, 0, 1); PG8_SCHED; PG8_LDA(At, 0, 0); PG8_STAGE(PG8_SA(1, 1), a1 + hstepA, voffA);
;             PG8_WAIT_V(8); PG8_WAIT_L(0); PG8_BAR; PG8_MMA(0, 0, At, B0); PG8_MMA(0, 1, At, B1); PG8_BAR; PG8_SCHED;
;             PG8_LDA(At, 0, 1); PG8_STAGE(PG8_SB(0, 0), b2, voffB); PG8_STAGE(PG8_SB(0, 1), b2 + hstepB, voffB); PG8_STAGE(PG8_SA(0, 0), a2, voffA);
;             PG8_WAIT_V(8); PG8_WAIT_L(0); PG8_BAR; PG8_MMA(1, 0, At, B0); PG8_MMA(1, 1, At, B1); PG8_BAR; PG8_SCHED;
.LBB0_641:
	s_add_i32 s59, s40, 2
	s_add_u32 s60, s38, 0x80
	s_addc_u32 s41, s39, 0
	s_add_i32 s63, 0, 0x10000
	s_cmp_eq_u32 s51, s40
	s_cselect_b32 s41, s1, s41
	s_cselect_b32 s40, s0, s60
	s_cselect_b32 s61, s29, s58
	s_cselect_b32 s60, s28, s57
	s_add_i32 s66, 0, 0x14000
	v_add_u32_e32 v154, s63, v147
	v_add_u32_e32 v170, s66, v147
	ds_read_b128 v[138:141], v154
	ds_read_b128 v[142:145], v154 offset:1024
	ds_read_b128 v[150:153], v154 offset:2048
	ds_read_b128 v[154:157], v154 offset:3072
	ds_read_b128 v[158:161], v170
	ds_read_b128 v[162:165], v170 offset:1024
	ds_read_b128 v[166:169], v170 offset:2048
	ds_read_b128 v[170:173], v170 offset:3072
	s_add_i32 m0, s24, 0xc000
	ds_read_b128 v[174:177], v149
	ds_read_b128 v[178:181], v149 offset:1024
	ds_read_b128 v[192:195], v149 offset:2048
	ds_read_b128 v[196:199], v149 offset:3072
	ds_read_b128 v[200:203], v149 offset:4096
	ds_read_b128 v[204:207], v149 offset:5120
	ds_read_b128 v[210:213], v149 offset:6144
	ds_read_b128 v[214:217], v149 offset:7168
	global_load_lds_dwordx4 v136, s[38:39]
	s_add_i32 m0, s24, 0xe000
	s_nop 0
	global_load_lds_dwordx4 v134, s[38:39]
	s_waitcnt vmcnt(8)
	s_waitcnt lgkmcnt(0)
	s_barrier
	s_setprio 1
	s_waitcnt lgkmcnt(0)
	v_mfma_f32_16x16x32_bf16 v[124:127], v[138:141], v[174:177], v[124:127]
	v_mfma_f32_16x16x32_bf16 v[120:123], v[150:153], v[174:177], v[120:123]
	v_mfma_f32_16x16x32_bf16 v[108:111], v[138:141], v[192:195], v[108:111]
	v_mfma_f32_16x16x32_bf16 v[104:107], v[150:153], v[192:195], v[104:107]
	v_mfma_f32_16x16x32_bf16 v[92:95], v[138:141], v[200:203], v[92:95]
	v_mfma_f32_16x16x32_bf16 v[88:91], v[150:153], v[200:203], v[88:91]
	v_mfma_f32_16x16x32_bf16 v[76:79], v[138:141], v[210:213], v[76:79]
	v_mfma_f32_16x16x32_bf16 v[72:75], v[150:153], v[210:213], v[72:75]
	v_mfma_f32_16x16x32_bf16 v[124:127], v[142:145], v[178:181], v[124:127]
	v_mfma_f32_16x16x32_bf16 v[120:123], v[154:157], v[178:181], v[120:123]
	v_mfma_f32_16x16x32_bf16 v[108:111], v[142:145], v[196:199], v[108:111]
	v_mfma_f32_16x16x32_bf16 v[104:107], v[154:157], v[196:199], v[104:107]
	v_mfma_f32_16x16x32_bf16 v[92:95], v[142:145], v[204:207], v[92:95]
	v_mfma_f32_16x16x32_bf16 v[88:91], v[154:157], v[204:207], v[88:91]
	v_mfma_f32_16x16x32_bf16 v[76:79], v[142:145], v[214:217], v[76:79]
	v_mfma_f32_16x16x32_bf16 v[72:75], v[154:157], v[214:217], v[72:75]
	s_setprio 0
	s_setprio 1
	v_mfma_f32_16x16x32_bf16 v[116:119], v[158:161], v[174:177], v[116:119]
	v_mfma_f32_16x16x32_bf16 v[112:115], v[166:169], v[174:177], v[112:115]
	v_mfma_f32_16x16x32_bf16 v[100:103], v[158:161], v[192:195], v[100:103]
	v_mfma_f32_16x16x32_bf16 v[96:99], v[166:169], v[192:195], v[96:99]
	v_mfma_f32_16x16x32_bf16 v[84:87], v[158:161], v[200:203], v[84:87]
	v_mfma_f32_16x16x32_bf16 v[80:83], v[166:169], v[200:203], v[80:83]
	v_mfma_f32_16x16x32_bf16 v[68:71], v[158:161], v[210:213], v[68:71]
	v_mfma_f32_16x16x32_bf16 v[64:67], v[166:169], v[210:213], v[64:67]
	v_mfma_f32_16x16x32_bf16 v[116:119], v[162:165], v[178:181], v[116:119]
	v_mfma_f32_16x16x32_bf16 v[112:115], v[170:173], v[178:181], v[112:115]
	v_mfma_f32_16x16x32_bf16 v[100:103], v[162:165], v[196:199], v[100:103]
	v_mfma_f32_16x16x32_bf16 v[96:99], v[170:173], v[196:199], v[96:99]
	v_mfma_f32_16x16x32_bf16 v[84:87], v[162:165], v[204:207], v[84:87]
	v_mfma_f32_16x16x32_bf16 v[80:83], v[170:173], v[204:207], v[80:83]
	v_mfma_f32_16x16x32_bf16 v[68:71], v[162:165], v[214:217], v[68:71]
	v_mfma_f32_16x16x32_bf16 v[64:67], v[170:173], v[214:217], v[64:67]
	s_setprio 0
	s_barrier
	s_add_i32 s63, s63, s4
	v_lshl_add_u64 v[182:183], s[60:61], 0, v[184:185]
	s_mov_b32 m0, s63
	ds_read_b128 v[174:177], v149 offset:16384
	ds_read_b128 v[178:181], v149 offset:17408
	ds_read_b128 v[192:195], v149 offset:18432
	ds_read_b128 v[196:199], v149 offset:19456
	ds_read_b128 v[200:203], v149 offset:20480
	ds_read_b128 v[204:207], v149 offset:21504
	ds_read_b128 v[210:213], v149 offset:22528
	ds_read_b128 v[214:217], v149 offset:23552
	global_load_lds_dwordx4 v[182:183], off
	s_add_i32 m0, s63, 0x2000
	v_lshl_add_u64 v[188:189], s[60:61], 0, v[128:129]
	s_add_u32 s60, s60, s8
	s_addc_u32 s61, s61, s9
	s_add_i32 s63, s66, s4
	global_load_lds_dwordx4 v[188:189], off
	v_lshl_add_u64 v[190:191], s[60:61], 0, v[184:185]
	s_mov_b32 m0, s63
	v_lshl_add_u64 v[208:209], s[60:61], 0, v[128:129]
	global_load_lds_dwordx4 v[190:191], off
	s_add_i32 m0, s63, 0x2000
	v_lshl_add_u64 v[218:219], s[40:41], 0, v[132:133]
	global_load_lds_dwordx4 v[208:209], off
	s_mov_b32 m0, s24
	v_lshl_add_u64 v[220:221], s[40:41], 0, v[130:131]
	global_load_lds_dwordx4 v[218:219], off
	s_mov_b32 m0, s25
	s_nop 0
	global_load_lds_dwordx4 v[220:221], off
	s_waitcnt vmcnt(8)
	s_waitcnt lgkmcnt(0)
	s_barrier
; #define PG8_STAGE(bufoff, gbase, voff) do { _Pragma("unroll") for (int _i = 0; _i < 2; ++_i) \
;         __builtin_amdgcn_global_load_lds((const unsigned*)((const char*)(gbase) + (voff)[_i]), (LAS unsigned*)(lds + (bufoff) + ldsw + _i * 8192), 16, 0, 0); } while (0)
; #define PG8_LDA(dst, b, h) do { _Pragma("unroll") for (int m = 0; m < 4; ++m) _Pragma("unroll") for (int k = 0; k < 2; ++k) dst[m][k] = *(const LAS bf16x8*)(lds + PG8_SA(b, h) + aoff + m * 2048 + k * 1024); } while (0)
; #define PG8_LDB(dst, b, h) do { _Pragma("unroll") for (int n = 0; n < 2; ++n) _Pragma("unroll") for (int k = 0; k < 2; ++k) dst[n][k] = *(const LAS bf16x8*)(lds + PG8_SB(b, h) + boff + n * 2048 + k * 1024); } while (0)
; #define PG8_MMA(ai, bj, At, Bt) do { __builtin_amdgcn_s_setprio(1); _Pragma("unroll") for (int m = 0; m < 4; ++m) _Pragma("unroll") for (int n = 0; n < 2; ++n) _Pragma("unroll") for (int k = 0; k < 2; ++k) \
;         acc[ai][bj][m][n] = __builtin_amdgcn_mfma_f32_16x16x32_bf16(Bt[n][k], At[m][k], acc[ai][bj][m][n], 0, 0, 0); __builtin_amdgcn_s_setprio(0); } while (0)
; #define PG8_WAIT_V(n) asm volatile("s_waitcnt vmcnt(" #n ")" ::: "memory")
; #define PG8_WAIT_L(n) asm volatile("s_waitcnt lgkmcnt(" #n ")" ::: "memory")
; #define PG8_BAR __builtin_amdgcn_s_barrier()
; #define PG8_SCHED __builtin_amdgcn_sched_barrier(0)
; template <class Epi, bool ALIGN_EPI>
; __device__ __forceinline__ void gemm_phase(LAS unsigned char* lds, const Gemm g, const StaticOrder& S, const Epi& E, const int wave_s) {
;     ...
;             PG8_WAIT_V(8); PG8_WAIT_L(0); PG8_BAR; PG8_MMA(1, 0, At, B0); PG8_MMA(1, 1, At, B1); PG8_BAR; PG8_SCHED;
;             PG8_LDB(B0, 1, 0); PG8_LDB(B1, 1, 1); PG8_SCHED; PG8_LDA(At, 1, 0); PG8_STAGE(PG8_SA(0, 1), a2 + hstepA, voffA);
;             PG8_WAIT_V(8); PG8_WAIT_L(0); PG8_BAR; PG8_MMA(0, 0, At, B0); PG8_MMA(0, 1, At, B1); PG8_BAR; PG8_SCHED;
	s_setprio 1
	s_waitcnt lgkmcnt(0)
	v_mfma_f32_16x16x32_bf16 v[60:63], v[138:141], v[174:177], v[60:63]
	v_mfma_f32_16x16x32_bf16 v[56:59], v[150:153], v[174:177], v[56:59]
	v_mfma_f32_16x16x32_bf16 v[44:47], v[138:141], v[192:195], v[44:47]
	v_mfma_f32_16x16x32_bf16 v[40:43], v[150:153], v[192:195], v[40:43]
	v_mfma_f32_16x16x32_bf16 v[28:31], v[138:141], v[200:203], v[28:31]
	v_mfma_f32_16x16x32_bf16 v[24:27], v[150:153], v[200:203], v[24:27]
	v_mfma_f32_16x16x32_bf16 v[12:15], v[138:141], v[210:213], v[12:15]
	v_mfma_f32_16x16x32_bf16 v[8:11], v[150:153], v[210:213], v[8:11]
	v_mfma_f32_16x16x32_bf16 v[60:63], v[142:145], v[178:181], v[60:63]
	v_mfma_f32_16x16x32_bf16 v[56:59], v[154:157], v[178:181], v[56:59]
	v_mfma_f32_16x16x32_bf16 v[44:47], v[142:145], v[196:199], v[44:47]
	v_mfma_f32_16x16x32_bf16 v[40:43], v[154:157], v[196:199], v[40:43]
	v_mfma_f32_16x16x32_bf16 v[28:31], v[142:145], v[204:207], v[28:31]
	v_mfma_f32_16x16x32_bf16 v[24:27], v[154:157], v[204:207], v[24:27]
	v_mfma_f32_16x16x32_bf16 v[12:15], v[142:145], v[214:217], v[12:15]
	v_mfma_f32_16x16x32_bf16 v[8:11], v[154:157], v[214:217], v[8:11]
	s_setprio 0
	s_setprio 1
	v_mfma_f32_16x16x32_bf16 v[52:55], v[158:161], v[174:177], v[52:55]
	v_mfma_f32_16x16x32_bf16 v[48:51], v[166:169], v[174:177], v[48:51]
	v_mfma_f32_16x16x32_bf16 v[36:39], v[158:161], v[192:195], v[36:39]
	v_mfma_f32_16x16x32_bf16 v[32:35], v[166:169], v[192:195], v[32:35]
	v_mfma_f32_16x16x32_bf16 v[20:23], v[158:161], v[200:203], v[20:23]
	v_mfma_f32_16x16x32_bf16 v[16:19], v[166:169], v[200:203], v[16:19]
	v_mfma_f32_16x16x32_bf16 v[4:7], v[158:161], v[210:213], v[4:7]
	v_mfma_f32_16x16x32_bf16 v[0:3], v[166:169], v[210:213], v[0:3]
	v_mfma_f32_16x16x32_bf16 v[52:55], v[162:165], v[178:181], v[52:55]
	v_mfma_f32_16x16x32_bf16 v[48:51], v[170:173], v[178:181], v[48:51]
	v_mfma_f32_16x16x32_bf16 v[36:39], v[162:165], v[196:199], v[36:39]
	v_mfma_f32_16x16x32_bf16 v[32:35], v[170:173], v[196:199], v[32:35]
	v_mfma_f32_16x16x32_bf16 v[20:23], v[162:165], v[204:207], v[20:23]
	v_mfma_f32_16x16x32_bf16 v[16:19], v[170:173], v[204:207], v[16:19]
	v_mfma_f32_16x16x32_bf16 v[4:7], v[162:165], v[214:217], v[4:7]
	v_mfma_f32_16x16x32_bf16 v[0:3], v[170:173], v[214:217], v[0:3]
	s_setprio 0
	s_barrier
	s_add_i32 s60, 0, 0x18000
	s_add_i32 s61, 0, 0x1c000
	v_add_u32_e32 v154, s60, v147
	v_add_u32_e32 v170, s61, v147
	ds_read_b128 v[138:141], v154
	ds_read_b128 v[142:145], v154 offset:1024
	ds_read_b128 v[150:153], v154 offset:2048
	ds_read_b128 v[154:157], v154 offset:3072
	ds_read_b128 v[158:161], v170
	ds_read_b128 v[162:165], v170 offset:1024
	ds_read_b128 v[166:169], v170 offset:2048
	ds_read_b128 v[170:173], v170 offset:3072
	s_add_u32 s40, s40, s6
	s_addc_u32 s41, s41, s7
	s_mov_b32 m0, s46
	ds_read_b128 v[174:177], v149 offset:32768
	ds_read_b128 v[178:181], v149 offset:33792
	ds_read_b128 v[192:195], v149 offset:34816
	ds_read_b128 v[196:199], v149 offset:35840
	ds_read_b128 v[200:203], v149 offset:36864
	ds_read_b128 v[204:207], v149 offset:37888
	ds_read_b128 v[210:213], v149 offset:38912
	ds_read_b128 v[214:217], v149 offset:39936
	global_load_lds_dwordx4 v132, s[40:41]
	v_lshl_add_u64 v[222:223], s[40:41], 0, v[130:131]
	s_mov_b32 m0, s47
	s_nop 0
	global_load_lds_dwordx4 v[222:223], off
	s_waitcnt vmcnt(8)
	s_waitcnt lgkmcnt(0)
	s_barrier
	s_setprio 1
	s_waitcnt lgkmcnt(0)
	v_mfma_f32_16x16x32_bf16 v[124:127], v[138:141], v[174:177], v[124:127]
	v_mfma_f32_16x16x32_bf16 v[120:123], v[150:153], v[174:177], v[120:123]
	v_mfma_f32_16x16x32_bf16 v[108:111], v[138:141], v[192:195], v[108:111]
	v_mfma_f32_16x16x32_bf16 v[104:107], v[150:153], v[192:195], v[104:107]
	v_mfma_f32_16x16x32_bf16 v[92:95], v[138:141], v[200:203], v[92:95]
	v_mfma_f32_16x16x32_bf16 v[88:91], v[150:153], v[200:203], v[88:91]
	v_mfma_f32_16x16x32_bf16 v[76:79], v[138:141], v[210:213], v[76:79]
	v_mfma_f32_16x16x32_bf16 v[72:75], v[150:153], v[210:213], v[72:75]
	v_mfma_f32_16x16x32_bf16 v[124:127], v[142:145], v[178:181], v[124:127]
	v_mfma_f32_16x16x32_bf16 v[120:123], v[154:157], v[178:181], v[120:123]
	v_mfma_f32_16x16x32_bf16 v[108:111], v[142:145], v[196:199], v[108:111]
	v_mfma_f32_16x16x32_bf16 v[104:107], v[154:157], v[196:199], v[104:107]
	v_mfma_f32_16x16x32_bf16 v[92:95], v[142:145], v[204:207], v[92:95]
	v_mfma_f32_16x16x32_bf16 v[88:91], v[154:157], v[204:207], v[88:91]
	v_mfma_f32_16x16x32_bf16 v[76:79], v[142:145], v[214:217], v[76:79]
	v_mfma_f32_16x16x32_bf16 v[72:75], v[154:157], v[214:217], v[72:75]
	s_setprio 0
	s_setprio 1
	v_mfma_f32_16x16x32_bf16 v[116:119], v[158:161], v[174:177], v[116:119]
	v_mfma_f32_16x16x32_bf16 v[112:115], v[166:169], v[174:177], v[112:115]
	v_mfma_f32_16x16x32_bf16 v[100:103], v[158:161], v[192:195], v[100:103]
	v_mfma_f32_16x16x32_bf16 v[96:99], v[166:169], v[192:195], v[96:99]
	v_mfma_f32_16x16x32_bf16 v[84:87], v[158:161], v[200:203], v[84:87]
	v_mfma_f32_16x16x32_bf16 v[80:83], v[166:169], v[200:203], v[80:83]
	v_mfma_f32_16x16x32_bf16 v[68:71], v[158:161], v[210:213], v[68:71]
	v_mfma_f32_16x16x32_bf16 v[64:67], v[166:169], v[210:213], v[64:67]
	v_mfma_f32_16x16x32_bf16 v[116:119], v[162:165], v[178:181], v[116:119]
	v_mfma_f32_16x16x32_bf16 v[112:115], v[170:173], v[178:181], v[112:115]
	v_mfma_f32_16x16x32_bf16 v[100:103], v[162:165], v[196:199], v[100:103]
	v_mfma_f32_16x16x32_bf16 v[96:99], v[170:173], v[196:199], v[96:99]
	v_mfma_f32_16x16x32_bf16 v[84:87], v[162:165], v[204:207], v[84:87]
	v_mfma_f32_16x16x32_bf16 v[80:83], v[170:173], v[204:207], v[80:83]
	v_mfma_f32_16x16x32_bf16 v[68:71], v[162:165], v[214:217], v[68:71]
	v_mfma_f32_16x16x32_bf16 v[64:67], v[170:173], v[214:217], v[64:67]
	s_setprio 0
	s_barrier
; #define PG8_STAGE(bufoff, gbase, voff) do { _Pragma("unroll") for (int _i = 0; _i < 2; ++_i) \
;         __builtin_amdgcn_global_load_lds((const unsigned*)((const char*)(gbase) + (voff)[_i]), (LAS unsigned*)(lds + (bufoff) + ldsw + _i * 8192), 16, 0, 0); } while (0)
; #define PG8_LDA(dst, b, h) do { _Pragma("unroll") for (int m = 0; m < 4; ++m) _Pragma("unroll") for (int k = 0; k < 2; ++k) dst[m][k] = *(const LAS bf16x8*)(lds + PG8_SA(b, h) + aoff + m * 2048 + k * 1024); } while (0)
; #define PG8_MMA(ai, bj, At, Bt) do { __builtin_amdgcn_s_setprio(1); _Pragma("unroll") for (int m = 0; m < 4; ++m) _Pragma("unroll") for (int n = 0; n < 2; ++n) _Pragma("unroll") for (int k = 0; k < 2; ++k) \
;         acc[ai][bj][m][n] = __builtin_amdgcn_mfma_f32_16x16x32_bf16(Bt[n][k], At[m][k], acc[ai][bj][m][n], 0, 0, 0); __builtin_amdgcn_s_setprio(0); } while (0)
; #define PG8_WAIT_V(n) asm volatile("s_waitcnt vmcnt(" #n ")" ::: "memory")
; #define PG8_WAIT_L(n) asm volatile("s_waitcnt lgkmcnt(" #n ")" ::: "memory")
; #define PG8_BAR __builtin_amdgcn_s_barrier()
; #define PG8_SCHED __builtin_amdgcn_sched_barrier(0)
; template <class Epi, bool ALIGN_EPI>
; __device__ __forceinline__ void gemm_phase(LAS unsigned char* lds, const Gemm g, const StaticOrder& S, const Epi& E, const int wave_s) {
;     ...
;             PG8_LDA(At, 1, 1); PG8_STAGE(PG8_SB(1, 0), b3, voffB); PG8_STAGE(PG8_SB(1, 1), b3 + hstepB, voffB); PG8_STAGE(PG8_SA(1, 0), a3, voffA);
;             PG8_WAIT_V(8); PG8_WAIT_L(0); PG8_BAR; PG8_MMA(1, 0, At, B0); PG8_MMA(1, 1, At, B1); PG8_BAR; PG8_SCHED;
;         }
	s_add_i32 s40, s60, s4
	v_lshl_add_u64 v[182:183], v[182:183], 0, s[64:65]
	s_mov_b32 m0, s40
	ds_read_b128 v[174:177], v149 offset:49152
	ds_read_b128 v[178:181], v149 offset:50176
	ds_read_b128 v[192:195], v149 offset:51200
	ds_read_b128 v[196:199], v149 offset:52224
	ds_read_b128 v[200:203], v149 offset:53248
	ds_read_b128 v[204:207], v149 offset:54272
	ds_read_b128 v[210:213], v149 offset:55296
	ds_read_b128 v[214:217], v149 offset:56320
	global_load_lds_dwordx4 v[182:183], off
	v_lshl_add_u64 v[182:183], v[188:189], 0, s[64:65]
	s_add_i32 m0, s40, 0x2000
	s_add_i32 s40, s61, s4
	global_load_lds_dwordx4 v[182:183], off
	v_lshl_add_u64 v[182:183], v[190:191], 0, s[64:65]
	s_mov_b32 m0, s40
	s_nop 0
	global_load_lds_dwordx4 v[182:183], off
	v_lshl_add_u64 v[182:183], v[208:209], 0, s[64:65]
	s_add_i32 m0, s40, 0x2000
	s_nop 0
	global_load_lds_dwordx4 v[182:183], off
	v_lshl_add_u64 v[182:183], v[218:219], 0, s[64:65]
	s_mov_b32 m0, s48
	s_nop 0
	global_load_lds_dwordx4 v[182:183], off
	v_lshl_add_u64 v[182:183], v[220:221], 0, s[64:65]
	s_mov_b32 m0, s49
	s_nop 0
	global_load_lds_dwordx4 v[182:183], off
	s_waitcnt vmcnt(8)
	s_waitcnt lgkmcnt(0)
	s_barrier
	s_setprio 1
	s_waitcnt lgkmcnt(0)
	v_mfma_f32_16x16x32_bf16 v[60:63], v[138:141], v[174:177], v[60:63]
	v_mfma_f32_16x16x32_bf16 v[56:59], v[150:153], v[174:177], v[56:59]
	v_mfma_f32_16x16x32_bf16 v[44:47], v[138:141], v[192:195], v[44:47]
	v_mfma_f32_16x16x32_bf16 v[40:43], v[150:153], v[192:195], v[40:43]
	v_mfma_f32_16x16x32_bf16 v[28:31], v[138:141], v[200:203], v[28:31]
	v_mfma_f32_16x16x32_bf16 v[24:27], v[150:153], v[200:203], v[24:27]
	v_mfma_f32_16x16x32_bf16 v[12:15], v[138:141], v[210:213], v[12:15]
	v_mfma_f32_16x16x32_bf16 v[8:11], v[150:153], v[210:213], v[8:11]
	v_mfma_f32_16x16x32_bf16 v[60:63], v[142:145], v[178:181], v[60:63]
	v_mfma_f32_16x16x32_bf16 v[56:59], v[154:157], v[178:181], v[56:59]
	v_mfma_f32_16x16x32_bf16 v[44:47], v[142:145], v[196:199], v[44:47]
	v_mfma_f32_16x16x32_bf16 v[40:43], v[154:157], v[196:199], v[40:43]
	v_mfma_f32_16x16x32_bf16 v[28:31], v[142:145], v[204:207], v[28:31]
	v_mfma_f32_16x16x32_bf16 v[24:27], v[154:157], v[204:207], v[24:27]
	v_mfma_f32_16x16x32_bf16 v[12:15], v[142:145], v[214:217], v[12:15]
	v_mfma_f32_16x16x32_bf16 v[8:11], v[154:157], v[214:217], v[8:11]
	s_setprio 0
	s_setprio 1
	v_mfma_f32_16x16x32_bf16 v[52:55], v[158:161], v[174:177], v[52:55]
	v_mfma_f32_16x16x32_bf16 v[48:51], v[166:169], v[174:177], v[48:51]
	v_mfma_f32_16x16x32_bf16 v[36:39], v[158:161], v[192:195], v[36:39]
	v_mfma_f32_16x16x32_bf16 v[32:35], v[166:169], v[192:195], v[32:35]
	v_mfma_f32_16x16x32_bf16 v[20:23], v[158:161], v[200:203], v[20:23]
	v_mfma_f32_16x16x32_bf16 v[16:19], v[166:169], v[200:203], v[16:19]
	v_mfma_f32_16x16x32_bf16 v[4:7], v[158:161], v[210:213], v[4:7]
	v_mfma_f32_16x16x32_bf16 v[0:3], v[166:169], v[210:213], v[0:3]
	v_mfma_f32_16x16x32_bf16 v[52:55], v[162:165], v[178:181], v[52:55]
	v_mfma_f32_16x16x32_bf16 v[48:51], v[170:173], v[178:181], v[48:51]
	v_mfma_f32_16x16x32_bf16 v[36:39], v[162:165], v[196:199], v[36:39]
	v_mfma_f32_16x16x32_bf16 v[32:35], v[170:173], v[196:199], v[32:35]
	v_mfma_f32_16x16x32_bf16 v[20:23], v[162:165], v[204:207], v[20:23]
	v_mfma_f32_16x16x32_bf16 v[16:19], v[170:173], v[204:207], v[16:19]
	v_mfma_f32_16x16x32_bf16 v[4:7], v[162:165], v[214:217], v[4:7]
	v_mfma_f32_16x16x32_bf16 v[0:3], v[170:173], v[214:217], v[0:3]
	s_setprio 0
	s_barrier
	s_add_u32 s57, s57, 0x100
	s_addc_u32 s58, s58, 0
	s_add_u32 s38, s38, 0x100
	s_addc_u32 s39, s39, 0
	s_cmp_ge_i32 s59, s50
	s_mov_b32 s40, s59
	s_cbranch_scc0 .LBB0_641
	v_readlane_b32 s42, v252, 12
	s_and_b64 vcc, exec, s[20:21]
	s_cbranch_vccnz .LBB0_646
	s_branch .LBB0_647

; #define PG8_STAGE(bufoff, gbase, voff) do { _Pragma("unroll") for (int _i = 0; _i < 2; ++_i) \
;         __builtin_amdgcn_global_load_lds((const unsigned*)((const char*)(gbase) + (voff)[_i]), (LAS unsigned*)(lds + (bufoff) + ldsw + _i * 8192), 16, 0, 0); } while (0)
; #define PG8_LDA(dst, b, h) do { _Pragma("unroll") for (int m = 0; m < 4; ++m) _Pragma("unroll") for (int k = 0; k < 2; ++k) dst[m][k] = *(const LAS bf16x8*)(lds + PG8_SA(b, h) + aoff + m * 2048 + k * 1024); } while (0)
; #define PG8_LDB(dst, b, h) do { _Pragma("unroll") for (int n = 0; n < 2; ++n) _Pragma("unroll") for (int k = 0; k < 2; ++k) dst[n][k] = *(const LAS bf16x8*)(lds + PG8_SB(b, h) + boff + n * 2048 + k * 1024); } while (0)
; #define PG8_MMA(ai, bj, At, Bt) do { __builtin_amdgcn_s_setprio(1); _Pragma("unroll") for (int m = 0; m < 4; ++m) _Pragma("unroll") for (int n = 0; n < 2; ++n) _Pragma("unroll") for (int k = 0; k < 2; ++k) \
;         acc[ai][bj][m][n] = __builtin_amdgcn_mfma_f32_16x16x32_bf16(Bt[n][k], At[m][k], acc[ai][bj][m][n], 0, 0, 0); __builtin_amdgcn_s_setprio(0); } while (0)
; #define PG8_WAIT_V(n) asm volatile("s_waitcnt vmcnt(" #n ")" ::: "memory")
; #define PG8_WAIT_L(n) asm volatile("s_waitcnt lgkmcnt(" #n ")" ::: "memory")
; #define PG8_BAR __builtin_amdgcn_s_barrier()
; #define PG8_SCHED __builtin_amdgcn_sched_barrier(0)
; template <class Epi, bool ALIGN_EPI>
; __device__ __forceinline__ void gemm_phase(LAS unsigned char* lds, const Gemm g, const StaticOrder& S, const Epi& E, const int wave_s) {
;     ...
;         for (int t = 0; t < nt; t += 2) {
;             const bool last = (t == nt - 2);
;             const char* a1 = cA + (size_t)(t + 1) * kstep;
;             const char* a2 = last ? nA : cA + (size_t)(t + 2) * kstep; const char* b2 = last ? nB : cB + (size_t)(t + 2) * kstep;
;             const char* a3 = a2 + kstep; const char* b3 = b2 + kstep;
;             PG8_LDB(B0, 0, 0); PG8_LDB(B1, 0, 1); PG8_SCHED; PG8_LDA(At, 0, 0); PG8_STAGE(PG8_SA(1, 1), a1 + hstepA, voffA);
;             PG8_WAIT_V(8); PG8_WAIT_L(0); PG8_BAR; PG8_MMA(0, 0, At, B0); PG8_MMA(0, 1, At, B1); PG8_BAR; PG8_SCHED;
;             PG8_LDA(At, 0, 1); PG8_STAGE(PG8_SB(0, 0), b2, voffB); PG8_STAGE(PG8_SB(0, 1), b2 + hstepB, voffB); PG8_STAGE(PG8_SA(0, 0), a2, voffA);
;             PG8_WAIT_V(8); PG8_WAIT_L(0); PG8_BAR; PG8_MMA(1, 0, At, B0); PG8_MMA(1, 1, At, B1); PG8_BAR; PG8_SCHED;
.LBB0_888:
	s_add_i32 s57, s42, 2
	s_add_u32 s58, s40, 0x80
	s_addc_u32 s43, s41, 0
	s_add_i32 s60, 0, 0x10000
	s_cmp_eq_u32 s49, s42
	s_cselect_b32 s43, s1, s43
	s_cselect_b32 s42, s0, s58
	s_cselect_b32 s59, s29, s56
	s_cselect_b32 s58, s28, s55
	s_add_i32 s61, 0, 0x14000
	v_add_u32_e32 v44, s60, v165
	v_add_u32_e32 v162, s61, v165
	ds_read_b128 v[24:27], v44
	ds_read_b128 v[28:31], v44 offset:1024
	ds_read_b128 v[40:43], v44 offset:2048
	ds_read_b128 v[44:47], v44 offset:3072
	ds_read_b128 v[154:157], v162
	ds_read_b128 v[158:161], v162 offset:1024
	ds_read_b128 v[170:173], v162 offset:2048
	ds_read_b128 v[174:177], v162 offset:3072
	s_add_i32 m0, s24, 0xc000
	ds_read_b128 v[178:181], v169
	ds_read_b128 v[188:191], v169 offset:1024
	ds_read_b128 v[192:195], v169 offset:2048
	ds_read_b128 v[196:199], v169 offset:3072
	ds_read_b128 v[200:203], v169 offset:4096
	ds_read_b128 v[204:207], v169 offset:5120
	ds_read_b128 v[208:211], v169 offset:6144
	ds_read_b128 v[212:215], v169 offset:7168
	global_load_lds_dwordx4 v152, s[40:41]
	s_add_i32 m0, s24, 0xe000
	s_nop 0
	global_load_lds_dwordx4 v150, s[40:41]
	s_waitcnt vmcnt(8)
	s_waitcnt lgkmcnt(0)
	s_barrier
	s_setprio 1
	s_waitcnt lgkmcnt(0)
	v_mfma_f32_16x16x32_bf16 v[140:143], v[24:27], v[178:181], v[140:143]
	v_mfma_f32_16x16x32_bf16 v[136:139], v[40:43], v[178:181], v[136:139]
	v_mfma_f32_16x16x32_bf16 v[124:127], v[24:27], v[192:195], v[124:127]
	v_mfma_f32_16x16x32_bf16 v[120:123], v[40:43], v[192:195], v[120:123]
	v_mfma_f32_16x16x32_bf16 v[108:111], v[24:27], v[200:203], v[108:111]
	v_mfma_f32_16x16x32_bf16 v[104:107], v[40:43], v[200:203], v[104:107]
	v_mfma_f32_16x16x32_bf16 v[92:95], v[24:27], v[208:211], v[92:95]
	v_mfma_f32_16x16x32_bf16 v[88:91], v[40:43], v[208:211], v[88:91]
	v_mfma_f32_16x16x32_bf16 v[140:143], v[28:31], v[188:191], v[140:143]
	v_mfma_f32_16x16x32_bf16 v[136:139], v[44:47], v[188:191], v[136:139]
	v_mfma_f32_16x16x32_bf16 v[124:127], v[28:31], v[196:199], v[124:127]
	v_mfma_f32_16x16x32_bf16 v[120:123], v[44:47], v[196:199], v[120:123]
	v_mfma_f32_16x16x32_bf16 v[108:111], v[28:31], v[204:207], v[108:111]
	v_mfma_f32_16x16x32_bf16 v[104:107], v[44:47], v[204:207], v[104:107]
	v_mfma_f32_16x16x32_bf16 v[92:95], v[28:31], v[212:215], v[92:95]
	v_mfma_f32_16x16x32_bf16 v[88:91], v[44:47], v[212:215], v[88:91]
	s_setprio 0
	s_setprio 1
	v_mfma_f32_16x16x32_bf16 v[132:135], v[154:157], v[178:181], v[132:135]
	v_mfma_f32_16x16x32_bf16 v[128:131], v[170:173], v[178:181], v[128:131]
	v_mfma_f32_16x16x32_bf16 v[116:119], v[154:157], v[192:195], v[116:119]
	v_mfma_f32_16x16x32_bf16 v[112:115], v[170:173], v[192:195], v[112:115]
	v_mfma_f32_16x16x32_bf16 v[100:103], v[154:157], v[200:203], v[100:103]
	v_mfma_f32_16x16x32_bf16 v[96:99], v[170:173], v[200:203], v[96:99]
	v_mfma_f32_16x16x32_bf16 v[84:87], v[154:157], v[208:211], v[84:87]
	v_mfma_f32_16x16x32_bf16 v[80:83], v[170:173], v[208:211], v[80:83]
	v_mfma_f32_16x16x32_bf16 v[132:135], v[158:161], v[188:191], v[132:135]
	v_mfma_f32_16x16x32_bf16 v[128:131], v[174:177], v[188:191], v[128:131]
	v_mfma_f32_16x16x32_bf16 v[116:119], v[158:161], v[196:199], v[116:119]
	v_mfma_f32_16x16x32_bf16 v[112:115], v[174:177], v[196:199], v[112:115]
	v_mfma_f32_16x16x32_bf16 v[100:103], v[158:161], v[204:207], v[100:103]
	v_mfma_f32_16x16x32_bf16 v[96:99], v[174:177], v[204:207], v[96:99]
	v_mfma_f32_16x16x32_bf16 v[84:87], v[158:161], v[212:215], v[84:87]
	v_mfma_f32_16x16x32_bf16 v[80:83], v[174:177], v[212:215], v[80:83]
	s_setprio 0
	s_barrier
	s_add_i32 s60, s60, s4
	v_lshl_add_u64 v[162:163], s[58:59], 0, v[184:185]
	s_mov_b32 m0, s60
	ds_read_b128 v[178:181], v169 offset:16384
	ds_read_b128 v[188:191], v169 offset:17408
	ds_read_b128 v[192:195], v169 offset:18432
	ds_read_b128 v[196:199], v169 offset:19456
	ds_read_b128 v[200:203], v169 offset:20480
	ds_read_b128 v[204:207], v169 offset:21504
	ds_read_b128 v[208:211], v169 offset:22528
	ds_read_b128 v[212:215], v169 offset:23552
	global_load_lds_dwordx4 v[162:163], off
	s_add_i32 m0, s60, 0x2000
	v_lshl_add_u64 v[182:183], s[58:59], 0, v[144:145]
	s_add_u32 s58, s58, s8
	s_addc_u32 s59, s59, s9
	s_add_i32 s60, s61, s4
	global_load_lds_dwordx4 v[182:183], off
	v_lshl_add_u64 v[216:217], s[58:59], 0, v[184:185]
	s_mov_b32 m0, s60
	v_lshl_add_u64 v[218:219], s[58:59], 0, v[144:145]
	global_load_lds_dwordx4 v[216:217], off
	s_add_i32 m0, s60, 0x2000
	v_lshl_add_u64 v[220:221], s[42:43], 0, v[148:149]
	global_load_lds_dwordx4 v[218:219], off
	s_mov_b32 m0, s24
	v_lshl_add_u64 v[222:223], s[42:43], 0, v[146:147]
	global_load_lds_dwordx4 v[220:221], off
	s_mov_b32 m0, s25
	s_nop 0
	global_load_lds_dwordx4 v[222:223], off
	s_waitcnt vmcnt(8)
	s_waitcnt lgkmcnt(0)
	s_barrier
; #define PG8_STAGE(bufoff, gbase, voff) do { _Pragma("unroll") for (int _i = 0; _i < 2; ++_i) \
;         __builtin_amdgcn_global_load_lds((const unsigned*)((const char*)(gbase) + (voff)[_i]), (LAS unsigned*)(lds + (bufoff) + ldsw + _i * 8192), 16, 0, 0); } while (0)
; #define PG8_LDA(dst, b, h) do { _Pragma("unroll") for (int m = 0; m < 4; ++m) _Pragma("unroll") for (int k = 0; k < 2; ++k) dst[m][k] = *(const LAS bf16x8*)(lds + PG8_SA(b, h) + aoff + m * 2048 + k * 1024); } while (0)
; #define PG8_LDB(dst, b, h) do { _Pragma("unroll") for (int n = 0; n < 2; ++n) _Pragma("unroll") for (int k = 0; k < 2; ++k) dst[n][k] = *(const LAS bf16x8*)(lds + PG8_SB(b, h) + boff + n * 2048 + k * 1024); } while (0)
; #define PG8_MMA(ai, bj, At, Bt) do { __builtin_amdgcn_s_setprio(1); _Pragma("unroll") for (int m = 0; m < 4; ++m) _Pragma("unroll") for (int n = 0; n < 2; ++n) _Pragma("unroll") for (int k = 0; k < 2; ++k) \
;         acc[ai][bj][m][n] = __builtin_amdgcn_mfma_f32_16x16x32_bf16(Bt[n][k], At[m][k], acc[ai][bj][m][n], 0, 0, 0); __builtin_amdgcn_s_setprio(0); } while (0)
; #define PG8_WAIT_V(n) asm volatile("s_waitcnt vmcnt(" #n ")" ::: "memory")
; #define PG8_WAIT_L(n) asm volatile("s_waitcnt lgkmcnt(" #n ")" ::: "memory")
; #define PG8_BAR __builtin_amdgcn_s_barrier()
; #define PG8_SCHED __builtin_amdgcn_sched_barrier(0)
; template <class Epi, bool ALIGN_EPI>
; __device__ __forceinline__ void gemm_phase(LAS unsigned char* lds, const Gemm g, const StaticOrder& S, const Epi& E, const int wave_s) {
;     ...
;             PG8_WAIT_V(8); PG8_WAIT_L(0); PG8_BAR; PG8_MMA(1, 0, At, B0); PG8_MMA(1, 1, At, B1); PG8_BAR; PG8_SCHED;
;             PG8_LDB(B0, 1, 0); PG8_LDB(B1, 1, 1); PG8_SCHED; PG8_LDA(At, 1, 0); PG8_STAGE(PG8_SA(0, 1), a2 + hstepA, voffA);
;             PG8_WAIT_V(8); PG8_WAIT_L(0); PG8_BAR; PG8_MMA(0, 0, At, B0); PG8_MMA(0, 1, At, B1); PG8_BAR; PG8_SCHED;
	s_setprio 1
	s_waitcnt lgkmcnt(0)
	v_mfma_f32_16x16x32_bf16 v[76:79], v[24:27], v[178:181], v[76:79]
	v_mfma_f32_16x16x32_bf16 v[72:75], v[40:43], v[178:181], v[72:75]
	v_mfma_f32_16x16x32_bf16 v[60:63], v[24:27], v[192:195], v[60:63]
	v_mfma_f32_16x16x32_bf16 v[56:59], v[40:43], v[192:195], v[56:59]
	v_mfma_f32_16x16x32_bf16 v[36:39], v[24:27], v[200:203], v[36:39]
	v_mfma_f32_16x16x32_bf16 v[32:35], v[40:43], v[200:203], v[32:35]
	v_mfma_f32_16x16x32_bf16 v[12:15], v[24:27], v[208:211], v[12:15]
	v_mfma_f32_16x16x32_bf16 v[8:11], v[40:43], v[208:211], v[8:11]
	v_mfma_f32_16x16x32_bf16 v[76:79], v[28:31], v[188:191], v[76:79]
	v_mfma_f32_16x16x32_bf16 v[72:75], v[44:47], v[188:191], v[72:75]
	v_mfma_f32_16x16x32_bf16 v[60:63], v[28:31], v[196:199], v[60:63]
	v_mfma_f32_16x16x32_bf16 v[56:59], v[44:47], v[196:199], v[56:59]
	v_mfma_f32_16x16x32_bf16 v[36:39], v[28:31], v[204:207], v[36:39]
	v_mfma_f32_16x16x32_bf16 v[32:35], v[44:47], v[204:207], v[32:35]
	v_mfma_f32_16x16x32_bf16 v[12:15], v[28:31], v[212:215], v[12:15]
	v_mfma_f32_16x16x32_bf16 v[8:11], v[44:47], v[212:215], v[8:11]
	s_setprio 0
	s_setprio 1
	v_mfma_f32_16x16x32_bf16 v[20:23], v[154:157], v[200:203], v[20:23]
	v_mfma_f32_16x16x32_bf16 v[16:19], v[170:173], v[200:203], v[16:19]
	v_mfma_f32_16x16x32_bf16 v[4:7], v[154:157], v[208:211], v[4:7]
	v_mfma_f32_16x16x32_bf16 v[0:3], v[170:173], v[208:211], v[0:3]
	v_mfma_f32_16x16x32_bf16 v[24:27], v[154:157], v[178:181], v[68:71]
	v_mfma_f32_16x16x32_bf16 v[28:31], v[170:173], v[178:181], v[64:67]
	v_mfma_f32_16x16x32_bf16 v[40:43], v[154:157], v[192:195], v[52:55]
	v_mfma_f32_16x16x32_bf16 v[44:47], v[170:173], v[192:195], v[48:51]
	v_mfma_f32_16x16x32_bf16 v[20:23], v[158:161], v[204:207], v[20:23]
	v_mfma_f32_16x16x32_bf16 v[16:19], v[174:177], v[204:207], v[16:19]
	v_mfma_f32_16x16x32_bf16 v[4:7], v[158:161], v[212:215], v[4:7]
	v_mfma_f32_16x16x32_bf16 v[0:3], v[174:177], v[212:215], v[0:3]
	v_mfma_f32_16x16x32_bf16 v[24:27], v[158:161], v[188:191], v[24:27]
	v_mfma_f32_16x16x32_bf16 v[28:31], v[174:177], v[188:191], v[28:31]
	v_mfma_f32_16x16x32_bf16 v[40:43], v[158:161], v[196:199], v[40:43]
	v_mfma_f32_16x16x32_bf16 v[44:47], v[174:177], v[196:199], v[44:47]
	s_setprio 0
	s_barrier
	s_add_i32 s58, 0, 0x18000
	s_add_i32 s59, 0, 0x1c000
	v_add_u32_e32 v68, s58, v165
	v_add_u32_e32 v174, s59, v165
	ds_read_b128 v[48:51], v68
	ds_read_b128 v[52:55], v68 offset:1024
	ds_read_b128 v[64:67], v68 offset:2048
	ds_read_b128 v[68:71], v68 offset:3072
	ds_read_b128 v[154:157], v174
	ds_read_b128 v[158:161], v174 offset:1024
	ds_read_b128 v[170:173], v174 offset:2048
	ds_read_b128 v[174:177], v174 offset:3072
	s_add_u32 s42, s42, s6
	s_addc_u32 s43, s43, s7
	s_mov_b32 m0, s44
	ds_read_b128 v[178:181], v169 offset:32768
	ds_read_b128 v[188:191], v169 offset:33792
	ds_read_b128 v[192:195], v169 offset:34816
	ds_read_b128 v[196:199], v169 offset:35840
	ds_read_b128 v[200:203], v169 offset:36864
	ds_read_b128 v[204:207], v169 offset:37888
	ds_read_b128 v[208:211], v169 offset:38912
	ds_read_b128 v[212:215], v169 offset:39936
	global_load_lds_dwordx4 v148, s[42:43]
	v_lshl_add_u64 v[224:225], s[42:43], 0, v[146:147]
	s_mov_b32 m0, s45
	s_nop 0
	global_load_lds_dwordx4 v[224:225], off
	s_waitcnt vmcnt(8)
	s_waitcnt lgkmcnt(0)
	s_barrier
	s_setprio 1
	s_waitcnt lgkmcnt(0)
	v_mfma_f32_16x16x32_bf16 v[140:143], v[48:51], v[178:181], v[140:143]
	v_mfma_f32_16x16x32_bf16 v[136:139], v[64:67], v[178:181], v[136:139]
	v_mfma_f32_16x16x32_bf16 v[124:127], v[48:51], v[192:195], v[124:127]
	v_mfma_f32_16x16x32_bf16 v[120:123], v[64:67], v[192:195], v[120:123]
	v_mfma_f32_16x16x32_bf16 v[108:111], v[48:51], v[200:203], v[108:111]
	v_mfma_f32_16x16x32_bf16 v[104:107], v[64:67], v[200:203], v[104:107]
	v_mfma_f32_16x16x32_bf16 v[92:95], v[48:51], v[208:211], v[92:95]
	v_mfma_f32_16x16x32_bf16 v[88:91], v[64:67], v[208:211], v[88:91]
	v_mfma_f32_16x16x32_bf16 v[140:143], v[52:55], v[188:191], v[140:143]
	v_mfma_f32_16x16x32_bf16 v[136:139], v[68:71], v[188:191], v[136:139]
	v_mfma_f32_16x16x32_bf16 v[124:127], v[52:55], v[196:199], v[124:127]
	v_mfma_f32_16x16x32_bf16 v[120:123], v[68:71], v[196:199], v[120:123]
	v_mfma_f32_16x16x32_bf16 v[108:111], v[52:55], v[204:207], v[108:111]
	v_mfma_f32_16x16x32_bf16 v[104:107], v[68:71], v[204:207], v[104:107]
	v_mfma_f32_16x16x32_bf16 v[92:95], v[52:55], v[212:215], v[92:95]
	v_mfma_f32_16x16x32_bf16 v[88:91], v[68:71], v[212:215], v[88:91]
	s_setprio 0
	s_setprio 1
	v_mfma_f32_16x16x32_bf16 v[132:135], v[154:157], v[178:181], v[132:135]
	v_mfma_f32_16x16x32_bf16 v[128:131], v[170:173], v[178:181], v[128:131]
	v_mfma_f32_16x16x32_bf16 v[116:119], v[154:157], v[192:195], v[116:119]
	v_mfma_f32_16x16x32_bf16 v[112:115], v[170:173], v[192:195], v[112:115]
	v_mfma_f32_16x16x32_bf16 v[100:103], v[154:157], v[200:203], v[100:103]
	v_mfma_f32_16x16x32_bf16 v[96:99], v[170:173], v[200:203], v[96:99]
	v_mfma_f32_16x16x32_bf16 v[84:87], v[154:157], v[208:211], v[84:87]
	v_mfma_f32_16x16x32_bf16 v[80:83], v[170:173], v[208:211], v[80:83]
	v_mfma_f32_16x16x32_bf16 v[132:135], v[158:161], v[188:191], v[132:135]
	v_mfma_f32_16x16x32_bf16 v[128:131], v[174:177], v[188:191], v[128:131]
	v_mfma_f32_16x16x32_bf16 v[116:119], v[158:161], v[196:199], v[116:119]
	v_mfma_f32_16x16x32_bf16 v[112:115], v[174:177], v[196:199], v[112:115]
	v_mfma_f32_16x16x32_bf16 v[100:103], v[158:161], v[204:207], v[100:103]
	v_mfma_f32_16x16x32_bf16 v[96:99], v[174:177], v[204:207], v[96:99]
	v_mfma_f32_16x16x32_bf16 v[84:87], v[158:161], v[212:215], v[84:87]
	v_mfma_f32_16x16x32_bf16 v[80:83], v[174:177], v[212:215], v[80:83]
	s_setprio 0
	s_barrier
; #define PG8_STAGE(bufoff, gbase, voff) do { _Pragma("unroll") for (int _i = 0; _i < 2; ++_i) \
;         __builtin_amdgcn_global_load_lds((const unsigned*)((const char*)(gbase) + (voff)[_i]), (LAS unsigned*)(lds + (bufoff) + ldsw + _i * 8192), 16, 0, 0); } while (0)
; #define PG8_LDA(dst, b, h) do { _Pragma("unroll") for (int m = 0; m < 4; ++m) _Pragma("unroll") for (int k = 0; k < 2; ++k) dst[m][k] = *(const LAS bf16x8*)(lds + PG8_SA(b, h) + aoff + m * 2048 + k * 1024); } while (0)
; #define PG8_MMA(ai, bj, At, Bt) do { __builtin_amdgcn_s_setprio(1); _Pragma("unroll") for (int m = 0; m < 4; ++m) _Pragma("unroll") for (int n = 0; n < 2; ++n) _Pragma("unroll") for (int k = 0; k < 2; ++k) \
;         acc[ai][bj][m][n] = __builtin_amdgcn_mfma_f32_16x16x32_bf16(Bt[n][k], At[m][k], acc[ai][bj][m][n], 0, 0, 0); __builtin_amdgcn_s_setprio(0); } while (0)
; #define PG8_WAIT_V(n) asm volatile("s_waitcnt vmcnt(" #n ")" ::: "memory")
; #define PG8_WAIT_L(n) asm volatile("s_waitcnt lgkmcnt(" #n ")" ::: "memory")
; #define PG8_BAR __builtin_amdgcn_s_barrier()
; #define PG8_SCHED __builtin_amdgcn_sched_barrier(0)
; template <class Epi, bool ALIGN_EPI>
; __device__ __forceinline__ void gemm_phase(LAS unsigned char* lds, const Gemm g, const StaticOrder& S, const Epi& E, const int wave_s) {
;     ...
;             PG8_LDA(At, 1, 1); PG8_STAGE(PG8_SB(1, 0), b3, voffB); PG8_STAGE(PG8_SB(1, 1), b3 + hstepB, voffB); PG8_STAGE(PG8_SA(1, 0), a3, voffA);
;             PG8_WAIT_V(8); PG8_WAIT_L(0); PG8_BAR; PG8_MMA(1, 0, At, B0); PG8_MMA(1, 1, At, B1); PG8_BAR; PG8_SCHED;
;         }
	s_add_i32 s42, s58, s4
	v_lshl_add_u64 v[162:163], v[162:163], 0, s[64:65]
	s_mov_b32 m0, s42
	ds_read_b128 v[178:181], v169 offset:49152
	ds_read_b128 v[188:191], v169 offset:50176
	ds_read_b128 v[192:195], v169 offset:51200
	ds_read_b128 v[196:199], v169 offset:52224
	ds_read_b128 v[200:203], v169 offset:53248
	ds_read_b128 v[204:207], v169 offset:54272
	ds_read_b128 v[208:211], v169 offset:55296
	ds_read_b128 v[212:215], v169 offset:56320
	global_load_lds_dwordx4 v[162:163], off
	v_lshl_add_u64 v[162:163], v[182:183], 0, s[64:65]
	s_add_i32 m0, s42, 0x2000
	s_add_i32 s42, s59, s4
	global_load_lds_dwordx4 v[162:163], off
	v_lshl_add_u64 v[162:163], v[216:217], 0, s[64:65]
	s_mov_b32 m0, s42
	s_nop 0
	global_load_lds_dwordx4 v[162:163], off
	v_lshl_add_u64 v[162:163], v[218:219], 0, s[64:65]
	s_add_i32 m0, s42, 0x2000
	s_nop 0
	global_load_lds_dwordx4 v[162:163], off
	v_lshl_add_u64 v[162:163], v[220:221], 0, s[64:65]
	s_mov_b32 m0, s46
	s_nop 0
	global_load_lds_dwordx4 v[162:163], off
	v_lshl_add_u64 v[162:163], v[222:223], 0, s[64:65]
	s_mov_b32 m0, s47
	s_nop 0
	global_load_lds_dwordx4 v[162:163], off
	s_waitcnt vmcnt(8)
	s_waitcnt lgkmcnt(0)
	s_barrier
	s_setprio 1
	s_waitcnt lgkmcnt(0)
	v_mfma_f32_16x16x32_bf16 v[76:79], v[48:51], v[178:181], v[76:79]
	v_mfma_f32_16x16x32_bf16 v[72:75], v[64:67], v[178:181], v[72:75]
	v_mfma_f32_16x16x32_bf16 v[60:63], v[48:51], v[192:195], v[60:63]
	v_mfma_f32_16x16x32_bf16 v[56:59], v[64:67], v[192:195], v[56:59]
	v_mfma_f32_16x16x32_bf16 v[36:39], v[48:51], v[200:203], v[36:39]
	v_mfma_f32_16x16x32_bf16 v[32:35], v[64:67], v[200:203], v[32:35]
	v_mfma_f32_16x16x32_bf16 v[12:15], v[48:51], v[208:211], v[12:15]
	v_mfma_f32_16x16x32_bf16 v[8:11], v[64:67], v[208:211], v[8:11]
	v_mfma_f32_16x16x32_bf16 v[76:79], v[52:55], v[188:191], v[76:79]
	v_mfma_f32_16x16x32_bf16 v[72:75], v[68:71], v[188:191], v[72:75]
	v_mfma_f32_16x16x32_bf16 v[60:63], v[52:55], v[196:199], v[60:63]
	v_mfma_f32_16x16x32_bf16 v[56:59], v[68:71], v[196:199], v[56:59]
	v_mfma_f32_16x16x32_bf16 v[36:39], v[52:55], v[204:207], v[36:39]
	v_mfma_f32_16x16x32_bf16 v[32:35], v[68:71], v[204:207], v[32:35]
	v_mfma_f32_16x16x32_bf16 v[12:15], v[52:55], v[212:215], v[12:15]
	v_mfma_f32_16x16x32_bf16 v[8:11], v[68:71], v[212:215], v[8:11]
	s_setprio 0
	s_setprio 1
	v_mfma_f32_16x16x32_bf16 v[24:27], v[154:157], v[178:181], v[24:27]
	v_mfma_f32_16x16x32_bf16 v[68:71], v[158:161], v[188:191], v[24:27]
	v_mfma_f32_16x16x32_bf16 v[24:27], v[170:173], v[178:181], v[28:31]
	v_mfma_f32_16x16x32_bf16 v[64:67], v[174:177], v[188:191], v[24:27]
	v_mfma_f32_16x16x32_bf16 v[24:27], v[154:157], v[192:195], v[40:43]
	v_mfma_f32_16x16x32_bf16 v[52:55], v[158:161], v[196:199], v[24:27]
	v_mfma_f32_16x16x32_bf16 v[24:27], v[170:173], v[192:195], v[44:47]
	v_mfma_f32_16x16x32_bf16 v[20:23], v[154:157], v[200:203], v[20:23]
	v_mfma_f32_16x16x32_bf16 v[16:19], v[170:173], v[200:203], v[16:19]
	v_mfma_f32_16x16x32_bf16 v[4:7], v[154:157], v[208:211], v[4:7]
	v_mfma_f32_16x16x32_bf16 v[0:3], v[170:173], v[208:211], v[0:3]
	v_mfma_f32_16x16x32_bf16 v[48:51], v[174:177], v[196:199], v[24:27]
	v_mfma_f32_16x16x32_bf16 v[20:23], v[158:161], v[204:207], v[20:23]
	v_mfma_f32_16x16x32_bf16 v[16:19], v[174:177], v[204:207], v[16:19]
	v_mfma_f32_16x16x32_bf16 v[4:7], v[158:161], v[212:215], v[4:7]
	v_mfma_f32_16x16x32_bf16 v[0:3], v[174:177], v[212:215], v[0:3]
	s_setprio 0
	s_barrier
	s_add_u32 s55, s55, 0x100
	s_addc_u32 s56, s56, 0
	s_add_u32 s40, s40, 0x100
	s_addc_u32 s41, s41, 0
	s_cmp_ge_i32 s57, s48
	s_mov_b32 s42, s57
	s_cbranch_scc0 .LBB0_888
	s_mov_b64 s[58:59], 0x90000
	v_readlane_b32 s60, v252, 12
	s_and_b64 vcc, exec, s[20:21]
	s_cbranch_vccnz .LBB0_893
	s_branch .LBB0_894
